# v3 with one counted lgkmcnt wait in front of every MFMA (finer waits beat paired waits)
# baseline (speedup 1.0000x reference)
; #define LAS __attribute__((address_space(3)))
; #define VREADS1(arr, d_) do { const unsigned ad_ = vbase ^ (unsigned)((d_) << 6); __builtin_amdgcn_sched_barrier(0); \
;         _Pragma("unroll") for (int ks_ = 0; ks_ < 4; ++ks_) { VTR(arr[ks_ * 2], ad_, ks_ * 4096); VTR(arr[ks_ * 2 + 1], ad_, ks_ * 4096 + 2048); } __builtin_amdgcn_sched_barrier(0); } while (0)
; #define PV1(arr, d_) do { _Pragma("unroll") for (int ks_ = 0; ks_ < 4; ++ks_) { const s16x4 lo_ = arr[ks_ * 2], hh_ = arr[ks_ * 2 + 1]; \
;         const bf16x8 bv_ = (bf16x8){lo_[0], lo_[1], lo_[2], lo_[3], hh_[0], hh_[1], hh_[2], hh_[3]}; \
;         O[d_] = __builtin_amdgcn_mfma_f32_32x32x16_bf16(pa[ks_], bv_, O[d_], 0, 0, 0); } __builtin_amdgcn_sched_barrier(0); } while (0)
; __device__ __forceinline__ void attn_unit(LAS unsigned char* lds, const bf16_t* Z, bf16_t* A2, const float* tabg, int seq_base, int S, int h, int qb, float lam) {
;     ...
;             for (int ds = 0; ds < 4; ++ds) { kf[2 * ds] = *(const LAS bf16x8*)(Kt + (kfo ^ (unsigned)(ds << 5))); kf[2 * ds + 1] = *(const LAS bf16x8*)(Kt + 32 * 256 + (kfo ^ (unsigned)(ds << 5))); }
;             __builtin_amdgcn_sched_barrier(0);
;             p0 = __builtin_amdgcn_mfma_f32_32x32x16_bf16(kf[0], qf[0], cblk, 0, 0, 0);
;             p1 = __builtin_amdgcn_mfma_f32_32x32x16_bf16(kf[1], qf[0], cblk, 0, 0, 0);
; #pragma unroll
;             for (int ds = 1; ds < 4; ++ds) {
;                 p0 = __builtin_amdgcn_mfma_f32_32x32x16_bf16(kf[2 * ds], qf[ds], p0, 0, 0, 0);
;                 p1 = __builtin_amdgcn_mfma_f32_32x32x16_bf16(kf[2 * ds + 1], qf[ds], p1, 0, 0, 0);
;             }
;     ...
; #pragma unroll
;         for (int r = 0; r < 16; ++r) { p0[r] = __builtin_amdgcn_exp2f(p0[r]); p1[r] = __builtin_amdgcn_exp2f(p1[r]); }
; #pragma unroll
;         for (int r = 0; r < 16; r += 2) { ls2 += (f32x2){p0[r], p0[r + 1]}; ls2 += (f32x2){p1[r], p1[r + 1]}; }
;         bf16x8 pa[4]; pa[0] = pack8(p0, 0); pa[1] = pack8(p0, 8); pa[2] = pack8(p1, 0); pa[3] = pack8(p1, 8);
;         LGKM0(); VREADS1(vb, 1); PV1(va, 0); LGKM0(); VREADS1(va, 2); PV1(vb, 1); LGKM0(); VREADS1(vb, 3); PV1(va, 2); LGKM0(); PV1(vb, 3);
;     ...
;         if (t + 2 < NT) asm volatile("s_waitcnt vmcnt(4) lgkmcnt(0)" ::: "memory"); else asm volatile("s_waitcnt vmcnt(0) lgkmcnt(0)" ::: "memory");
;         __builtin_amdgcn_s_barrier(); asm volatile("" ::: "memory");
.LatA_rareret_h0:
	s_waitcnt lgkmcnt(6)
	v_mfma_f32_32x32x16_bf16 v[188:203], v[132:135], v[116:119], v[2:17]
	ds_read_b128 v[132:135], v182 offset:24576
	v_exp_f32_e32 v84, v84
	v_exp_f32_e32 v85, v85
	v_exp_f32_e32 v86, v86
	v_exp_f32_e32 v87, v87
	v_pk_add_f32 v[150:151], v[150:151], v[84:85]
	v_pk_add_f32 v[150:151], v[150:151], v[86:87]
	v_exp_f32_e32 v88, v88
	s_waitcnt lgkmcnt(6)
	s_mov_b32 m0, s28
	v_mfma_f32_32x32x16_bf16 v[204:219], v[136:139], v[116:119], v[2:17]
	global_load_lds_dwordx4 v236, s[8:9]
	v_exp_f32_e32 v89, v89
	v_cvt_pk_bf16_f32 v84, v84, v85
	v_cvt_pk_bf16_f32 v85, v86, v87
	v_exp_f32_e32 v90, v90
	v_exp_f32_e32 v91, v91
	v_pk_add_f32 v[150:151], v[150:151], v[88:89]
	v_pk_add_f32 v[150:151], v[150:151], v[90:91]
	v_cvt_pk_bf16_f32 v86, v88, v89
	v_cvt_pk_bf16_f32 v87, v90, v91
	s_waitcnt lgkmcnt(5)
	v_mfma_f32_32x32x16_bf16 v[188:203], v[140:143], v[120:123], v[188:203]
	v_exp_f32_e32 v92, v92
	v_exp_f32_e32 v93, v93
	v_exp_f32_e32 v94, v94
	v_exp_f32_e32 v95, v95
	v_pk_add_f32 v[150:151], v[150:151], v[92:93]
	v_pk_add_f32 v[150:151], v[150:151], v[94:95]
	v_exp_f32_e32 v96, v96
	s_waitcnt lgkmcnt(4)
	s_add_u32 m0, s28, 0x2000
	v_mfma_f32_32x32x16_bf16 v[204:219], v[144:147], v[120:123], v[204:219]
	global_load_lds_dwordx4 v237, s[8:9]
	v_exp_f32_e32 v97, v97
	v_cvt_pk_bf16_f32 v88, v92, v93
	v_cvt_pk_bf16_f32 v89, v94, v95
	v_exp_f32_e32 v98, v98
	v_exp_f32_e32 v99, v99
	v_pk_add_f32 v[150:151], v[150:151], v[96:97]
	v_pk_add_f32 v[150:151], v[150:151], v[98:99]
	v_cvt_pk_bf16_f32 v90, v96, v97
	v_cvt_pk_bf16_f32 v91, v98, v99
	s_waitcnt lgkmcnt(3)
	v_mfma_f32_32x32x16_bf16 v[188:203], v[220:223], v[124:127], v[188:203]
	v_exp_f32_e32 v100, v100
	v_exp_f32_e32 v101, v101
	v_exp_f32_e32 v102, v102
	v_exp_f32_e32 v103, v103
	v_pk_add_f32 v[150:151], v[150:151], v[100:101]
	v_pk_add_f32 v[150:151], v[150:151], v[102:103]
	v_exp_f32_e32 v104, v104
	s_waitcnt lgkmcnt(2)
	v_mfma_f32_32x32x16_bf16 v[204:219], v[224:227], v[124:127], v[204:219]
	v_exp_f32_e32 v105, v105
	v_cvt_pk_bf16_f32 v100, v100, v101
	v_cvt_pk_bf16_f32 v101, v102, v103
	v_exp_f32_e32 v106, v106
	v_exp_f32_e32 v107, v107
	v_pk_add_f32 v[150:151], v[150:151], v[104:105]
	v_pk_add_f32 v[150:151], v[150:151], v[106:107]
	v_cvt_pk_bf16_f32 v102, v104, v105
	v_cvt_pk_bf16_f32 v103, v106, v107
	s_waitcnt lgkmcnt(1)
	v_mfma_f32_32x32x16_bf16 v[188:203], v[232:235], v[128:131], v[188:203]
	v_exp_f32_e32 v108, v108
	v_exp_f32_e32 v109, v109
	v_exp_f32_e32 v110, v110
	v_exp_f32_e32 v111, v111
	v_pk_add_f32 v[150:151], v[150:151], v[108:109]
	v_pk_add_f32 v[150:151], v[150:151], v[110:111]
	v_exp_f32_e32 v112, v112
	s_waitcnt lgkmcnt(0)
	v_mfma_f32_32x32x16_bf16 v[204:219], v[132:135], v[128:131], v[204:219]
	v_exp_f32_e32 v113, v113
	v_cvt_pk_bf16_f32 v104, v108, v109
	v_cvt_pk_bf16_f32 v105, v110, v111
	v_exp_f32_e32 v114, v114
	v_exp_f32_e32 v115, v115
	v_pk_add_f32 v[150:151], v[150:151], v[112:113]
	v_pk_add_f32 v[150:151], v[150:151], v[114:115]
	v_cvt_pk_bf16_f32 v106, v112, v113
	v_cvt_pk_bf16_f32 v107, v114, v115
	s_add_u32 s8, s8, 0x40000
	s_addc_u32 s9, s9, 0
	s_waitcnt vmcnt(2) lgkmcnt(0)
	s_barrier
	s_sub_u32 s10, s10, 1
	s_cbranch_scc1 .LatA_evs_h1

; #define LAS __attribute__((address_space(3)))
; __device__ __forceinline__ void attn_unit(LAS unsigned char* lds, const bf16_t* Z, bf16_t* A2, const float* tabg, int seq_base, int S, int h, int qb, float lam) {
;     ...
;             for (int ds = 0; ds < 4; ++ds) { kf[2 * ds] = *(const LAS bf16x8*)(Kt + (kfo ^ (unsigned)(ds << 5))); kf[2 * ds + 1] = *(const LAS bf16x8*)(Kt + 32 * 256 + (kfo ^ (unsigned)(ds << 5))); }
;             __builtin_amdgcn_sched_barrier(0);
;             p0 = __builtin_amdgcn_mfma_f32_32x32x16_bf16(kf[0], qf[0], cblk, 0, 0, 0);
;             p1 = __builtin_amdgcn_mfma_f32_32x32x16_bf16(kf[1], qf[0], cblk, 0, 0, 0);
; #pragma unroll
;             for (int ds = 1; ds < 4; ++ds) {
;                 p0 = __builtin_amdgcn_mfma_f32_32x32x16_bf16(kf[2 * ds], qf[ds], p0, 0, 0, 0);
;                 p1 = __builtin_amdgcn_mfma_f32_32x32x16_bf16(kf[2 * ds + 1], qf[ds], p1, 0, 0, 0);
;             }
;         }
;     ...
;         const unsigned vbase = (unsigned)(size_t)Vt + vfo;
;         s16x4 va[8], vb[8];
;         VREADS1(va, 0);
;         if (near) {
;             const LAS float* tp = tab + (kv0 + 4 * hi - (qlo + r32) + 224);
; #pragma unroll
;             for (int r = 0; r < 16; ++r) { p0[r] += tp[(r & 3) + 8 * (r >> 2)]; p1[r] += tp[32 + (r & 3) + 8 * (r >> 2)]; }
;         }
;         float mx = max2f(max16f(p0), max16f(p1));
;         const bool first = (t == 0);
;         if (first || __any(mx > THR)) {
;             { auto rr = __builtin_amdgcn_permlane32_swap(__float_as_uint(mx), __float_as_uint(mx), false, false); mx = max2f(__uint_as_float(rr[0]), __uint_as_float(rr[1])); }
;             const float delta = first ? mx : fmaxf(mx, 0.f);
;             const float alpha = first ? 1.0f : __builtin_amdgcn_exp2f(-delta);
;             mu += delta; ls2 *= alpha;
;             if (!first) {
;                 asm volatile("" ::: "memory");
;                 scr[r32] = alpha;
;                 asm volatile("s_waitcnt lgkmcnt(0)" ::: "memory");
; #pragma unroll
;                 for (int g = 0; g < 4; ++g) { const f32x4 a4 = *(const LAS f32x4*)(scr + 8 * g + 4 * hi);
; #pragma unroll
;                     for (int d = 0; d < 4; ++d) { O[d][4 * g + 0] *= a4[0]; O[d][4 * g + 1] *= a4[1]; O[d][4 * g + 2] *= a4[2]; O[d][4 * g + 3] *= a4[3]; } }
;                 asm volatile("s_waitcnt lgkmcnt(0)" ::: "memory");
;             }
; #pragma unroll
.LatA_rareret_h1:
	s_waitcnt lgkmcnt(12)
	v_mfma_f32_32x32x16_bf16 v[20:35], v[84:87], v[132:135], v[20:35]
	ds_read_b64_tr_b16 v[132:133], v231 offset:4096
	ds_read_b64_tr_b16 v[134:135], v231 offset:6144
	v_exp_f32_e32 v188, v188
	v_exp_f32_e32 v189, v189
	s_waitcnt lgkmcnt(12)
	v_mfma_f32_32x32x16_bf16 v[36:51], v[84:87], v[136:139], v[36:51]
	ds_read_b64_tr_b16 v[136:137], v228 offset:8192
	ds_read_b64_tr_b16 v[138:139], v228 offset:10240
	v_exp_f32_e32 v190, v190
	v_exp_f32_e32 v191, v191
	s_waitcnt lgkmcnt(12)
	v_mfma_f32_32x32x16_bf16 v[52:67], v[84:87], v[140:143], v[52:67]
	ds_read_b64_tr_b16 v[140:141], v229 offset:8192
	ds_read_b64_tr_b16 v[142:143], v229 offset:10240
	v_pk_add_f32 v[150:151], v[150:151], v[188:189]
	v_pk_add_f32 v[150:151], v[150:151], v[190:191]
	v_exp_f32_e32 v192, v192
	s_waitcnt lgkmcnt(12)
	s_add_u32 m0, s28, 0x4000
	v_mfma_f32_32x32x16_bf16 v[68:83], v[84:87], v[144:147], v[68:83]
	global_load_lds_dwordx4 v236, s[8:9]
	ds_read_b64_tr_b16 v[144:145], v230 offset:8192
	ds_read_b64_tr_b16 v[146:147], v230 offset:10240
	v_exp_f32_e32 v193, v193
	v_cvt_pk_bf16_f32 v188, v188, v189
	v_cvt_pk_bf16_f32 v189, v190, v191
	s_waitcnt lgkmcnt(12)
	v_mfma_f32_32x32x16_bf16 v[20:35], v[88:91], v[220:223], v[20:35]
	ds_read_b64_tr_b16 v[220:221], v231 offset:8192
	ds_read_b64_tr_b16 v[222:223], v231 offset:10240
	v_exp_f32_e32 v194, v194
	v_exp_f32_e32 v195, v195
	s_waitcnt lgkmcnt(12)
	v_mfma_f32_32x32x16_bf16 v[36:51], v[88:91], v[224:227], v[36:51]
	ds_read_b64_tr_b16 v[224:225], v228 offset:12288
	ds_read_b64_tr_b16 v[226:227], v228 offset:14336
	v_pk_add_f32 v[150:151], v[150:151], v[192:193]
	v_pk_add_f32 v[150:151], v[150:151], v[194:195]
	v_cvt_pk_bf16_f32 v190, v192, v193
	v_cvt_pk_bf16_f32 v191, v194, v195
	s_waitcnt lgkmcnt(12)
	v_mfma_f32_32x32x16_bf16 v[52:67], v[88:91], v[232:235], v[52:67]
	ds_read_b64_tr_b16 v[232:233], v229 offset:12288
	ds_read_b64_tr_b16 v[234:235], v229 offset:14336
	v_exp_f32_e32 v196, v196
	v_exp_f32_e32 v197, v197
	s_waitcnt lgkmcnt(12)
	s_add_u32 m0, s29, 0x8000
	v_mfma_f32_32x32x16_bf16 v[68:83], v[88:91], v[132:135], v[68:83]
	global_load_lds_dwordx4 v160, s[8:9]
	ds_read_b64_tr_b16 v[132:133], v230 offset:12288
	ds_read_b64_tr_b16 v[134:135], v230 offset:14336
	v_exp_f32_e32 v198, v198
	v_exp_f32_e32 v199, v199
	s_waitcnt lgkmcnt(12)
	v_mfma_f32_32x32x16_bf16 v[20:35], v[100:103], v[136:139], v[20:35]
	ds_read_b64_tr_b16 v[136:137], v231 offset:12288
	ds_read_b64_tr_b16 v[138:139], v231 offset:14336
	v_pk_add_f32 v[150:151], v[150:151], v[196:197]
	v_pk_add_f32 v[150:151], v[150:151], v[198:199]
	v_exp_f32_e32 v200, v200
	s_waitcnt lgkmcnt(12)
	v_mfma_f32_32x32x16_bf16 v[36:51], v[100:103], v[140:143], v[36:51]
	ds_read_b128 v[140:143], v19 offset:32768
	v_exp_f32_e32 v201, v201
	v_cvt_pk_bf16_f32 v192, v196, v197
	v_cvt_pk_bf16_f32 v193, v198, v199
	s_waitcnt lgkmcnt(11)
	v_mfma_f32_32x32x16_bf16 v[52:67], v[100:103], v[144:147], v[52:67]
	ds_read_b128 v[144:147], v19 offset:40960
	v_exp_f32_e32 v202, v202
	v_exp_f32_e32 v203, v203
	s_waitcnt lgkmcnt(10)
	s_add_u32 m0, s28, 0x6000
	v_mfma_f32_32x32x16_bf16 v[68:83], v[100:103], v[220:223], v[68:83]
	global_load_lds_dwordx4 v237, s[8:9]
	ds_read_b128 v[220:223], v180 offset:32768
	v_pk_add_f32 v[150:151], v[150:151], v[200:201]
	v_pk_add_f32 v[150:151], v[150:151], v[202:203]
	v_cvt_pk_bf16_f32 v194, v200, v201
	v_cvt_pk_bf16_f32 v195, v202, v203
	s_waitcnt lgkmcnt(9)
	v_mfma_f32_32x32x16_bf16 v[20:35], v[104:107], v[224:227], v[20:35]
	ds_read_b128 v[224:227], v180 offset:40960
	v_exp_f32_e32 v204, v204
	v_exp_f32_e32 v205, v205
	s_waitcnt lgkmcnt(8)
	v_mfma_f32_32x32x16_bf16 v[36:51], v[104:107], v[232:235], v[36:51]
	ds_read_b128 v[232:235], v181 offset:32768
	v_exp_f32_e32 v206, v206
	v_exp_f32_e32 v207, v207
	s_waitcnt lgkmcnt(7)
	v_mfma_f32_32x32x16_bf16 v[52:67], v[104:107], v[132:135], v[52:67]
	ds_read_b128 v[132:135], v181 offset:40960
	v_pk_add_f32 v[150:151], v[150:151], v[204:205]
	v_pk_add_f32 v[150:151], v[150:151], v[206:207]
	v_exp_f32_e32 v208, v208
	s_waitcnt lgkmcnt(6)
	s_add_u32 m0, s29, 0xa000
	v_mfma_f32_32x32x16_bf16 v[68:83], v[104:107], v[136:139], v[68:83]
	global_load_lds_dwordx4 v176, s[8:9]
	ds_read_b128 v[136:139], v182 offset:32768
	v_exp_f32_e32 v209, v209
	v_cvt_pk_bf16_f32 v204, v204, v205
	v_cvt_pk_bf16_f32 v205, v206, v207
	s_waitcnt lgkmcnt(6)
	v_mfma_f32_32x32x16_bf16 v[84:99], v[140:143], v[116:119], v[2:17]
	ds_read_b128 v[140:143], v182 offset:40960
	v_exp_f32_e32 v210, v210
	v_exp_f32_e32 v211, v211
	s_waitcnt lgkmcnt(6)
	v_mfma_f32_32x32x16_bf16 v[100:115], v[144:147], v[116:119], v[2:17]
	v_pk_add_f32 v[150:151], v[150:151], v[208:209]
	v_pk_add_f32 v[150:151], v[150:151], v[210:211]
	v_cvt_pk_bf16_f32 v206, v208, v209
	v_cvt_pk_bf16_f32 v207, v210, v211
	s_waitcnt lgkmcnt(5)
	v_mfma_f32_32x32x16_bf16 v[84:99], v[220:223], v[120:123], v[84:99]
	v_exp_f32_e32 v212, v212
	v_exp_f32_e32 v213, v213
	s_waitcnt lgkmcnt(4)
	v_mfma_f32_32x32x16_bf16 v[100:115], v[224:227], v[120:123], v[100:115]
	v_exp_f32_e32 v214, v214
	v_exp_f32_e32 v215, v215
	s_waitcnt lgkmcnt(3)
	v_mfma_f32_32x32x16_bf16 v[84:99], v[232:235], v[124:127], v[84:99]
	v_pk_add_f32 v[150:151], v[150:151], v[212:213]
	v_pk_add_f32 v[150:151], v[150:151], v[214:215]
	v_exp_f32_e32 v216, v216
	s_waitcnt lgkmcnt(2)
	v_mfma_f32_32x32x16_bf16 v[100:115], v[132:135], v[124:127], v[100:115]
	v_exp_f32_e32 v217, v217
	v_cvt_pk_bf16_f32 v208, v212, v213
	v_cvt_pk_bf16_f32 v209, v214, v215
	s_waitcnt lgkmcnt(1)
	v_mfma_f32_32x32x16_bf16 v[84:99], v[136:139], v[128:131], v[84:99]
	v_exp_f32_e32 v218, v218
	v_exp_f32_e32 v219, v219
	s_waitcnt lgkmcnt(0)
	v_mfma_f32_32x32x16_bf16 v[100:115], v[140:143], v[128:131], v[100:115]
	v_pk_add_f32 v[150:151], v[150:151], v[216:217]
	v_pk_add_f32 v[150:151], v[150:151], v[218:219]
	v_cvt_pk_bf16_f32 v210, v216, v217
	v_cvt_pk_bf16_f32 v211, v218, v219
	s_add_u32 s8, s8, 0x40000
	s_addc_u32 s9, s9, 0
	s_waitcnt vmcnt(4) lgkmcnt(0)
	s_barrier
	s_sub_u32 s10, s10, 1
	s_cbranch_scc1 .LatA_evs_h2

; #define LAS __attribute__((address_space(3)))
; __device__ __forceinline__ void attn_unit(LAS unsigned char* lds, const bf16_t* Z, bf16_t* A2, const float* tabg, int seq_base, int S, int h, int qb, float lam) {
;     ...
;             for (int ds = 0; ds < 4; ++ds) { kf[2 * ds] = *(const LAS bf16x8*)(Kt + (kfo ^ (unsigned)(ds << 5))); kf[2 * ds + 1] = *(const LAS bf16x8*)(Kt + 32 * 256 + (kfo ^ (unsigned)(ds << 5))); }
;             __builtin_amdgcn_sched_barrier(0);
;             p0 = __builtin_amdgcn_mfma_f32_32x32x16_bf16(kf[0], qf[0], cblk, 0, 0, 0);
;             p1 = __builtin_amdgcn_mfma_f32_32x32x16_bf16(kf[1], qf[0], cblk, 0, 0, 0);
; #pragma unroll
;             for (int ds = 1; ds < 4; ++ds) {
;                 p0 = __builtin_amdgcn_mfma_f32_32x32x16_bf16(kf[2 * ds], qf[ds], p0, 0, 0, 0);
;                 p1 = __builtin_amdgcn_mfma_f32_32x32x16_bf16(kf[2 * ds + 1], qf[ds], p1, 0, 0, 0);
;             }
;         }
;     ...
;         const unsigned vbase = (unsigned)(size_t)Vt + vfo;
;         s16x4 va[8], vb[8];
;         VREADS1(va, 0);
;         if (near) {
;             const LAS float* tp = tab + (kv0 + 4 * hi - (qlo + r32) + 224);
; #pragma unroll
;             for (int r = 0; r < 16; ++r) { p0[r] += tp[(r & 3) + 8 * (r >> 2)]; p1[r] += tp[32 + (r & 3) + 8 * (r >> 2)]; }
;         }
;         float mx = max2f(max16f(p0), max16f(p1));
;         const bool first = (t == 0);
;         if (first || __any(mx > THR)) {
;             { auto rr = __builtin_amdgcn_permlane32_swap(__float_as_uint(mx), __float_as_uint(mx), false, false); mx = max2f(__uint_as_float(rr[0]), __uint_as_float(rr[1])); }
;             const float delta = first ? mx : fmaxf(mx, 0.f);
;             const float alpha = first ? 1.0f : __builtin_amdgcn_exp2f(-delta);
;             mu += delta; ls2 *= alpha;
;             if (!first) {
;                 asm volatile("" ::: "memory");
;                 scr[r32] = alpha;
;                 asm volatile("s_waitcnt lgkmcnt(0)" ::: "memory");
; #pragma unroll
;                 for (int g = 0; g < 4; ++g) { const f32x4 a4 = *(const LAS f32x4*)(scr + 8 * g + 4 * hi);
; #pragma unroll
;                     for (int d = 0; d < 4; ++d) { O[d][4 * g + 0] *= a4[0]; O[d][4 * g + 1] *= a4[1]; O[d][4 * g + 2] *= a4[2]; O[d][4 * g + 3] *= a4[3]; } }
;                 asm volatile("s_waitcnt lgkmcnt(0)" ::: "memory");
;             }
; #pragma unroll
.LatA_rareret_h2:
	s_waitcnt lgkmcnt(12)
	v_mfma_f32_32x32x16_bf16 v[20:35], v[188:191], v[132:135], v[20:35]
	ds_read_b64_tr_b16 v[132:133], v231 offset:20480
	ds_read_b64_tr_b16 v[134:135], v231 offset:22528
	v_exp_f32_e32 v84, v84
	v_exp_f32_e32 v85, v85
	s_waitcnt lgkmcnt(12)
	v_mfma_f32_32x32x16_bf16 v[36:51], v[188:191], v[136:139], v[36:51]
	ds_read_b64_tr_b16 v[136:137], v228 offset:24576
	ds_read_b64_tr_b16 v[138:139], v228 offset:26624
	v_exp_f32_e32 v86, v86
	v_exp_f32_e32 v87, v87
	s_waitcnt lgkmcnt(12)
	v_mfma_f32_32x32x16_bf16 v[52:67], v[188:191], v[140:143], v[52:67]
	ds_read_b64_tr_b16 v[140:141], v229 offset:24576
	ds_read_b64_tr_b16 v[142:143], v229 offset:26624
	v_pk_add_f32 v[150:151], v[150:151], v[84:85]
	v_pk_add_f32 v[150:151], v[150:151], v[86:87]
	v_exp_f32_e32 v88, v88
	s_waitcnt lgkmcnt(12)
	s_add_u32 m0, s28, 0x8000
	v_mfma_f32_32x32x16_bf16 v[68:83], v[188:191], v[144:147], v[68:83]
	global_load_lds_dwordx4 v236, s[8:9]
	ds_read_b64_tr_b16 v[144:145], v230 offset:24576
	ds_read_b64_tr_b16 v[146:147], v230 offset:26624
	v_exp_f32_e32 v89, v89
	v_cvt_pk_bf16_f32 v84, v84, v85
	v_cvt_pk_bf16_f32 v85, v86, v87
	s_waitcnt lgkmcnt(12)
	v_mfma_f32_32x32x16_bf16 v[20:35], v[192:195], v[220:223], v[20:35]
	ds_read_b64_tr_b16 v[220:221], v231 offset:24576
	ds_read_b64_tr_b16 v[222:223], v231 offset:26624
	v_exp_f32_e32 v90, v90
	v_exp_f32_e32 v91, v91
	s_waitcnt lgkmcnt(12)
	v_mfma_f32_32x32x16_bf16 v[36:51], v[192:195], v[224:227], v[36:51]
	ds_read_b64_tr_b16 v[224:225], v228 offset:28672
	ds_read_b64_tr_b16 v[226:227], v228 offset:30720
	v_pk_add_f32 v[150:151], v[150:151], v[88:89]
	v_pk_add_f32 v[150:151], v[150:151], v[90:91]
	v_cvt_pk_bf16_f32 v86, v88, v89
	v_cvt_pk_bf16_f32 v87, v90, v91
	s_waitcnt lgkmcnt(12)
	v_mfma_f32_32x32x16_bf16 v[52:67], v[192:195], v[232:235], v[52:67]
	ds_read_b64_tr_b16 v[232:233], v229 offset:28672
	ds_read_b64_tr_b16 v[234:235], v229 offset:30720
	v_exp_f32_e32 v92, v92
	v_exp_f32_e32 v93, v93
	s_waitcnt lgkmcnt(12)
	s_mov_b32 m0, s29
	v_mfma_f32_32x32x16_bf16 v[68:83], v[192:195], v[132:135], v[68:83]
	global_load_lds_dwordx4 v160, s[8:9]
	ds_read_b64_tr_b16 v[132:133], v230 offset:28672
	ds_read_b64_tr_b16 v[134:135], v230 offset:30720
	v_exp_f32_e32 v94, v94
	v_exp_f32_e32 v95, v95
	s_waitcnt lgkmcnt(12)
	v_mfma_f32_32x32x16_bf16 v[20:35], v[204:207], v[136:139], v[20:35]
	ds_read_b64_tr_b16 v[136:137], v231 offset:28672
	ds_read_b64_tr_b16 v[138:139], v231 offset:30720
	v_pk_add_f32 v[150:151], v[150:151], v[92:93]
	v_pk_add_f32 v[150:151], v[150:151], v[94:95]
	v_exp_f32_e32 v96, v96
	s_waitcnt lgkmcnt(12)
	v_mfma_f32_32x32x16_bf16 v[36:51], v[204:207], v[140:143], v[36:51]
	ds_read_b128 v[140:143], v19
	v_exp_f32_e32 v97, v97
	v_cvt_pk_bf16_f32 v88, v92, v93
	v_cvt_pk_bf16_f32 v89, v94, v95
	s_waitcnt lgkmcnt(11)
	v_mfma_f32_32x32x16_bf16 v[52:67], v[204:207], v[144:147], v[52:67]
	ds_read_b128 v[144:147], v19 offset:8192
	v_exp_f32_e32 v98, v98
	v_exp_f32_e32 v99, v99
	s_waitcnt lgkmcnt(10)
	s_add_u32 m0, s28, 0xa000
	v_mfma_f32_32x32x16_bf16 v[68:83], v[204:207], v[220:223], v[68:83]
	global_load_lds_dwordx4 v237, s[8:9]
	ds_read_b128 v[220:223], v180
	v_pk_add_f32 v[150:151], v[150:151], v[96:97]
	v_pk_add_f32 v[150:151], v[150:151], v[98:99]
	v_cvt_pk_bf16_f32 v90, v96, v97
	v_cvt_pk_bf16_f32 v91, v98, v99
	s_waitcnt lgkmcnt(9)
	v_mfma_f32_32x32x16_bf16 v[20:35], v[208:211], v[224:227], v[20:35]
	ds_read_b128 v[224:227], v180 offset:8192
	v_exp_f32_e32 v100, v100
	v_exp_f32_e32 v101, v101
	s_waitcnt lgkmcnt(8)
	v_mfma_f32_32x32x16_bf16 v[36:51], v[208:211], v[232:235], v[36:51]
	ds_read_b128 v[232:235], v181
	v_exp_f32_e32 v102, v102
	v_exp_f32_e32 v103, v103
	s_waitcnt lgkmcnt(7)
	v_mfma_f32_32x32x16_bf16 v[52:67], v[208:211], v[132:135], v[52:67]
	ds_read_b128 v[132:135], v181 offset:8192
	v_pk_add_f32 v[150:151], v[150:151], v[100:101]
	v_pk_add_f32 v[150:151], v[150:151], v[102:103]
	v_exp_f32_e32 v104, v104
	s_waitcnt lgkmcnt(6)
	s_add_u32 m0, s29, 0x2000
	v_mfma_f32_32x32x16_bf16 v[68:83], v[208:211], v[136:139], v[68:83]
	global_load_lds_dwordx4 v176, s[8:9]
	ds_read_b128 v[136:139], v182
	v_exp_f32_e32 v105, v105
	v_cvt_pk_bf16_f32 v100, v100, v101
	v_cvt_pk_bf16_f32 v101, v102, v103
	s_waitcnt lgkmcnt(6)
	v_mfma_f32_32x32x16_bf16 v[188:203], v[140:143], v[116:119], v[2:17]
	ds_read_b128 v[140:143], v182 offset:8192
	v_exp_f32_e32 v106, v106
	v_exp_f32_e32 v107, v107
	s_waitcnt lgkmcnt(6)
	v_mfma_f32_32x32x16_bf16 v[204:219], v[144:147], v[116:119], v[2:17]
	v_pk_add_f32 v[150:151], v[150:151], v[104:105]
	v_pk_add_f32 v[150:151], v[150:151], v[106:107]
	v_cvt_pk_bf16_f32 v102, v104, v105
	v_cvt_pk_bf16_f32 v103, v106, v107
	s_waitcnt lgkmcnt(5)
	v_mfma_f32_32x32x16_bf16 v[188:203], v[220:223], v[120:123], v[188:203]
	v_exp_f32_e32 v108, v108
	v_exp_f32_e32 v109, v109
	s_waitcnt lgkmcnt(4)
	v_mfma_f32_32x32x16_bf16 v[204:219], v[224:227], v[120:123], v[204:219]
	v_exp_f32_e32 v110, v110
	v_exp_f32_e32 v111, v111
	s_waitcnt lgkmcnt(3)
	v_mfma_f32_32x32x16_bf16 v[188:203], v[232:235], v[124:127], v[188:203]
	v_pk_add_f32 v[150:151], v[150:151], v[108:109]
	v_pk_add_f32 v[150:151], v[150:151], v[110:111]
	v_exp_f32_e32 v112, v112
	s_waitcnt lgkmcnt(2)
	v_mfma_f32_32x32x16_bf16 v[204:219], v[132:135], v[124:127], v[204:219]
	v_exp_f32_e32 v113, v113
	v_cvt_pk_bf16_f32 v104, v108, v109
	v_cvt_pk_bf16_f32 v105, v110, v111
	s_waitcnt lgkmcnt(1)
	v_mfma_f32_32x32x16_bf16 v[188:203], v[136:139], v[128:131], v[188:203]
	v_exp_f32_e32 v114, v114
	v_exp_f32_e32 v115, v115
	s_waitcnt lgkmcnt(0)
	v_mfma_f32_32x32x16_bf16 v[204:219], v[140:143], v[128:131], v[204:219]
	v_pk_add_f32 v[150:151], v[150:151], v[112:113]
	v_pk_add_f32 v[150:151], v[150:151], v[114:115]
	v_cvt_pk_bf16_f32 v106, v112, v113
	v_cvt_pk_bf16_f32 v107, v114, v115
	s_add_u32 s8, s8, 0x40000
	s_addc_u32 s9, s9, 0
	s_waitcnt vmcnt(4) lgkmcnt(0)
	s_barrier
	s_sub_u32 s10, s10, 1
	s_cbranch_scc1 .LatA_evs_h3

; #define LAS __attribute__((address_space(3)))
; __device__ __forceinline__ void attn_unit(LAS unsigned char* lds, const bf16_t* Z, bf16_t* A2, const float* tabg, int seq_base, int S, int h, int qb, float lam) {
;     ...
;             for (int ds = 0; ds < 4; ++ds) { kf[2 * ds] = *(const LAS bf16x8*)(Kt + (kfo ^ (unsigned)(ds << 5))); kf[2 * ds + 1] = *(const LAS bf16x8*)(Kt + 32 * 256 + (kfo ^ (unsigned)(ds << 5))); }
;             __builtin_amdgcn_sched_barrier(0);
;             p0 = __builtin_amdgcn_mfma_f32_32x32x16_bf16(kf[0], qf[0], cblk, 0, 0, 0);
;             p1 = __builtin_amdgcn_mfma_f32_32x32x16_bf16(kf[1], qf[0], cblk, 0, 0, 0);
; #pragma unroll
;             for (int ds = 1; ds < 4; ++ds) {
;                 p0 = __builtin_amdgcn_mfma_f32_32x32x16_bf16(kf[2 * ds], qf[ds], p0, 0, 0, 0);
;                 p1 = __builtin_amdgcn_mfma_f32_32x32x16_bf16(kf[2 * ds + 1], qf[ds], p1, 0, 0, 0);
;             }
;         }
;     ...
;         const unsigned vbase = (unsigned)(size_t)Vt + vfo;
;         s16x4 va[8], vb[8];
;         VREADS1(va, 0);
;         if (near) {
;             const LAS float* tp = tab + (kv0 + 4 * hi - (qlo + r32) + 224);
; #pragma unroll
;             for (int r = 0; r < 16; ++r) { p0[r] += tp[(r & 3) + 8 * (r >> 2)]; p1[r] += tp[32 + (r & 3) + 8 * (r >> 2)]; }
;         }
;         float mx = max2f(max16f(p0), max16f(p1));
;         const bool first = (t == 0);
;         if (first || __any(mx > THR)) {
;             { auto rr = __builtin_amdgcn_permlane32_swap(__float_as_uint(mx), __float_as_uint(mx), false, false); mx = max2f(__uint_as_float(rr[0]), __uint_as_float(rr[1])); }
;             const float delta = first ? mx : fmaxf(mx, 0.f);
;             const float alpha = first ? 1.0f : __builtin_amdgcn_exp2f(-delta);
;             mu += delta; ls2 *= alpha;
;             if (!first) {
;                 asm volatile("" ::: "memory");
;                 scr[r32] = alpha;
;                 asm volatile("s_waitcnt lgkmcnt(0)" ::: "memory");
; #pragma unroll
;                 for (int g = 0; g < 4; ++g) { const f32x4 a4 = *(const LAS f32x4*)(scr + 8 * g + 4 * hi);
; #pragma unroll
;                     for (int d = 0; d < 4; ++d) { O[d][4 * g + 0] *= a4[0]; O[d][4 * g + 1] *= a4[1]; O[d][4 * g + 2] *= a4[2]; O[d][4 * g + 3] *= a4[3]; } }
;                 asm volatile("s_waitcnt lgkmcnt(0)" ::: "memory");
;             }
; #pragma unroll
.LatA_rareret_h3:
	s_waitcnt lgkmcnt(12)
	v_mfma_f32_32x32x16_bf16 v[20:35], v[84:87], v[132:135], v[20:35]
	ds_read_b64_tr_b16 v[132:133], v231 offset:36864
	ds_read_b64_tr_b16 v[134:135], v231 offset:38912
	v_exp_f32_e32 v188, v188
	v_exp_f32_e32 v189, v189
	s_waitcnt lgkmcnt(12)
	v_mfma_f32_32x32x16_bf16 v[36:51], v[84:87], v[136:139], v[36:51]
	ds_read_b64_tr_b16 v[136:137], v228 offset:40960
	ds_read_b64_tr_b16 v[138:139], v228 offset:43008
	v_exp_f32_e32 v190, v190
	v_exp_f32_e32 v191, v191
	s_waitcnt lgkmcnt(12)
	v_mfma_f32_32x32x16_bf16 v[52:67], v[84:87], v[140:143], v[52:67]
	ds_read_b64_tr_b16 v[140:141], v229 offset:40960
	ds_read_b64_tr_b16 v[142:143], v229 offset:43008
	v_pk_add_f32 v[150:151], v[150:151], v[188:189]
	v_pk_add_f32 v[150:151], v[150:151], v[190:191]
	v_exp_f32_e32 v192, v192
	s_waitcnt lgkmcnt(12)
	s_mov_b32 m0, s28
	v_mfma_f32_32x32x16_bf16 v[68:83], v[84:87], v[144:147], v[68:83]
	global_load_lds_dwordx4 v236, s[8:9]
	ds_read_b64_tr_b16 v[144:145], v230 offset:40960
	ds_read_b64_tr_b16 v[146:147], v230 offset:43008
	v_exp_f32_e32 v193, v193
	v_cvt_pk_bf16_f32 v188, v188, v189
	v_cvt_pk_bf16_f32 v189, v190, v191
	s_waitcnt lgkmcnt(12)
	v_mfma_f32_32x32x16_bf16 v[20:35], v[88:91], v[220:223], v[20:35]
	ds_read_b64_tr_b16 v[220:221], v231 offset:40960
	ds_read_b64_tr_b16 v[222:223], v231 offset:43008
	v_exp_f32_e32 v194, v194
	v_exp_f32_e32 v195, v195
	s_waitcnt lgkmcnt(12)
	v_mfma_f32_32x32x16_bf16 v[36:51], v[88:91], v[224:227], v[36:51]
	ds_read_b64_tr_b16 v[224:225], v228 offset:45056
	ds_read_b64_tr_b16 v[226:227], v228 offset:47104
	v_pk_add_f32 v[150:151], v[150:151], v[192:193]
	v_pk_add_f32 v[150:151], v[150:151], v[194:195]
	v_cvt_pk_bf16_f32 v190, v192, v193
	v_cvt_pk_bf16_f32 v191, v194, v195
	s_waitcnt lgkmcnt(12)
	v_mfma_f32_32x32x16_bf16 v[52:67], v[88:91], v[232:235], v[52:67]
	ds_read_b64_tr_b16 v[232:233], v229 offset:45056
	ds_read_b64_tr_b16 v[234:235], v229 offset:47104
	v_exp_f32_e32 v196, v196
	v_exp_f32_e32 v197, v197
	s_waitcnt lgkmcnt(12)
	s_add_u32 m0, s29, 0x4000
	v_mfma_f32_32x32x16_bf16 v[68:83], v[88:91], v[132:135], v[68:83]
	global_load_lds_dwordx4 v160, s[8:9]
	ds_read_b64_tr_b16 v[132:133], v230 offset:45056
	ds_read_b64_tr_b16 v[134:135], v230 offset:47104
	v_exp_f32_e32 v198, v198
	v_exp_f32_e32 v199, v199
	s_waitcnt lgkmcnt(12)
	v_mfma_f32_32x32x16_bf16 v[20:35], v[100:103], v[136:139], v[20:35]
	ds_read_b64_tr_b16 v[136:137], v231 offset:45056
	ds_read_b64_tr_b16 v[138:139], v231 offset:47104
	v_pk_add_f32 v[150:151], v[150:151], v[196:197]
	v_pk_add_f32 v[150:151], v[150:151], v[198:199]
	v_exp_f32_e32 v200, v200
	s_waitcnt lgkmcnt(12)
	v_mfma_f32_32x32x16_bf16 v[36:51], v[100:103], v[140:143], v[36:51]
	ds_read_b128 v[140:143], v19 offset:16384
	v_exp_f32_e32 v201, v201
	v_cvt_pk_bf16_f32 v192, v196, v197
	v_cvt_pk_bf16_f32 v193, v198, v199
	s_waitcnt lgkmcnt(11)
	v_mfma_f32_32x32x16_bf16 v[52:67], v[100:103], v[144:147], v[52:67]
	ds_read_b128 v[144:147], v19 offset:24576
	v_exp_f32_e32 v202, v202
	v_exp_f32_e32 v203, v203
	s_waitcnt lgkmcnt(10)
	s_add_u32 m0, s28, 0x2000
	v_mfma_f32_32x32x16_bf16 v[68:83], v[100:103], v[220:223], v[68:83]
	global_load_lds_dwordx4 v237, s[8:9]
	ds_read_b128 v[220:223], v180 offset:16384
	v_pk_add_f32 v[150:151], v[150:151], v[200:201]
	v_pk_add_f32 v[150:151], v[150:151], v[202:203]
	v_cvt_pk_bf16_f32 v194, v200, v201
	v_cvt_pk_bf16_f32 v195, v202, v203
	s_waitcnt lgkmcnt(9)
	v_mfma_f32_32x32x16_bf16 v[20:35], v[104:107], v[224:227], v[20:35]
	ds_read_b128 v[224:227], v180 offset:24576
	v_exp_f32_e32 v204, v204
	v_exp_f32_e32 v205, v205
	s_waitcnt lgkmcnt(8)
	v_mfma_f32_32x32x16_bf16 v[36:51], v[104:107], v[232:235], v[36:51]
	ds_read_b128 v[232:235], v181 offset:16384
	v_exp_f32_e32 v206, v206
	v_exp_f32_e32 v207, v207
	s_waitcnt lgkmcnt(7)
	v_mfma_f32_32x32x16_bf16 v[52:67], v[104:107], v[132:135], v[52:67]
	ds_read_b128 v[132:135], v181 offset:24576
	v_pk_add_f32 v[150:151], v[150:151], v[204:205]
	v_pk_add_f32 v[150:151], v[150:151], v[206:207]
	v_exp_f32_e32 v208, v208
	s_waitcnt lgkmcnt(6)
	s_add_u32 m0, s29, 0x6000
	v_mfma_f32_32x32x16_bf16 v[68:83], v[104:107], v[136:139], v[68:83]
	global_load_lds_dwordx4 v176, s[8:9]
	ds_read_b128 v[136:139], v182 offset:16384
	v_exp_f32_e32 v209, v209
	v_cvt_pk_bf16_f32 v204, v204, v205
	v_cvt_pk_bf16_f32 v205, v206, v207
	s_waitcnt lgkmcnt(6)
	v_mfma_f32_32x32x16_bf16 v[84:99], v[140:143], v[116:119], v[2:17]
	ds_read_b128 v[140:143], v182 offset:24576
	v_exp_f32_e32 v210, v210
	v_exp_f32_e32 v211, v211
	s_waitcnt lgkmcnt(6)
	v_mfma_f32_32x32x16_bf16 v[100:115], v[144:147], v[116:119], v[2:17]
	v_pk_add_f32 v[150:151], v[150:151], v[208:209]
	v_pk_add_f32 v[150:151], v[150:151], v[210:211]
	v_cvt_pk_bf16_f32 v206, v208, v209
	v_cvt_pk_bf16_f32 v207, v210, v211
	s_waitcnt lgkmcnt(5)
	v_mfma_f32_32x32x16_bf16 v[84:99], v[220:223], v[120:123], v[84:99]
	v_exp_f32_e32 v212, v212
	v_exp_f32_e32 v213, v213
	s_waitcnt lgkmcnt(4)
	v_mfma_f32_32x32x16_bf16 v[100:115], v[224:227], v[120:123], v[100:115]
	v_exp_f32_e32 v214, v214
	v_exp_f32_e32 v215, v215
	s_waitcnt lgkmcnt(3)
	v_mfma_f32_32x32x16_bf16 v[84:99], v[232:235], v[124:127], v[84:99]
	v_pk_add_f32 v[150:151], v[150:151], v[212:213]
	v_pk_add_f32 v[150:151], v[150:151], v[214:215]
	v_exp_f32_e32 v216, v216
	s_waitcnt lgkmcnt(2)
	v_mfma_f32_32x32x16_bf16 v[100:115], v[132:135], v[124:127], v[100:115]
	v_exp_f32_e32 v217, v217
	v_cvt_pk_bf16_f32 v208, v212, v213
	v_cvt_pk_bf16_f32 v209, v214, v215
	s_waitcnt lgkmcnt(1)
	v_mfma_f32_32x32x16_bf16 v[84:99], v[136:139], v[128:131], v[84:99]
	v_exp_f32_e32 v218, v218
	v_exp_f32_e32 v219, v219
	s_waitcnt lgkmcnt(0)
	v_mfma_f32_32x32x16_bf16 v[100:115], v[140:143], v[128:131], v[100:115]
	v_pk_add_f32 v[150:151], v[150:151], v[216:217]
	v_pk_add_f32 v[150:151], v[150:151], v[218:219]
	v_cvt_pk_bf16_f32 v210, v216, v217
	v_cvt_pk_bf16_f32 v211, v218, v219
	s_add_u32 s8, s8, 0x40000
	s_addc_u32 s9, s9, 0
	s_waitcnt vmcnt(4) lgkmcnt(0)
	s_barrier
	s_movk_i32 s36, 20

; #define LAS __attribute__((address_space(3)))
; __device__ __forceinline__ void attn_unit(LAS unsigned char* lds, const bf16_t* Z, bf16_t* A2, const float* tabg, int seq_base, int S, int h, int qb, float lam) {
;     ...
;             for (int ds = 0; ds < 4; ++ds) { kf[2 * ds] = *(const LAS bf16x8*)(Kt + (kfo ^ (unsigned)(ds << 5))); kf[2 * ds + 1] = *(const LAS bf16x8*)(Kt + 32 * 256 + (kfo ^ (unsigned)(ds << 5))); }
;             __builtin_amdgcn_sched_barrier(0);
;             p0 = __builtin_amdgcn_mfma_f32_32x32x16_bf16(kf[0], qf[0], cblk, 0, 0, 0);
;             p1 = __builtin_amdgcn_mfma_f32_32x32x16_bf16(kf[1], qf[0], cblk, 0, 0, 0);
; #pragma unroll
;             for (int ds = 1; ds < 4; ++ds) {
;                 p0 = __builtin_amdgcn_mfma_f32_32x32x16_bf16(kf[2 * ds], qf[ds], p0, 0, 0, 0);
;                 p1 = __builtin_amdgcn_mfma_f32_32x32x16_bf16(kf[2 * ds + 1], qf[ds], p1, 0, 0, 0);
;             }
;         }
;     ...
;         const unsigned vbase = (unsigned)(size_t)Vt + vfo;
;         s16x4 va[8], vb[8];
;         VREADS1(va, 0);
;         if (near) {
;             const LAS float* tp = tab + (kv0 + 4 * hi - (qlo + r32) + 224);
; #pragma unroll
;             for (int r = 0; r < 16; ++r) { p0[r] += tp[(r & 3) + 8 * (r >> 2)]; p1[r] += tp[32 + (r & 3) + 8 * (r >> 2)]; }
;         }
;         float mx = max2f(max16f(p0), max16f(p1));
;         const bool first = (t == 0);
;         if (first || __any(mx > THR)) {
;             { auto rr = __builtin_amdgcn_permlane32_swap(__float_as_uint(mx), __float_as_uint(mx), false, false); mx = max2f(__uint_as_float(rr[0]), __uint_as_float(rr[1])); }
;             const float delta = first ? mx : fmaxf(mx, 0.f);
;             const float alpha = first ? 1.0f : __builtin_amdgcn_exp2f(-delta);
;             mu += delta; ls2 *= alpha;
;             if (!first) {
;                 asm volatile("" ::: "memory");
;                 scr[r32] = alpha;
;                 asm volatile("s_waitcnt lgkmcnt(0)" ::: "memory");
; #pragma unroll
;                 for (int g = 0; g < 4; ++g) { const f32x4 a4 = *(const LAS f32x4*)(scr + 8 * g + 4 * hi);
; #pragma unroll
;                     for (int d = 0; d < 4; ++d) { O[d][4 * g + 0] *= a4[0]; O[d][4 * g + 1] *= a4[1]; O[d][4 * g + 2] *= a4[2]; O[d][4 * g + 3] *= a4[3]; } }
;                 asm volatile("s_waitcnt lgkmcnt(0)" ::: "memory");
;             }
; #pragma unroll
.LatA_rareret_m0:
	s_waitcnt lgkmcnt(12)
	v_mfma_f32_32x32x16_bf16 v[20:35], v[188:191], v[132:135], v[20:35]
	ds_read_b64_tr_b16 v[132:133], v231 offset:4096
	ds_read_b64_tr_b16 v[134:135], v231 offset:6144
	v_exp_f32_e32 v84, v84
	v_exp_f32_e32 v85, v85
	s_waitcnt lgkmcnt(12)
	v_mfma_f32_32x32x16_bf16 v[36:51], v[188:191], v[136:139], v[36:51]
	ds_read_b64_tr_b16 v[136:137], v228 offset:8192
	ds_read_b64_tr_b16 v[138:139], v228 offset:10240
	v_exp_f32_e32 v86, v86
	v_exp_f32_e32 v87, v87
	s_waitcnt lgkmcnt(12)
	v_mfma_f32_32x32x16_bf16 v[52:67], v[188:191], v[140:143], v[52:67]
	ds_read_b64_tr_b16 v[140:141], v229 offset:8192
	ds_read_b64_tr_b16 v[142:143], v229 offset:10240
	v_pk_add_f32 v[150:151], v[150:151], v[84:85]
	v_pk_add_f32 v[150:151], v[150:151], v[86:87]
	v_exp_f32_e32 v88, v88
	s_waitcnt lgkmcnt(12)
	s_add_u32 m0, s28, 0x4000
	v_mfma_f32_32x32x16_bf16 v[68:83], v[188:191], v[144:147], v[68:83]
	global_load_lds_dwordx4 v236, s[8:9]
	ds_read_b64_tr_b16 v[144:145], v230 offset:8192
	ds_read_b64_tr_b16 v[146:147], v230 offset:10240
	v_exp_f32_e32 v89, v89
	v_cvt_pk_bf16_f32 v84, v84, v85
	v_cvt_pk_bf16_f32 v85, v86, v87
	s_waitcnt lgkmcnt(12)
	v_mfma_f32_32x32x16_bf16 v[20:35], v[192:195], v[220:223], v[20:35]
	ds_read_b64_tr_b16 v[220:221], v231 offset:8192
	ds_read_b64_tr_b16 v[222:223], v231 offset:10240
	v_exp_f32_e32 v90, v90
	v_exp_f32_e32 v91, v91
	s_waitcnt lgkmcnt(12)
	v_mfma_f32_32x32x16_bf16 v[36:51], v[192:195], v[224:227], v[36:51]
	ds_read_b64_tr_b16 v[224:225], v228 offset:12288
	ds_read_b64_tr_b16 v[226:227], v228 offset:14336
	v_pk_add_f32 v[150:151], v[150:151], v[88:89]
	v_pk_add_f32 v[150:151], v[150:151], v[90:91]
	v_cvt_pk_bf16_f32 v86, v88, v89
	v_cvt_pk_bf16_f32 v87, v90, v91
	s_waitcnt lgkmcnt(12)
	v_mfma_f32_32x32x16_bf16 v[52:67], v[192:195], v[232:235], v[52:67]
	ds_read_b64_tr_b16 v[232:233], v229 offset:12288
	ds_read_b64_tr_b16 v[234:235], v229 offset:14336
	v_exp_f32_e32 v92, v92
	v_exp_f32_e32 v93, v93
	s_waitcnt lgkmcnt(12)
	s_add_u32 m0, s29, 0x8000
	v_mfma_f32_32x32x16_bf16 v[68:83], v[192:195], v[132:135], v[68:83]
	global_load_lds_dwordx4 v160, s[8:9]
	ds_read_b64_tr_b16 v[132:133], v230 offset:12288
	ds_read_b64_tr_b16 v[134:135], v230 offset:14336
	v_exp_f32_e32 v94, v94
	v_exp_f32_e32 v95, v95
	s_waitcnt lgkmcnt(12)
	v_mfma_f32_32x32x16_bf16 v[20:35], v[204:207], v[136:139], v[20:35]
	ds_read_b64_tr_b16 v[136:137], v231 offset:12288
	ds_read_b64_tr_b16 v[138:139], v231 offset:14336
	v_pk_add_f32 v[150:151], v[150:151], v[92:93]
	v_pk_add_f32 v[150:151], v[150:151], v[94:95]
	v_exp_f32_e32 v96, v96
	s_waitcnt lgkmcnt(12)
	v_mfma_f32_32x32x16_bf16 v[36:51], v[204:207], v[140:143], v[36:51]
	ds_read_b128 v[140:143], v19 offset:32768
	v_exp_f32_e32 v97, v97
	v_cvt_pk_bf16_f32 v88, v92, v93
	v_cvt_pk_bf16_f32 v89, v94, v95
	s_waitcnt lgkmcnt(11)
	v_mfma_f32_32x32x16_bf16 v[52:67], v[204:207], v[144:147], v[52:67]
	ds_read_b128 v[144:147], v19 offset:40960
	v_exp_f32_e32 v98, v98
	v_exp_f32_e32 v99, v99
	s_waitcnt lgkmcnt(10)
	s_add_u32 m0, s28, 0x6000
	v_mfma_f32_32x32x16_bf16 v[68:83], v[204:207], v[220:223], v[68:83]
	global_load_lds_dwordx4 v237, s[8:9]
	ds_read_b128 v[220:223], v180 offset:32768
	v_pk_add_f32 v[150:151], v[150:151], v[96:97]
	v_pk_add_f32 v[150:151], v[150:151], v[98:99]
	v_cvt_pk_bf16_f32 v90, v96, v97
	v_cvt_pk_bf16_f32 v91, v98, v99
	s_waitcnt lgkmcnt(9)
	v_mfma_f32_32x32x16_bf16 v[20:35], v[208:211], v[224:227], v[20:35]
	ds_read_b128 v[224:227], v180 offset:40960
	v_exp_f32_e32 v100, v100
	v_exp_f32_e32 v101, v101
	s_waitcnt lgkmcnt(8)
	v_mfma_f32_32x32x16_bf16 v[36:51], v[208:211], v[232:235], v[36:51]
	ds_read_b128 v[232:235], v181 offset:32768
	v_exp_f32_e32 v102, v102
	v_exp_f32_e32 v103, v103
	s_waitcnt lgkmcnt(7)
	v_mfma_f32_32x32x16_bf16 v[52:67], v[208:211], v[132:135], v[52:67]
	ds_read_b128 v[132:135], v181 offset:40960
	v_pk_add_f32 v[150:151], v[150:151], v[100:101]
	v_pk_add_f32 v[150:151], v[150:151], v[102:103]
	v_exp_f32_e32 v104, v104
	s_waitcnt lgkmcnt(6)
	s_add_u32 m0, s29, 0xa000
	v_mfma_f32_32x32x16_bf16 v[68:83], v[208:211], v[136:139], v[68:83]
	global_load_lds_dwordx4 v176, s[8:9]
	ds_read_b128 v[136:139], v182 offset:32768
	v_exp_f32_e32 v105, v105
	v_cvt_pk_bf16_f32 v100, v100, v101
	v_cvt_pk_bf16_f32 v101, v102, v103
	s_waitcnt lgkmcnt(6)
	v_mfma_f32_32x32x16_bf16 v[188:203], v[140:143], v[116:119], v[2:17]
	ds_read_b128 v[140:143], v182 offset:40960
	v_exp_f32_e32 v106, v106
	v_exp_f32_e32 v107, v107
	s_waitcnt lgkmcnt(6)
	v_mfma_f32_32x32x16_bf16 v[204:219], v[144:147], v[116:119], v[2:17]
	v_pk_add_f32 v[150:151], v[150:151], v[104:105]
	v_pk_add_f32 v[150:151], v[150:151], v[106:107]
	v_cvt_pk_bf16_f32 v102, v104, v105
	v_cvt_pk_bf16_f32 v103, v106, v107
	s_waitcnt lgkmcnt(5)
	v_mfma_f32_32x32x16_bf16 v[188:203], v[220:223], v[120:123], v[188:203]
	v_exp_f32_e32 v108, v108
	v_exp_f32_e32 v109, v109
	s_waitcnt lgkmcnt(4)
	v_mfma_f32_32x32x16_bf16 v[204:219], v[224:227], v[120:123], v[204:219]
	v_exp_f32_e32 v110, v110
	v_exp_f32_e32 v111, v111
	s_waitcnt lgkmcnt(3)
	v_mfma_f32_32x32x16_bf16 v[188:203], v[232:235], v[124:127], v[188:203]
	v_pk_add_f32 v[150:151], v[150:151], v[108:109]
	v_pk_add_f32 v[150:151], v[150:151], v[110:111]
	v_exp_f32_e32 v112, v112
	s_waitcnt lgkmcnt(2)
	v_mfma_f32_32x32x16_bf16 v[204:219], v[132:135], v[124:127], v[204:219]
	v_exp_f32_e32 v113, v113
	v_cvt_pk_bf16_f32 v104, v108, v109
	v_cvt_pk_bf16_f32 v105, v110, v111
	s_waitcnt lgkmcnt(1)
	v_mfma_f32_32x32x16_bf16 v[188:203], v[136:139], v[128:131], v[188:203]
	v_exp_f32_e32 v114, v114
	v_exp_f32_e32 v115, v115
	s_waitcnt lgkmcnt(0)
	v_mfma_f32_32x32x16_bf16 v[204:219], v[140:143], v[128:131], v[204:219]
	v_pk_add_f32 v[150:151], v[150:151], v[112:113]
	v_pk_add_f32 v[150:151], v[150:151], v[114:115]
	v_cvt_pk_bf16_f32 v106, v112, v113
	v_cvt_pk_bf16_f32 v107, v114, v115
	s_add_u32 s8, s8, 0x40000
	s_addc_u32 s9, s9, 0
	s_waitcnt vmcnt(4) lgkmcnt(0)
	s_barrier
	s_sub_u32 s10, s10, 1
	s_cbranch_scc1 .LatA_evs_m1

; #define LAS __attribute__((address_space(3)))
; __device__ __forceinline__ void attn_unit(LAS unsigned char* lds, const bf16_t* Z, bf16_t* A2, const float* tabg, int seq_base, int S, int h, int qb, float lam) {
;     ...
;             for (int ds = 0; ds < 4; ++ds) { kf[2 * ds] = *(const LAS bf16x8*)(Kt + (kfo ^ (unsigned)(ds << 5))); kf[2 * ds + 1] = *(const LAS bf16x8*)(Kt + 32 * 256 + (kfo ^ (unsigned)(ds << 5))); }
;             __builtin_amdgcn_sched_barrier(0);
;             p0 = __builtin_amdgcn_mfma_f32_32x32x16_bf16(kf[0], qf[0], cblk, 0, 0, 0);
;             p1 = __builtin_amdgcn_mfma_f32_32x32x16_bf16(kf[1], qf[0], cblk, 0, 0, 0);
; #pragma unroll
;             for (int ds = 1; ds < 4; ++ds) {
;                 p0 = __builtin_amdgcn_mfma_f32_32x32x16_bf16(kf[2 * ds], qf[ds], p0, 0, 0, 0);
;                 p1 = __builtin_amdgcn_mfma_f32_32x32x16_bf16(kf[2 * ds + 1], qf[ds], p1, 0, 0, 0);
;             }
;         }
;     ...
;         const unsigned vbase = (unsigned)(size_t)Vt + vfo;
;         s16x4 va[8], vb[8];
;         VREADS1(va, 0);
;         if (near) {
;             const LAS float* tp = tab + (kv0 + 4 * hi - (qlo + r32) + 224);
; #pragma unroll
;             for (int r = 0; r < 16; ++r) { p0[r] += tp[(r & 3) + 8 * (r >> 2)]; p1[r] += tp[32 + (r & 3) + 8 * (r >> 2)]; }
;         }
;         float mx = max2f(max16f(p0), max16f(p1));
;         const bool first = (t == 0);
;         if (first || __any(mx > THR)) {
;             { auto rr = __builtin_amdgcn_permlane32_swap(__float_as_uint(mx), __float_as_uint(mx), false, false); mx = max2f(__uint_as_float(rr[0]), __uint_as_float(rr[1])); }
;             const float delta = first ? mx : fmaxf(mx, 0.f);
;             const float alpha = first ? 1.0f : __builtin_amdgcn_exp2f(-delta);
;             mu += delta; ls2 *= alpha;
;             if (!first) {
;                 asm volatile("" ::: "memory");
;                 scr[r32] = alpha;
;                 asm volatile("s_waitcnt lgkmcnt(0)" ::: "memory");
; #pragma unroll
;                 for (int g = 0; g < 4; ++g) { const f32x4 a4 = *(const LAS f32x4*)(scr + 8 * g + 4 * hi);
; #pragma unroll
;                     for (int d = 0; d < 4; ++d) { O[d][4 * g + 0] *= a4[0]; O[d][4 * g + 1] *= a4[1]; O[d][4 * g + 2] *= a4[2]; O[d][4 * g + 3] *= a4[3]; } }
;                 asm volatile("s_waitcnt lgkmcnt(0)" ::: "memory");
;             }
; #pragma unroll
.LatA_rareret_m1:
	s_waitcnt lgkmcnt(12)
	v_mfma_f32_32x32x16_bf16 v[20:35], v[84:87], v[132:135], v[20:35]
	ds_read_b64_tr_b16 v[132:133], v231 offset:20480
	ds_read_b64_tr_b16 v[134:135], v231 offset:22528
	v_exp_f32_e32 v188, v188
	v_exp_f32_e32 v189, v189
	s_waitcnt lgkmcnt(12)
	v_mfma_f32_32x32x16_bf16 v[36:51], v[84:87], v[136:139], v[36:51]
	ds_read_b64_tr_b16 v[136:137], v228 offset:24576
	ds_read_b64_tr_b16 v[138:139], v228 offset:26624
	v_exp_f32_e32 v190, v190
	v_exp_f32_e32 v191, v191
	s_waitcnt lgkmcnt(12)
	v_mfma_f32_32x32x16_bf16 v[52:67], v[84:87], v[140:143], v[52:67]
	ds_read_b64_tr_b16 v[140:141], v229 offset:24576
	ds_read_b64_tr_b16 v[142:143], v229 offset:26624
	v_pk_add_f32 v[150:151], v[150:151], v[188:189]
	v_pk_add_f32 v[150:151], v[150:151], v[190:191]
	v_exp_f32_e32 v192, v192
	s_waitcnt lgkmcnt(12)
	s_add_u32 m0, s28, 0x8000
	v_mfma_f32_32x32x16_bf16 v[68:83], v[84:87], v[144:147], v[68:83]
	global_load_lds_dwordx4 v236, s[8:9]
	ds_read_b64_tr_b16 v[144:145], v230 offset:24576
	ds_read_b64_tr_b16 v[146:147], v230 offset:26624
	v_exp_f32_e32 v193, v193
	v_cvt_pk_bf16_f32 v188, v188, v189
	v_cvt_pk_bf16_f32 v189, v190, v191
	s_waitcnt lgkmcnt(12)
	v_mfma_f32_32x32x16_bf16 v[20:35], v[88:91], v[220:223], v[20:35]
	ds_read_b64_tr_b16 v[220:221], v231 offset:24576
	ds_read_b64_tr_b16 v[222:223], v231 offset:26624
	v_exp_f32_e32 v194, v194
	v_exp_f32_e32 v195, v195
	s_waitcnt lgkmcnt(12)
	v_mfma_f32_32x32x16_bf16 v[36:51], v[88:91], v[224:227], v[36:51]
	ds_read_b64_tr_b16 v[224:225], v228 offset:28672
	ds_read_b64_tr_b16 v[226:227], v228 offset:30720
	v_pk_add_f32 v[150:151], v[150:151], v[192:193]
	v_pk_add_f32 v[150:151], v[150:151], v[194:195]
	v_cvt_pk_bf16_f32 v190, v192, v193
	v_cvt_pk_bf16_f32 v191, v194, v195
	s_waitcnt lgkmcnt(12)
	v_mfma_f32_32x32x16_bf16 v[52:67], v[88:91], v[232:235], v[52:67]
	ds_read_b64_tr_b16 v[232:233], v229 offset:28672
	ds_read_b64_tr_b16 v[234:235], v229 offset:30720
	v_exp_f32_e32 v196, v196
	v_exp_f32_e32 v197, v197
	s_waitcnt lgkmcnt(12)
	s_mov_b32 m0, s29
	v_mfma_f32_32x32x16_bf16 v[68:83], v[88:91], v[132:135], v[68:83]
	global_load_lds_dwordx4 v160, s[8:9]
	ds_read_b64_tr_b16 v[132:133], v230 offset:28672
	ds_read_b64_tr_b16 v[134:135], v230 offset:30720
	v_exp_f32_e32 v198, v198
	v_exp_f32_e32 v199, v199
	s_waitcnt lgkmcnt(12)
	v_mfma_f32_32x32x16_bf16 v[20:35], v[100:103], v[136:139], v[20:35]
	ds_read_b64_tr_b16 v[136:137], v231 offset:28672
	ds_read_b64_tr_b16 v[138:139], v231 offset:30720
	v_pk_add_f32 v[150:151], v[150:151], v[196:197]
	v_pk_add_f32 v[150:151], v[150:151], v[198:199]
	v_exp_f32_e32 v200, v200
	s_waitcnt lgkmcnt(12)
	v_mfma_f32_32x32x16_bf16 v[36:51], v[100:103], v[140:143], v[36:51]
	ds_read_b128 v[140:143], v19
	v_exp_f32_e32 v201, v201
	v_cvt_pk_bf16_f32 v192, v196, v197
	v_cvt_pk_bf16_f32 v193, v198, v199
	s_waitcnt lgkmcnt(11)
	v_mfma_f32_32x32x16_bf16 v[52:67], v[100:103], v[144:147], v[52:67]
	ds_read_b128 v[144:147], v19 offset:8192
	v_exp_f32_e32 v202, v202
	v_exp_f32_e32 v203, v203
	s_waitcnt lgkmcnt(10)
	s_add_u32 m0, s28, 0xa000
	v_mfma_f32_32x32x16_bf16 v[68:83], v[100:103], v[220:223], v[68:83]
	global_load_lds_dwordx4 v237, s[8:9]
	ds_read_b128 v[220:223], v180
	v_pk_add_f32 v[150:151], v[150:151], v[200:201]
	v_pk_add_f32 v[150:151], v[150:151], v[202:203]
	v_cvt_pk_bf16_f32 v194, v200, v201
	v_cvt_pk_bf16_f32 v195, v202, v203
	s_waitcnt lgkmcnt(9)
	v_mfma_f32_32x32x16_bf16 v[20:35], v[104:107], v[224:227], v[20:35]
	ds_read_b128 v[224:227], v180 offset:8192
	v_exp_f32_e32 v204, v204
	v_exp_f32_e32 v205, v205
	s_waitcnt lgkmcnt(8)
	v_mfma_f32_32x32x16_bf16 v[36:51], v[104:107], v[232:235], v[36:51]
	ds_read_b128 v[232:235], v181
	v_exp_f32_e32 v206, v206
	v_exp_f32_e32 v207, v207
	s_waitcnt lgkmcnt(7)
	v_mfma_f32_32x32x16_bf16 v[52:67], v[104:107], v[132:135], v[52:67]
	ds_read_b128 v[132:135], v181 offset:8192
	v_pk_add_f32 v[150:151], v[150:151], v[204:205]
	v_pk_add_f32 v[150:151], v[150:151], v[206:207]
	v_exp_f32_e32 v208, v208
	s_waitcnt lgkmcnt(6)
	s_add_u32 m0, s29, 0x2000
	v_mfma_f32_32x32x16_bf16 v[68:83], v[104:107], v[136:139], v[68:83]
	global_load_lds_dwordx4 v176, s[8:9]
	ds_read_b128 v[136:139], v182
	v_exp_f32_e32 v209, v209
	v_cvt_pk_bf16_f32 v204, v204, v205
	v_cvt_pk_bf16_f32 v205, v206, v207
	s_waitcnt lgkmcnt(6)
	v_mfma_f32_32x32x16_bf16 v[84:99], v[140:143], v[116:119], v[2:17]
	ds_read_b128 v[140:143], v182 offset:8192
	v_exp_f32_e32 v210, v210
	v_exp_f32_e32 v211, v211
	s_waitcnt lgkmcnt(6)
	v_mfma_f32_32x32x16_bf16 v[100:115], v[144:147], v[116:119], v[2:17]
	v_pk_add_f32 v[150:151], v[150:151], v[208:209]
	v_pk_add_f32 v[150:151], v[150:151], v[210:211]
	v_cvt_pk_bf16_f32 v206, v208, v209
	v_cvt_pk_bf16_f32 v207, v210, v211
	s_waitcnt lgkmcnt(5)
	v_mfma_f32_32x32x16_bf16 v[84:99], v[220:223], v[120:123], v[84:99]
	v_exp_f32_e32 v212, v212
	v_exp_f32_e32 v213, v213
	s_waitcnt lgkmcnt(4)
	v_mfma_f32_32x32x16_bf16 v[100:115], v[224:227], v[120:123], v[100:115]
	v_exp_f32_e32 v214, v214
	v_exp_f32_e32 v215, v215
	s_waitcnt lgkmcnt(3)
	v_mfma_f32_32x32x16_bf16 v[84:99], v[232:235], v[124:127], v[84:99]
	v_pk_add_f32 v[150:151], v[150:151], v[212:213]
	v_pk_add_f32 v[150:151], v[150:151], v[214:215]
	v_exp_f32_e32 v216, v216
	s_waitcnt lgkmcnt(2)
	v_mfma_f32_32x32x16_bf16 v[100:115], v[132:135], v[124:127], v[100:115]
	v_exp_f32_e32 v217, v217
	v_cvt_pk_bf16_f32 v208, v212, v213
	v_cvt_pk_bf16_f32 v209, v214, v215
	s_waitcnt lgkmcnt(1)
	v_mfma_f32_32x32x16_bf16 v[84:99], v[136:139], v[128:131], v[84:99]
	v_exp_f32_e32 v218, v218
	v_exp_f32_e32 v219, v219
	s_waitcnt lgkmcnt(0)
	v_mfma_f32_32x32x16_bf16 v[100:115], v[140:143], v[128:131], v[100:115]
	v_pk_add_f32 v[150:151], v[150:151], v[216:217]
	v_pk_add_f32 v[150:151], v[150:151], v[218:219]
	v_cvt_pk_bf16_f32 v210, v216, v217
	v_cvt_pk_bf16_f32 v211, v218, v219
	s_add_u32 s8, s8, 0x40000
	s_addc_u32 s9, s9, 0
	s_waitcnt vmcnt(4) lgkmcnt(0)
	s_barrier
	s_sub_u32 s10, s10, 1
	s_cbranch_scc1 .LatA_evs_m2

; #define LAS __attribute__((address_space(3)))
; __device__ __forceinline__ void attn_unit(LAS unsigned char* lds, const bf16_t* Z, bf16_t* A2, const float* tabg, int seq_base, int S, int h, int qb, float lam) {
;     ...
;             for (int ds = 0; ds < 4; ++ds) { kf[2 * ds] = *(const LAS bf16x8*)(Kt + (kfo ^ (unsigned)(ds << 5))); kf[2 * ds + 1] = *(const LAS bf16x8*)(Kt + 32 * 256 + (kfo ^ (unsigned)(ds << 5))); }
;             __builtin_amdgcn_sched_barrier(0);
;             p0 = __builtin_amdgcn_mfma_f32_32x32x16_bf16(kf[0], qf[0], cblk, 0, 0, 0);
;             p1 = __builtin_amdgcn_mfma_f32_32x32x16_bf16(kf[1], qf[0], cblk, 0, 0, 0);
; #pragma unroll
;             for (int ds = 1; ds < 4; ++ds) {
;                 p0 = __builtin_amdgcn_mfma_f32_32x32x16_bf16(kf[2 * ds], qf[ds], p0, 0, 0, 0);
;                 p1 = __builtin_amdgcn_mfma_f32_32x32x16_bf16(kf[2 * ds + 1], qf[ds], p1, 0, 0, 0);
;             }
;         }
;     ...
;         const unsigned vbase = (unsigned)(size_t)Vt + vfo;
;         s16x4 va[8], vb[8];
;         VREADS1(va, 0);
;         if (near) {
;             const LAS float* tp = tab + (kv0 + 4 * hi - (qlo + r32) + 224);
; #pragma unroll
;             for (int r = 0; r < 16; ++r) { p0[r] += tp[(r & 3) + 8 * (r >> 2)]; p1[r] += tp[32 + (r & 3) + 8 * (r >> 2)]; }
;         }
;         float mx = max2f(max16f(p0), max16f(p1));
;         const bool first = (t == 0);
;         if (first || __any(mx > THR)) {
;             { auto rr = __builtin_amdgcn_permlane32_swap(__float_as_uint(mx), __float_as_uint(mx), false, false); mx = max2f(__uint_as_float(rr[0]), __uint_as_float(rr[1])); }
;             const float delta = first ? mx : fmaxf(mx, 0.f);
;             const float alpha = first ? 1.0f : __builtin_amdgcn_exp2f(-delta);
;             mu += delta; ls2 *= alpha;
;             if (!first) {
;                 asm volatile("" ::: "memory");
;                 scr[r32] = alpha;
;                 asm volatile("s_waitcnt lgkmcnt(0)" ::: "memory");
; #pragma unroll
;                 for (int g = 0; g < 4; ++g) { const f32x4 a4 = *(const LAS f32x4*)(scr + 8 * g + 4 * hi);
; #pragma unroll
;                     for (int d = 0; d < 4; ++d) { O[d][4 * g + 0] *= a4[0]; O[d][4 * g + 1] *= a4[1]; O[d][4 * g + 2] *= a4[2]; O[d][4 * g + 3] *= a4[3]; } }
;                 asm volatile("s_waitcnt lgkmcnt(0)" ::: "memory");
;             }
; #pragma unroll
.LatA_rareret_m2:
	s_waitcnt lgkmcnt(12)
	v_mfma_f32_32x32x16_bf16 v[20:35], v[188:191], v[132:135], v[20:35]
	ds_read_b64_tr_b16 v[132:133], v231 offset:36864
	ds_read_b64_tr_b16 v[134:135], v231 offset:38912
	v_exp_f32_e32 v84, v84
	v_exp_f32_e32 v85, v85
	s_waitcnt lgkmcnt(12)
	v_mfma_f32_32x32x16_bf16 v[36:51], v[188:191], v[136:139], v[36:51]
	ds_read_b64_tr_b16 v[136:137], v228 offset:40960
	ds_read_b64_tr_b16 v[138:139], v228 offset:43008
	v_exp_f32_e32 v86, v86
	v_exp_f32_e32 v87, v87
	s_waitcnt lgkmcnt(12)
	v_mfma_f32_32x32x16_bf16 v[52:67], v[188:191], v[140:143], v[52:67]
	ds_read_b64_tr_b16 v[140:141], v229 offset:40960
	ds_read_b64_tr_b16 v[142:143], v229 offset:43008
	v_pk_add_f32 v[150:151], v[150:151], v[84:85]
	v_pk_add_f32 v[150:151], v[150:151], v[86:87]
	v_exp_f32_e32 v88, v88
	s_waitcnt lgkmcnt(12)
	s_mov_b32 m0, s28
	v_mfma_f32_32x32x16_bf16 v[68:83], v[188:191], v[144:147], v[68:83]
	global_load_lds_dwordx4 v236, s[8:9]
	ds_read_b64_tr_b16 v[144:145], v230 offset:40960
	ds_read_b64_tr_b16 v[146:147], v230 offset:43008
	v_exp_f32_e32 v89, v89
	v_cvt_pk_bf16_f32 v84, v84, v85
	v_cvt_pk_bf16_f32 v85, v86, v87
	s_waitcnt lgkmcnt(12)
	v_mfma_f32_32x32x16_bf16 v[20:35], v[192:195], v[220:223], v[20:35]
	ds_read_b64_tr_b16 v[220:221], v231 offset:40960
	ds_read_b64_tr_b16 v[222:223], v231 offset:43008
	v_exp_f32_e32 v90, v90
	v_exp_f32_e32 v91, v91
	s_waitcnt lgkmcnt(12)
	v_mfma_f32_32x32x16_bf16 v[36:51], v[192:195], v[224:227], v[36:51]
	ds_read_b64_tr_b16 v[224:225], v228 offset:45056
	ds_read_b64_tr_b16 v[226:227], v228 offset:47104
	v_pk_add_f32 v[150:151], v[150:151], v[88:89]
	v_pk_add_f32 v[150:151], v[150:151], v[90:91]
	v_cvt_pk_bf16_f32 v86, v88, v89
	v_cvt_pk_bf16_f32 v87, v90, v91
	s_waitcnt lgkmcnt(12)
	v_mfma_f32_32x32x16_bf16 v[52:67], v[192:195], v[232:235], v[52:67]
	ds_read_b64_tr_b16 v[232:233], v229 offset:45056
	ds_read_b64_tr_b16 v[234:235], v229 offset:47104
	v_exp_f32_e32 v92, v92
	v_exp_f32_e32 v93, v93
	s_waitcnt lgkmcnt(12)
	s_add_u32 m0, s29, 0x4000
	v_mfma_f32_32x32x16_bf16 v[68:83], v[192:195], v[132:135], v[68:83]
	global_load_lds_dwordx4 v160, s[8:9]
	ds_read_b64_tr_b16 v[132:133], v230 offset:45056
	ds_read_b64_tr_b16 v[134:135], v230 offset:47104
	v_exp_f32_e32 v94, v94
	v_exp_f32_e32 v95, v95
	s_waitcnt lgkmcnt(12)
	v_mfma_f32_32x32x16_bf16 v[20:35], v[204:207], v[136:139], v[20:35]
	ds_read_b64_tr_b16 v[136:137], v231 offset:45056
	ds_read_b64_tr_b16 v[138:139], v231 offset:47104
	v_pk_add_f32 v[150:151], v[150:151], v[92:93]
	v_pk_add_f32 v[150:151], v[150:151], v[94:95]
	v_exp_f32_e32 v96, v96
	s_waitcnt lgkmcnt(12)
	v_mfma_f32_32x32x16_bf16 v[36:51], v[204:207], v[140:143], v[36:51]
	ds_read_b128 v[140:143], v19 offset:16384
	v_exp_f32_e32 v97, v97
	v_cvt_pk_bf16_f32 v88, v92, v93
	v_cvt_pk_bf16_f32 v89, v94, v95
	s_waitcnt lgkmcnt(11)
	v_mfma_f32_32x32x16_bf16 v[52:67], v[204:207], v[144:147], v[52:67]
	ds_read_b128 v[144:147], v19 offset:24576
	v_exp_f32_e32 v98, v98
	v_exp_f32_e32 v99, v99
	s_waitcnt lgkmcnt(10)
	s_add_u32 m0, s28, 0x2000
	v_mfma_f32_32x32x16_bf16 v[68:83], v[204:207], v[220:223], v[68:83]
	global_load_lds_dwordx4 v237, s[8:9]
	ds_read_b128 v[220:223], v180 offset:16384
	v_pk_add_f32 v[150:151], v[150:151], v[96:97]
	v_pk_add_f32 v[150:151], v[150:151], v[98:99]
	v_cvt_pk_bf16_f32 v90, v96, v97
	v_cvt_pk_bf16_f32 v91, v98, v99
	s_waitcnt lgkmcnt(9)
	v_mfma_f32_32x32x16_bf16 v[20:35], v[208:211], v[224:227], v[20:35]
	ds_read_b128 v[224:227], v180 offset:24576
	v_exp_f32_e32 v100, v100
	v_exp_f32_e32 v101, v101
	s_waitcnt lgkmcnt(8)
	v_mfma_f32_32x32x16_bf16 v[36:51], v[208:211], v[232:235], v[36:51]
	ds_read_b128 v[232:235], v181 offset:16384
	v_exp_f32_e32 v102, v102
	v_exp_f32_e32 v103, v103
	s_waitcnt lgkmcnt(7)
	v_mfma_f32_32x32x16_bf16 v[52:67], v[208:211], v[132:135], v[52:67]
	ds_read_b128 v[132:135], v181 offset:24576
	v_pk_add_f32 v[150:151], v[150:151], v[100:101]
	v_pk_add_f32 v[150:151], v[150:151], v[102:103]
	v_exp_f32_e32 v104, v104
	s_waitcnt lgkmcnt(6)
	s_add_u32 m0, s29, 0x6000
	v_mfma_f32_32x32x16_bf16 v[68:83], v[208:211], v[136:139], v[68:83]
	global_load_lds_dwordx4 v176, s[8:9]
	ds_read_b128 v[136:139], v182 offset:16384
	v_exp_f32_e32 v105, v105
	v_cvt_pk_bf16_f32 v100, v100, v101
	v_cvt_pk_bf16_f32 v101, v102, v103
	s_waitcnt lgkmcnt(6)
	v_mfma_f32_32x32x16_bf16 v[188:203], v[140:143], v[116:119], v[2:17]
	ds_read_b128 v[140:143], v182 offset:24576
	v_exp_f32_e32 v106, v106
	v_exp_f32_e32 v107, v107
	s_waitcnt lgkmcnt(6)
	v_mfma_f32_32x32x16_bf16 v[204:219], v[144:147], v[116:119], v[2:17]
	v_pk_add_f32 v[150:151], v[150:151], v[104:105]
	v_pk_add_f32 v[150:151], v[150:151], v[106:107]
	v_cvt_pk_bf16_f32 v102, v104, v105
	v_cvt_pk_bf16_f32 v103, v106, v107
	s_waitcnt lgkmcnt(5)
	v_mfma_f32_32x32x16_bf16 v[188:203], v[220:223], v[120:123], v[188:203]
	v_exp_f32_e32 v108, v108
	v_exp_f32_e32 v109, v109
	s_waitcnt lgkmcnt(4)
	v_mfma_f32_32x32x16_bf16 v[204:219], v[224:227], v[120:123], v[204:219]
	v_exp_f32_e32 v110, v110
	v_exp_f32_e32 v111, v111
	s_waitcnt lgkmcnt(3)
	v_mfma_f32_32x32x16_bf16 v[188:203], v[232:235], v[124:127], v[188:203]
	v_pk_add_f32 v[150:151], v[150:151], v[108:109]
	v_pk_add_f32 v[150:151], v[150:151], v[110:111]
	v_exp_f32_e32 v112, v112
	s_waitcnt lgkmcnt(2)
	v_mfma_f32_32x32x16_bf16 v[204:219], v[132:135], v[124:127], v[204:219]
	v_exp_f32_e32 v113, v113
	v_cvt_pk_bf16_f32 v104, v108, v109
	v_cvt_pk_bf16_f32 v105, v110, v111
	s_waitcnt lgkmcnt(1)
	v_mfma_f32_32x32x16_bf16 v[188:203], v[136:139], v[128:131], v[188:203]
	v_exp_f32_e32 v114, v114
	v_exp_f32_e32 v115, v115
	s_waitcnt lgkmcnt(0)
	v_mfma_f32_32x32x16_bf16 v[204:219], v[140:143], v[128:131], v[204:219]
	v_pk_add_f32 v[150:151], v[150:151], v[112:113]
	v_pk_add_f32 v[150:151], v[150:151], v[114:115]
	v_cvt_pk_bf16_f32 v106, v112, v113
	v_cvt_pk_bf16_f32 v107, v114, v115
	s_add_u32 s8, s8, 0x40000
	s_addc_u32 s9, s9, 0
	s_waitcnt vmcnt(4) lgkmcnt(0)
	s_barrier
	s_sub_u32 s10, s10, 1
	s_cbranch_scc1 .LatA_evs_m3

; #define LAS __attribute__((address_space(3)))
; __device__ __forceinline__ void attn_unit(LAS unsigned char* lds, const bf16_t* Z, bf16_t* A2, const float* tabg, int seq_base, int S, int h, int qb, float lam) {
;     ...
;             for (int ds = 0; ds < 4; ++ds) { kf[2 * ds] = *(const LAS bf16x8*)(Kt + (kfo ^ (unsigned)(ds << 5))); kf[2 * ds + 1] = *(const LAS bf16x8*)(Kt + 32 * 256 + (kfo ^ (unsigned)(ds << 5))); }
;             __builtin_amdgcn_sched_barrier(0);
;             p0 = __builtin_amdgcn_mfma_f32_32x32x16_bf16(kf[0], qf[0], cblk, 0, 0, 0);
;             p1 = __builtin_amdgcn_mfma_f32_32x32x16_bf16(kf[1], qf[0], cblk, 0, 0, 0);
; #pragma unroll
;             for (int ds = 1; ds < 4; ++ds) {
;                 p0 = __builtin_amdgcn_mfma_f32_32x32x16_bf16(kf[2 * ds], qf[ds], p0, 0, 0, 0);
;                 p1 = __builtin_amdgcn_mfma_f32_32x32x16_bf16(kf[2 * ds + 1], qf[ds], p1, 0, 0, 0);
;             }
;         }
;     ...
;         const unsigned vbase = (unsigned)(size_t)Vt + vfo;
;         s16x4 va[8], vb[8];
;         VREADS1(va, 0);
;         if (near) {
;             const LAS float* tp = tab + (kv0 + 4 * hi - (qlo + r32) + 224);
; #pragma unroll
;             for (int r = 0; r < 16; ++r) { p0[r] += tp[(r & 3) + 8 * (r >> 2)]; p1[r] += tp[32 + (r & 3) + 8 * (r >> 2)]; }
;         }
;         float mx = max2f(max16f(p0), max16f(p1));
;         const bool first = (t == 0);
;         if (first || __any(mx > THR)) {
;             { auto rr = __builtin_amdgcn_permlane32_swap(__float_as_uint(mx), __float_as_uint(mx), false, false); mx = max2f(__uint_as_float(rr[0]), __uint_as_float(rr[1])); }
;             const float delta = first ? mx : fmaxf(mx, 0.f);
;             const float alpha = first ? 1.0f : __builtin_amdgcn_exp2f(-delta);
;             mu += delta; ls2 *= alpha;
;             if (!first) {
;                 asm volatile("" ::: "memory");
;                 scr[r32] = alpha;
;                 asm volatile("s_waitcnt lgkmcnt(0)" ::: "memory");
; #pragma unroll
;                 for (int g = 0; g < 4; ++g) { const f32x4 a4 = *(const LAS f32x4*)(scr + 8 * g + 4 * hi);
; #pragma unroll
;                     for (int d = 0; d < 4; ++d) { O[d][4 * g + 0] *= a4[0]; O[d][4 * g + 1] *= a4[1]; O[d][4 * g + 2] *= a4[2]; O[d][4 * g + 3] *= a4[3]; } }
;                 asm volatile("s_waitcnt lgkmcnt(0)" ::: "memory");
;             }
; #pragma unroll
.LatA_rareret_m5:
	s_waitcnt lgkmcnt(12)
	v_mfma_f32_32x32x16_bf16 v[20:35], v[84:87], v[132:135], v[20:35]
	ds_read_b64_tr_b16 v[132:133], v231 offset:36864
	ds_read_b64_tr_b16 v[134:135], v231 offset:38912
	v_exp_f32_e32 v188, v188
	v_exp_f32_e32 v189, v189
	s_waitcnt lgkmcnt(12)
	v_mfma_f32_32x32x16_bf16 v[36:51], v[84:87], v[136:139], v[36:51]
	ds_read_b64_tr_b16 v[136:137], v228 offset:40960
	ds_read_b64_tr_b16 v[138:139], v228 offset:43008
	v_exp_f32_e32 v190, v190
	v_exp_f32_e32 v191, v191
	s_waitcnt lgkmcnt(12)
	v_mfma_f32_32x32x16_bf16 v[52:67], v[84:87], v[140:143], v[52:67]
	ds_read_b64_tr_b16 v[140:141], v229 offset:40960
	ds_read_b64_tr_b16 v[142:143], v229 offset:43008
	v_pk_add_f32 v[150:151], v[150:151], v[188:189]
	v_pk_add_f32 v[150:151], v[150:151], v[190:191]
	v_exp_f32_e32 v192, v192
	s_waitcnt lgkmcnt(12)
	s_mov_b32 m0, s28
	v_mfma_f32_32x32x16_bf16 v[68:83], v[84:87], v[144:147], v[68:83]
	global_load_lds_dwordx4 v236, s[8:9]
	ds_read_b64_tr_b16 v[144:145], v230 offset:40960
	ds_read_b64_tr_b16 v[146:147], v230 offset:43008
	v_exp_f32_e32 v193, v193
	v_cvt_pk_bf16_f32 v188, v188, v189
	v_cvt_pk_bf16_f32 v189, v190, v191
	s_waitcnt lgkmcnt(12)
	v_mfma_f32_32x32x16_bf16 v[20:35], v[88:91], v[220:223], v[20:35]
	ds_read_b64_tr_b16 v[220:221], v231 offset:40960
	ds_read_b64_tr_b16 v[222:223], v231 offset:43008
	v_exp_f32_e32 v194, v194
	v_exp_f32_e32 v195, v195
	s_waitcnt lgkmcnt(12)
	v_mfma_f32_32x32x16_bf16 v[36:51], v[88:91], v[224:227], v[36:51]
	ds_read_b64_tr_b16 v[224:225], v228 offset:45056
	ds_read_b64_tr_b16 v[226:227], v228 offset:47104
	v_pk_add_f32 v[150:151], v[150:151], v[192:193]
	v_pk_add_f32 v[150:151], v[150:151], v[194:195]
	v_cvt_pk_bf16_f32 v190, v192, v193
	v_cvt_pk_bf16_f32 v191, v194, v195
	s_waitcnt lgkmcnt(12)
	v_mfma_f32_32x32x16_bf16 v[52:67], v[88:91], v[232:235], v[52:67]
	ds_read_b64_tr_b16 v[232:233], v229 offset:45056
	ds_read_b64_tr_b16 v[234:235], v229 offset:47104
	v_exp_f32_e32 v196, v196
	v_exp_f32_e32 v197, v197
	s_waitcnt lgkmcnt(12)
	s_add_u32 m0, s29, 0x4000
	v_mfma_f32_32x32x16_bf16 v[68:83], v[88:91], v[132:135], v[68:83]
	global_load_lds_dwordx4 v160, s[8:9]
	ds_read_b64_tr_b16 v[132:133], v230 offset:45056
	ds_read_b64_tr_b16 v[134:135], v230 offset:47104
	v_exp_f32_e32 v198, v198
	v_exp_f32_e32 v199, v199
	s_waitcnt lgkmcnt(12)
	v_mfma_f32_32x32x16_bf16 v[20:35], v[100:103], v[136:139], v[20:35]
	ds_read_b64_tr_b16 v[136:137], v231 offset:45056
	ds_read_b64_tr_b16 v[138:139], v231 offset:47104
	v_pk_add_f32 v[150:151], v[150:151], v[196:197]
	v_pk_add_f32 v[150:151], v[150:151], v[198:199]
	v_exp_f32_e32 v200, v200
	s_waitcnt lgkmcnt(12)
	v_mfma_f32_32x32x16_bf16 v[36:51], v[100:103], v[140:143], v[36:51]
	ds_read_b128 v[140:143], v19 offset:16384
	v_exp_f32_e32 v201, v201
	v_cvt_pk_bf16_f32 v192, v196, v197
	v_cvt_pk_bf16_f32 v193, v198, v199
	s_waitcnt lgkmcnt(11)
	v_mfma_f32_32x32x16_bf16 v[52:67], v[100:103], v[144:147], v[52:67]
	ds_read_b128 v[144:147], v19 offset:24576
	v_exp_f32_e32 v202, v202
	v_exp_f32_e32 v203, v203
	s_waitcnt lgkmcnt(10)
	s_add_u32 m0, s28, 0x2000
	v_mfma_f32_32x32x16_bf16 v[68:83], v[100:103], v[220:223], v[68:83]
	global_load_lds_dwordx4 v237, s[8:9]
	ds_read_b128 v[220:223], v180 offset:16384
	v_pk_add_f32 v[150:151], v[150:151], v[200:201]
	v_pk_add_f32 v[150:151], v[150:151], v[202:203]
	v_cvt_pk_bf16_f32 v194, v200, v201
	v_cvt_pk_bf16_f32 v195, v202, v203
	s_waitcnt lgkmcnt(9)
	v_mfma_f32_32x32x16_bf16 v[20:35], v[104:107], v[224:227], v[20:35]
	ds_read_b128 v[224:227], v180 offset:24576
	v_exp_f32_e32 v204, v204
	v_exp_f32_e32 v205, v205
	s_waitcnt lgkmcnt(8)
	v_mfma_f32_32x32x16_bf16 v[36:51], v[104:107], v[232:235], v[36:51]
	ds_read_b128 v[232:235], v181 offset:16384
	v_exp_f32_e32 v206, v206
	v_exp_f32_e32 v207, v207
	s_waitcnt lgkmcnt(7)
	v_mfma_f32_32x32x16_bf16 v[52:67], v[104:107], v[132:135], v[52:67]
	ds_read_b128 v[132:135], v181 offset:24576
	v_pk_add_f32 v[150:151], v[150:151], v[204:205]
	v_pk_add_f32 v[150:151], v[150:151], v[206:207]
	v_exp_f32_e32 v208, v208
	s_waitcnt lgkmcnt(6)
	s_add_u32 m0, s29, 0x6000
	v_mfma_f32_32x32x16_bf16 v[68:83], v[104:107], v[136:139], v[68:83]
	global_load_lds_dwordx4 v176, s[8:9]
	ds_read_b128 v[136:139], v182 offset:16384
	v_exp_f32_e32 v209, v209
	v_cvt_pk_bf16_f32 v204, v204, v205
	v_cvt_pk_bf16_f32 v205, v206, v207
	s_waitcnt lgkmcnt(6)
	v_mfma_f32_32x32x16_bf16 v[84:99], v[140:143], v[116:119], v[2:17]
	ds_read_b128 v[140:143], v182 offset:24576
	v_exp_f32_e32 v210, v210
	v_exp_f32_e32 v211, v211
	s_waitcnt lgkmcnt(6)
	v_mfma_f32_32x32x16_bf16 v[100:115], v[144:147], v[116:119], v[2:17]
	v_pk_add_f32 v[150:151], v[150:151], v[208:209]
	v_pk_add_f32 v[150:151], v[150:151], v[210:211]
	v_cvt_pk_bf16_f32 v206, v208, v209
	v_cvt_pk_bf16_f32 v207, v210, v211
	s_waitcnt lgkmcnt(5)
	v_mfma_f32_32x32x16_bf16 v[84:99], v[220:223], v[120:123], v[84:99]
	v_exp_f32_e32 v212, v212
	v_exp_f32_e32 v213, v213
	s_waitcnt lgkmcnt(4)
	v_mfma_f32_32x32x16_bf16 v[100:115], v[224:227], v[120:123], v[100:115]
	v_exp_f32_e32 v214, v214
	v_exp_f32_e32 v215, v215
	s_waitcnt lgkmcnt(3)
	v_mfma_f32_32x32x16_bf16 v[84:99], v[232:235], v[124:127], v[84:99]
	v_pk_add_f32 v[150:151], v[150:151], v[212:213]
	v_pk_add_f32 v[150:151], v[150:151], v[214:215]
	v_exp_f32_e32 v216, v216
	s_waitcnt lgkmcnt(2)
	v_mfma_f32_32x32x16_bf16 v[100:115], v[132:135], v[124:127], v[100:115]
	v_exp_f32_e32 v217, v217
	v_cvt_pk_bf16_f32 v208, v212, v213
	v_cvt_pk_bf16_f32 v209, v214, v215
	s_waitcnt lgkmcnt(1)
	v_mfma_f32_32x32x16_bf16 v[84:99], v[136:139], v[128:131], v[84:99]
	v_exp_f32_e32 v218, v218
	v_exp_f32_e32 v219, v219
	s_waitcnt lgkmcnt(0)
	v_mfma_f32_32x32x16_bf16 v[100:115], v[140:143], v[128:131], v[100:115]
	v_pk_add_f32 v[150:151], v[150:151], v[216:217]
	v_pk_add_f32 v[150:151], v[150:151], v[218:219]
	v_cvt_pk_bf16_f32 v210, v216, v217
	v_cvt_pk_bf16_f32 v211, v218, v219
	s_add_u32 s8, s8, 0x40000
	s_addc_u32 s9, s9, 0
	s_waitcnt vmcnt(4) lgkmcnt(0)
	s_barrier
	s_sub_u32 s36, s36, 1
	s_cmp_lg_u32 s36, 0
	s_cbranch_scc1 .LatA_loop
	s_sub_u32 s10, s10, 1
	s_cbranch_scc1 .LatA_evs_x4

; #define LAS __attribute__((address_space(3)))
; __device__ __forceinline__ void attn_unit(LAS unsigned char* lds, const bf16_t* Z, bf16_t* A2, const float* tabg, int seq_base, int S, int h, int qb, float lam) {
;     ...
;             for (int ds = 0; ds < 4; ++ds) { kf[2 * ds] = *(const LAS bf16x8*)(Kt + (kfo ^ (unsigned)(ds << 5))); kf[2 * ds + 1] = *(const LAS bf16x8*)(Kt + 32 * 256 + (kfo ^ (unsigned)(ds << 5))); }
;             __builtin_amdgcn_sched_barrier(0);
;             p0 = __builtin_amdgcn_mfma_f32_32x32x16_bf16(kf[0], qf[0], cblk, 0, 0, 0);
;             p1 = __builtin_amdgcn_mfma_f32_32x32x16_bf16(kf[1], qf[0], cblk, 0, 0, 0);
; #pragma unroll
;             for (int ds = 1; ds < 4; ++ds) {
;                 p0 = __builtin_amdgcn_mfma_f32_32x32x16_bf16(kf[2 * ds], qf[ds], p0, 0, 0, 0);
;                 p1 = __builtin_amdgcn_mfma_f32_32x32x16_bf16(kf[2 * ds + 1], qf[ds], p1, 0, 0, 0);
;             }
;         }
;     ...
;         const unsigned vbase = (unsigned)(size_t)Vt + vfo;
;         s16x4 va[8], vb[8];
;         VREADS1(va, 0);
;         if (near) {
;             const LAS float* tp = tab + (kv0 + 4 * hi - (qlo + r32) + 224);
; #pragma unroll
;             for (int r = 0; r < 16; ++r) { p0[r] += tp[(r & 3) + 8 * (r >> 2)]; p1[r] += tp[32 + (r & 3) + 8 * (r >> 2)]; }
;         }
;         float mx = max2f(max16f(p0), max16f(p1));
;         const bool first = (t == 0);
;         if (first || __any(mx > THR)) {
;             { auto rr = __builtin_amdgcn_permlane32_swap(__float_as_uint(mx), __float_as_uint(mx), false, false); mx = max2f(__uint_as_float(rr[0]), __uint_as_float(rr[1])); }
;             const float delta = first ? mx : fmaxf(mx, 0.f);
;             const float alpha = first ? 1.0f : __builtin_amdgcn_exp2f(-delta);
;             mu += delta; ls2 *= alpha;
;             if (!first) {
;                 asm volatile("" ::: "memory");
;                 scr[r32] = alpha;
;                 asm volatile("s_waitcnt lgkmcnt(0)" ::: "memory");
; #pragma unroll
;                 for (int g = 0; g < 4; ++g) { const f32x4 a4 = *(const LAS f32x4*)(scr + 8 * g + 4 * hi);
; #pragma unroll
;                     for (int d = 0; d < 4; ++d) { O[d][4 * g + 0] *= a4[0]; O[d][4 * g + 1] *= a4[1]; O[d][4 * g + 2] *= a4[2]; O[d][4 * g + 3] *= a4[3]; } }
;                 asm volatile("s_waitcnt lgkmcnt(0)" ::: "memory");
;             }
; #pragma unroll
.LatA_rareret_x3:
	s_waitcnt lgkmcnt(12)
	v_mfma_f32_32x32x16_bf16 v[20:35], v[84:87], v[132:135], v[20:35]
	ds_read_b64_tr_b16 v[132:133], v231 offset:20480
	ds_read_b64_tr_b16 v[134:135], v231 offset:22528
	v_exp_f32_e32 v188, v188
	v_exp_f32_e32 v189, v189
	s_waitcnt lgkmcnt(12)
	v_mfma_f32_32x32x16_bf16 v[36:51], v[84:87], v[136:139], v[36:51]
	ds_read_b64_tr_b16 v[136:137], v228 offset:24576
	ds_read_b64_tr_b16 v[138:139], v228 offset:26624
	v_exp_f32_e32 v190, v190
	v_exp_f32_e32 v191, v191
	s_waitcnt lgkmcnt(12)
	v_mfma_f32_32x32x16_bf16 v[52:67], v[84:87], v[140:143], v[52:67]
	ds_read_b64_tr_b16 v[140:141], v229 offset:24576
	ds_read_b64_tr_b16 v[142:143], v229 offset:26624
	v_pk_add_f32 v[150:151], v[150:151], v[188:189]
	v_pk_add_f32 v[150:151], v[150:151], v[190:191]
	v_exp_f32_e32 v192, v192
	s_waitcnt lgkmcnt(12)
	v_mfma_f32_32x32x16_bf16 v[68:83], v[84:87], v[144:147], v[68:83]
	ds_read_b64_tr_b16 v[144:145], v230 offset:24576
	ds_read_b64_tr_b16 v[146:147], v230 offset:26624
	v_exp_f32_e32 v193, v193
	v_cvt_pk_bf16_f32 v188, v188, v189
	v_cvt_pk_bf16_f32 v189, v190, v191
	s_waitcnt lgkmcnt(12)
	v_mfma_f32_32x32x16_bf16 v[20:35], v[88:91], v[220:223], v[20:35]
	ds_read_b64_tr_b16 v[220:221], v231 offset:24576
	ds_read_b64_tr_b16 v[222:223], v231 offset:26624
	v_exp_f32_e32 v194, v194
	v_exp_f32_e32 v195, v195
	s_waitcnt lgkmcnt(12)
	v_mfma_f32_32x32x16_bf16 v[36:51], v[88:91], v[224:227], v[36:51]
	ds_read_b64_tr_b16 v[224:225], v228 offset:28672
	ds_read_b64_tr_b16 v[226:227], v228 offset:30720
	v_pk_add_f32 v[150:151], v[150:151], v[192:193]
	v_pk_add_f32 v[150:151], v[150:151], v[194:195]
	v_cvt_pk_bf16_f32 v190, v192, v193
	v_cvt_pk_bf16_f32 v191, v194, v195
	s_waitcnt lgkmcnt(12)
	v_mfma_f32_32x32x16_bf16 v[52:67], v[88:91], v[232:235], v[52:67]
	ds_read_b64_tr_b16 v[232:233], v229 offset:28672
	ds_read_b64_tr_b16 v[234:235], v229 offset:30720
	v_exp_f32_e32 v196, v196
	v_exp_f32_e32 v197, v197
	s_waitcnt lgkmcnt(12)
	s_mov_b32 m0, s29
	v_mfma_f32_32x32x16_bf16 v[68:83], v[88:91], v[132:135], v[68:83]
	global_load_lds_dwordx4 v160, s[8:9]
	ds_read_b64_tr_b16 v[132:133], v230 offset:28672
	ds_read_b64_tr_b16 v[134:135], v230 offset:30720
	v_exp_f32_e32 v198, v198
	v_exp_f32_e32 v199, v199
	s_waitcnt lgkmcnt(12)
	v_mfma_f32_32x32x16_bf16 v[20:35], v[100:103], v[136:139], v[20:35]
	ds_read_b64_tr_b16 v[136:137], v231 offset:28672
	ds_read_b64_tr_b16 v[138:139], v231 offset:30720
	v_pk_add_f32 v[150:151], v[150:151], v[196:197]
	v_pk_add_f32 v[150:151], v[150:151], v[198:199]
	v_exp_f32_e32 v200, v200
	s_waitcnt lgkmcnt(12)
	v_mfma_f32_32x32x16_bf16 v[36:51], v[100:103], v[140:143], v[36:51]
	ds_read_b128 v[140:143], v19
	v_exp_f32_e32 v201, v201
	v_cvt_pk_bf16_f32 v192, v196, v197
	v_cvt_pk_bf16_f32 v193, v198, v199
	s_waitcnt lgkmcnt(11)
	v_mfma_f32_32x32x16_bf16 v[52:67], v[100:103], v[144:147], v[52:67]
	ds_read_b128 v[144:147], v19 offset:8192
	v_exp_f32_e32 v202, v202
	v_exp_f32_e32 v203, v203
	s_waitcnt lgkmcnt(10)
	v_mfma_f32_32x32x16_bf16 v[68:83], v[100:103], v[220:223], v[68:83]
	ds_read_b128 v[220:223], v180
	v_pk_add_f32 v[150:151], v[150:151], v[200:201]
	v_pk_add_f32 v[150:151], v[150:151], v[202:203]
	v_cvt_pk_bf16_f32 v194, v200, v201
	v_cvt_pk_bf16_f32 v195, v202, v203
	s_waitcnt lgkmcnt(9)
	v_mfma_f32_32x32x16_bf16 v[20:35], v[104:107], v[224:227], v[20:35]
	ds_read_b128 v[224:227], v180 offset:8192
	v_exp_f32_e32 v204, v204
	v_exp_f32_e32 v205, v205
	s_waitcnt lgkmcnt(8)
	v_mfma_f32_32x32x16_bf16 v[36:51], v[104:107], v[232:235], v[36:51]
	ds_read_b128 v[232:235], v181
	v_exp_f32_e32 v206, v206
	v_exp_f32_e32 v207, v207
	s_waitcnt lgkmcnt(7)
	v_mfma_f32_32x32x16_bf16 v[52:67], v[104:107], v[132:135], v[52:67]
	ds_read_b128 v[132:135], v181 offset:8192
	v_pk_add_f32 v[150:151], v[150:151], v[204:205]
	v_pk_add_f32 v[150:151], v[150:151], v[206:207]
	v_exp_f32_e32 v208, v208
	s_waitcnt lgkmcnt(6)
	s_add_u32 m0, s29, 0x2000
	v_mfma_f32_32x32x16_bf16 v[68:83], v[104:107], v[136:139], v[68:83]
	global_load_lds_dwordx4 v176, s[8:9]
	ds_read_b128 v[136:139], v182
	v_exp_f32_e32 v209, v209
	v_cvt_pk_bf16_f32 v204, v204, v205
	v_cvt_pk_bf16_f32 v205, v206, v207
	s_waitcnt lgkmcnt(6)
	v_mfma_f32_32x32x16_bf16 v[84:99], v[140:143], v[116:119], v[2:17]
	ds_read_b128 v[140:143], v182 offset:8192
	v_exp_f32_e32 v210, v210
	v_exp_f32_e32 v211, v211
	s_waitcnt lgkmcnt(6)
	v_mfma_f32_32x32x16_bf16 v[100:115], v[144:147], v[116:119], v[2:17]
	v_pk_add_f32 v[150:151], v[150:151], v[208:209]
	v_pk_add_f32 v[150:151], v[150:151], v[210:211]
	v_cvt_pk_bf16_f32 v206, v208, v209
	v_cvt_pk_bf16_f32 v207, v210, v211
	s_waitcnt lgkmcnt(5)
	v_mfma_f32_32x32x16_bf16 v[84:99], v[220:223], v[120:123], v[84:99]
	v_exp_f32_e32 v212, v212
	v_exp_f32_e32 v213, v213
	s_waitcnt lgkmcnt(4)
	v_mfma_f32_32x32x16_bf16 v[100:115], v[224:227], v[120:123], v[100:115]
	v_exp_f32_e32 v214, v214
	v_exp_f32_e32 v215, v215
	s_waitcnt lgkmcnt(3)
	v_mfma_f32_32x32x16_bf16 v[84:99], v[232:235], v[124:127], v[84:99]
	v_pk_add_f32 v[150:151], v[150:151], v[212:213]
	v_pk_add_f32 v[150:151], v[150:151], v[214:215]
	v_exp_f32_e32 v216, v216
	s_waitcnt lgkmcnt(2)
	v_mfma_f32_32x32x16_bf16 v[100:115], v[132:135], v[124:127], v[100:115]
	v_exp_f32_e32 v217, v217
	v_cvt_pk_bf16_f32 v208, v212, v213
	v_cvt_pk_bf16_f32 v209, v214, v215
	s_waitcnt lgkmcnt(1)
	v_mfma_f32_32x32x16_bf16 v[84:99], v[136:139], v[128:131], v[84:99]
	v_exp_f32_e32 v218, v218
	v_exp_f32_e32 v219, v219
	s_waitcnt lgkmcnt(0)
	v_mfma_f32_32x32x16_bf16 v[100:115], v[140:143], v[128:131], v[100:115]
	v_pk_add_f32 v[150:151], v[150:151], v[216:217]
	v_pk_add_f32 v[150:151], v[150:151], v[218:219]
	v_cvt_pk_bf16_f32 v210, v216, v217
	v_cvt_pk_bf16_f32 v211, v218, v219
	s_add_u32 s8, s8, 0x40000
	s_addc_u32 s9, s9, 0
	s_waitcnt vmcnt(2) lgkmcnt(0)
	s_barrier
	s_sub_u32 s10, s10, 1
	s_cbranch_scc1 .LatA_evs_x2

; #define LAS __attribute__((address_space(3)))
; __device__ __forceinline__ void attn_unit(LAS unsigned char* lds, const bf16_t* Z, bf16_t* A2, const float* tabg, int seq_base, int S, int h, int qb, float lam) {
;     ...
;             for (int ds = 0; ds < 4; ++ds) { kf[2 * ds] = *(const LAS bf16x8*)(Kt + (kfo ^ (unsigned)(ds << 5))); kf[2 * ds + 1] = *(const LAS bf16x8*)(Kt + 32 * 256 + (kfo ^ (unsigned)(ds << 5))); }
;             __builtin_amdgcn_sched_barrier(0);
;             p0 = __builtin_amdgcn_mfma_f32_32x32x16_bf16(kf[0], qf[0], cblk, 0, 0, 0);
;             p1 = __builtin_amdgcn_mfma_f32_32x32x16_bf16(kf[1], qf[0], cblk, 0, 0, 0);
; #pragma unroll
;             for (int ds = 1; ds < 4; ++ds) {
;                 p0 = __builtin_amdgcn_mfma_f32_32x32x16_bf16(kf[2 * ds], qf[ds], p0, 0, 0, 0);
;                 p1 = __builtin_amdgcn_mfma_f32_32x32x16_bf16(kf[2 * ds + 1], qf[ds], p1, 0, 0, 0);
;             }
;         }
;     ...
;         const unsigned vbase = (unsigned)(size_t)Vt + vfo;
;         s16x4 va[8], vb[8];
;         VREADS1(va, 0);
;         if (near) {
;             const LAS float* tp = tab + (kv0 + 4 * hi - (qlo + r32) + 224);
; #pragma unroll
;             for (int r = 0; r < 16; ++r) { p0[r] += tp[(r & 3) + 8 * (r >> 2)]; p1[r] += tp[32 + (r & 3) + 8 * (r >> 2)]; }
;         }
;         float mx = max2f(max16f(p0), max16f(p1));
;         const bool first = (t == 0);
;         if (first || __any(mx > THR)) {
;             { auto rr = __builtin_amdgcn_permlane32_swap(__float_as_uint(mx), __float_as_uint(mx), false, false); mx = max2f(__uint_as_float(rr[0]), __uint_as_float(rr[1])); }
;             const float delta = first ? mx : fmaxf(mx, 0.f);
;             const float alpha = first ? 1.0f : __builtin_amdgcn_exp2f(-delta);
;             mu += delta; ls2 *= alpha;
;             if (!first) {
;                 asm volatile("" ::: "memory");
;                 scr[r32] = alpha;
;                 asm volatile("s_waitcnt lgkmcnt(0)" ::: "memory");
; #pragma unroll
;                 for (int g = 0; g < 4; ++g) { const f32x4 a4 = *(const LAS f32x4*)(scr + 8 * g + 4 * hi);
; #pragma unroll
;                     for (int d = 0; d < 4; ++d) { O[d][4 * g + 0] *= a4[0]; O[d][4 * g + 1] *= a4[1]; O[d][4 * g + 2] *= a4[2]; O[d][4 * g + 3] *= a4[3]; } }
;                 asm volatile("s_waitcnt lgkmcnt(0)" ::: "memory");
;             }
; #pragma unroll
.LatA_rareret_x2:
	s_waitcnt lgkmcnt(12)
	v_mfma_f32_32x32x16_bf16 v[20:35], v[188:191], v[132:135], v[20:35]
	ds_read_b64_tr_b16 v[132:133], v231 offset:36864
	ds_read_b64_tr_b16 v[134:135], v231 offset:38912
	v_exp_f32_e32 v84, v84
	v_exp_f32_e32 v85, v85
	s_waitcnt lgkmcnt(12)
	v_mfma_f32_32x32x16_bf16 v[36:51], v[188:191], v[136:139], v[36:51]
	ds_read_b64_tr_b16 v[136:137], v228 offset:40960
	ds_read_b64_tr_b16 v[138:139], v228 offset:43008
	v_exp_f32_e32 v86, v86
	v_exp_f32_e32 v87, v87
	s_waitcnt lgkmcnt(12)
	v_mfma_f32_32x32x16_bf16 v[52:67], v[188:191], v[140:143], v[52:67]
	ds_read_b64_tr_b16 v[140:141], v229 offset:40960
	ds_read_b64_tr_b16 v[142:143], v229 offset:43008
	v_pk_add_f32 v[150:151], v[150:151], v[84:85]
	v_pk_add_f32 v[150:151], v[150:151], v[86:87]
	v_exp_f32_e32 v88, v88
	s_waitcnt lgkmcnt(12)
	v_mfma_f32_32x32x16_bf16 v[68:83], v[188:191], v[144:147], v[68:83]
	ds_read_b64_tr_b16 v[144:145], v230 offset:40960
	ds_read_b64_tr_b16 v[146:147], v230 offset:43008
	v_exp_f32_e32 v89, v89
	v_cvt_pk_bf16_f32 v84, v84, v85
	v_cvt_pk_bf16_f32 v85, v86, v87
	s_waitcnt lgkmcnt(12)
	v_mfma_f32_32x32x16_bf16 v[20:35], v[192:195], v[220:223], v[20:35]
	ds_read_b64_tr_b16 v[220:221], v231 offset:40960
	ds_read_b64_tr_b16 v[222:223], v231 offset:43008
	v_exp_f32_e32 v90, v90
	v_exp_f32_e32 v91, v91
	s_waitcnt lgkmcnt(12)
	v_mfma_f32_32x32x16_bf16 v[36:51], v[192:195], v[224:227], v[36:51]
	ds_read_b64_tr_b16 v[224:225], v228 offset:45056
	ds_read_b64_tr_b16 v[226:227], v228 offset:47104
	v_pk_add_f32 v[150:151], v[150:151], v[88:89]
	v_pk_add_f32 v[150:151], v[150:151], v[90:91]
	v_cvt_pk_bf16_f32 v86, v88, v89
	v_cvt_pk_bf16_f32 v87, v90, v91
	s_waitcnt lgkmcnt(12)
	v_mfma_f32_32x32x16_bf16 v[52:67], v[192:195], v[232:235], v[52:67]
	ds_read_b64_tr_b16 v[232:233], v229 offset:45056
	ds_read_b64_tr_b16 v[234:235], v229 offset:47104
	v_exp_f32_e32 v92, v92
	v_exp_f32_e32 v93, v93
	s_waitcnt lgkmcnt(12)
	s_add_u32 m0, s29, 0x4000
	v_mfma_f32_32x32x16_bf16 v[68:83], v[192:195], v[132:135], v[68:83]
	global_load_lds_dwordx4 v160, s[8:9]
	ds_read_b64_tr_b16 v[132:133], v230 offset:45056
	ds_read_b64_tr_b16 v[134:135], v230 offset:47104
	v_exp_f32_e32 v94, v94
	v_exp_f32_e32 v95, v95
	s_waitcnt lgkmcnt(12)
	v_mfma_f32_32x32x16_bf16 v[20:35], v[204:207], v[136:139], v[20:35]
	ds_read_b64_tr_b16 v[136:137], v231 offset:45056
	ds_read_b64_tr_b16 v[138:139], v231 offset:47104
	v_pk_add_f32 v[150:151], v[150:151], v[92:93]
	v_pk_add_f32 v[150:151], v[150:151], v[94:95]
	v_exp_f32_e32 v96, v96
	s_waitcnt lgkmcnt(12)
	v_mfma_f32_32x32x16_bf16 v[36:51], v[204:207], v[140:143], v[36:51]
	ds_read_b128 v[140:143], v19 offset:16384
	v_exp_f32_e32 v97, v97
	v_cvt_pk_bf16_f32 v88, v92, v93
	v_cvt_pk_bf16_f32 v89, v94, v95
	s_waitcnt lgkmcnt(11)
	v_mfma_f32_32x32x16_bf16 v[52:67], v[204:207], v[144:147], v[52:67]
	ds_read_b128 v[144:147], v19 offset:24576
	v_exp_f32_e32 v98, v98
	v_exp_f32_e32 v99, v99
	s_waitcnt lgkmcnt(10)
	v_mfma_f32_32x32x16_bf16 v[68:83], v[204:207], v[220:223], v[68:83]
	ds_read_b128 v[220:223], v180 offset:16384
	v_pk_add_f32 v[150:151], v[150:151], v[96:97]
	v_pk_add_f32 v[150:151], v[150:151], v[98:99]
	v_cvt_pk_bf16_f32 v90, v96, v97
	v_cvt_pk_bf16_f32 v91, v98, v99
	s_waitcnt lgkmcnt(9)
	v_mfma_f32_32x32x16_bf16 v[20:35], v[208:211], v[224:227], v[20:35]
	ds_read_b128 v[224:227], v180 offset:24576
	v_exp_f32_e32 v100, v100
	v_exp_f32_e32 v101, v101
	s_waitcnt lgkmcnt(8)
	v_mfma_f32_32x32x16_bf16 v[36:51], v[208:211], v[232:235], v[36:51]
	ds_read_b128 v[232:235], v181 offset:16384
	v_exp_f32_e32 v102, v102
	v_exp_f32_e32 v103, v103
	s_waitcnt lgkmcnt(7)
	v_mfma_f32_32x32x16_bf16 v[52:67], v[208:211], v[132:135], v[52:67]
	ds_read_b128 v[132:135], v181 offset:24576
	v_pk_add_f32 v[150:151], v[150:151], v[100:101]
	v_pk_add_f32 v[150:151], v[150:151], v[102:103]
	v_exp_f32_e32 v104, v104
	s_waitcnt lgkmcnt(6)
	s_add_u32 m0, s29, 0x6000
	v_mfma_f32_32x32x16_bf16 v[68:83], v[208:211], v[136:139], v[68:83]
	global_load_lds_dwordx4 v176, s[8:9]
	ds_read_b128 v[136:139], v182 offset:16384
	v_exp_f32_e32 v105, v105
	v_cvt_pk_bf16_f32 v100, v100, v101
	v_cvt_pk_bf16_f32 v101, v102, v103
	s_waitcnt lgkmcnt(6)
	v_mfma_f32_32x32x16_bf16 v[188:203], v[140:143], v[116:119], v[2:17]
	ds_read_b128 v[140:143], v182 offset:24576
	v_exp_f32_e32 v106, v106
	v_exp_f32_e32 v107, v107
	s_waitcnt lgkmcnt(6)
	v_mfma_f32_32x32x16_bf16 v[204:219], v[144:147], v[116:119], v[2:17]
	v_pk_add_f32 v[150:151], v[150:151], v[104:105]
	v_pk_add_f32 v[150:151], v[150:151], v[106:107]
	v_cvt_pk_bf16_f32 v102, v104, v105
	v_cvt_pk_bf16_f32 v103, v106, v107
	s_waitcnt lgkmcnt(5)
	v_mfma_f32_32x32x16_bf16 v[188:203], v[220:223], v[120:123], v[188:203]
	v_exp_f32_e32 v108, v108
	v_exp_f32_e32 v109, v109
	s_waitcnt lgkmcnt(4)
	v_mfma_f32_32x32x16_bf16 v[204:219], v[224:227], v[120:123], v[204:219]
	v_exp_f32_e32 v110, v110
	v_exp_f32_e32 v111, v111
	s_waitcnt lgkmcnt(3)
	v_mfma_f32_32x32x16_bf16 v[188:203], v[232:235], v[124:127], v[188:203]
	v_pk_add_f32 v[150:151], v[150:151], v[108:109]
	v_pk_add_f32 v[150:151], v[150:151], v[110:111]
	v_exp_f32_e32 v112, v112
	s_waitcnt lgkmcnt(2)
	v_mfma_f32_32x32x16_bf16 v[204:219], v[132:135], v[124:127], v[204:219]
	v_exp_f32_e32 v113, v113
	v_cvt_pk_bf16_f32 v104, v108, v109
	v_cvt_pk_bf16_f32 v105, v110, v111
	s_waitcnt lgkmcnt(1)
	v_mfma_f32_32x32x16_bf16 v[188:203], v[136:139], v[128:131], v[188:203]
	v_exp_f32_e32 v114, v114
	v_exp_f32_e32 v115, v115
	s_waitcnt lgkmcnt(0)
	v_mfma_f32_32x32x16_bf16 v[204:219], v[140:143], v[128:131], v[204:219]
	v_pk_add_f32 v[150:151], v[150:151], v[112:113]
	v_pk_add_f32 v[150:151], v[150:151], v[114:115]
	v_cvt_pk_bf16_f32 v106, v112, v113
	v_cvt_pk_bf16_f32 v107, v114, v115
	s_add_u32 s8, s8, 0x40000
	s_addc_u32 s9, s9, 0
	s_waitcnt vmcnt(2) lgkmcnt(0)
	s_barrier
	s_sub_u32 s10, s10, 1
	s_cbranch_scc1 .LatA_evs_x1

; #define LAS __attribute__((address_space(3)))
; __device__ __forceinline__ void attn_unit(LAS unsigned char* lds, const bf16_t* Z, bf16_t* A2, const float* tabg, int seq_base, int S, int h, int qb, float lam) {
;     ...
;             for (int ds = 0; ds < 4; ++ds) { kf[2 * ds] = *(const LAS bf16x8*)(Kt + (kfo ^ (unsigned)(ds << 5))); kf[2 * ds + 1] = *(const LAS bf16x8*)(Kt + 32 * 256 + (kfo ^ (unsigned)(ds << 5))); }
;             __builtin_amdgcn_sched_barrier(0);
;             p0 = __builtin_amdgcn_mfma_f32_32x32x16_bf16(kf[0], qf[0], cblk, 0, 0, 0);
;             p1 = __builtin_amdgcn_mfma_f32_32x32x16_bf16(kf[1], qf[0], cblk, 0, 0, 0);
; #pragma unroll
;             for (int ds = 1; ds < 4; ++ds) {
;                 p0 = __builtin_amdgcn_mfma_f32_32x32x16_bf16(kf[2 * ds], qf[ds], p0, 0, 0, 0);
;                 p1 = __builtin_amdgcn_mfma_f32_32x32x16_bf16(kf[2 * ds + 1], qf[ds], p1, 0, 0, 0);
;             }
;         }
;     ...
;         const unsigned vbase = (unsigned)(size_t)Vt + vfo;
;         s16x4 va[8], vb[8];
;         VREADS1(va, 0);
;         if (near) {
;             const LAS float* tp = tab + (kv0 + 4 * hi - (qlo + r32) + 224);
; #pragma unroll
;             for (int r = 0; r < 16; ++r) { p0[r] += tp[(r & 3) + 8 * (r >> 2)]; p1[r] += tp[32 + (r & 3) + 8 * (r >> 2)]; }
;         }
;         float mx = max2f(max16f(p0), max16f(p1));
;         const bool first = (t == 0);
;         if (first || __any(mx > THR)) {
;             { auto rr = __builtin_amdgcn_permlane32_swap(__float_as_uint(mx), __float_as_uint(mx), false, false); mx = max2f(__uint_as_float(rr[0]), __uint_as_float(rr[1])); }
;             const float delta = first ? mx : fmaxf(mx, 0.f);
;             const float alpha = first ? 1.0f : __builtin_amdgcn_exp2f(-delta);
;             mu += delta; ls2 *= alpha;
;             if (!first) {
;                 asm volatile("" ::: "memory");
;                 scr[r32] = alpha;
;                 asm volatile("s_waitcnt lgkmcnt(0)" ::: "memory");
; #pragma unroll
;                 for (int g = 0; g < 4; ++g) { const f32x4 a4 = *(const LAS f32x4*)(scr + 8 * g + 4 * hi);
; #pragma unroll
;                     for (int d = 0; d < 4; ++d) { O[d][4 * g + 0] *= a4[0]; O[d][4 * g + 1] *= a4[1]; O[d][4 * g + 2] *= a4[2]; O[d][4 * g + 3] *= a4[3]; } }
;                 asm volatile("s_waitcnt lgkmcnt(0)" ::: "memory");
;             }
; #pragma unroll
.LatA_rareret_x1:
	s_waitcnt lgkmcnt(12)
	v_mfma_f32_32x32x16_bf16 v[20:35], v[84:87], v[132:135], v[20:35]
	ds_read_b64_tr_b16 v[132:133], v231 offset:4096
	ds_read_b64_tr_b16 v[134:135], v231 offset:6144
	v_exp_f32_e32 v188, v188
	v_exp_f32_e32 v189, v189
	v_exp_f32_e32 v190, v190
	s_waitcnt lgkmcnt(12)
	v_mfma_f32_32x32x16_bf16 v[36:51], v[84:87], v[136:139], v[36:51]
	ds_read_b64_tr_b16 v[136:137], v228 offset:8192
	ds_read_b64_tr_b16 v[138:139], v228 offset:10240
	v_exp_f32_e32 v191, v191
	v_pk_add_f32 v[150:151], v[150:151], v[188:189]
	v_pk_add_f32 v[150:151], v[150:151], v[190:191]
	v_exp_f32_e32 v192, v192
	s_waitcnt lgkmcnt(12)
	v_mfma_f32_32x32x16_bf16 v[52:67], v[84:87], v[140:143], v[52:67]
	ds_read_b64_tr_b16 v[140:141], v229 offset:8192
	ds_read_b64_tr_b16 v[142:143], v229 offset:10240
	v_exp_f32_e32 v193, v193
	v_cvt_pk_bf16_f32 v188, v188, v189
	v_cvt_pk_bf16_f32 v189, v190, v191
	v_exp_f32_e32 v194, v194
	s_waitcnt lgkmcnt(12)
	v_mfma_f32_32x32x16_bf16 v[68:83], v[84:87], v[144:147], v[68:83]
	ds_read_b64_tr_b16 v[144:145], v230 offset:8192
	ds_read_b64_tr_b16 v[146:147], v230 offset:10240
	v_exp_f32_e32 v195, v195
	v_pk_add_f32 v[150:151], v[150:151], v[192:193]
	v_pk_add_f32 v[150:151], v[150:151], v[194:195]
	v_cvt_pk_bf16_f32 v190, v192, v193
	v_cvt_pk_bf16_f32 v191, v194, v195
	s_waitcnt lgkmcnt(12)
	v_mfma_f32_32x32x16_bf16 v[20:35], v[88:91], v[220:223], v[20:35]
	ds_read_b64_tr_b16 v[220:221], v231 offset:8192
	ds_read_b64_tr_b16 v[222:223], v231 offset:10240
	v_exp_f32_e32 v196, v196
	v_exp_f32_e32 v197, v197
	v_exp_f32_e32 v198, v198
	s_waitcnt lgkmcnt(12)
	v_mfma_f32_32x32x16_bf16 v[36:51], v[88:91], v[224:227], v[36:51]
	ds_read_b64_tr_b16 v[224:225], v228 offset:12288
	ds_read_b64_tr_b16 v[226:227], v228 offset:14336
	v_exp_f32_e32 v199, v199
	v_pk_add_f32 v[150:151], v[150:151], v[196:197]
	v_pk_add_f32 v[150:151], v[150:151], v[198:199]
	v_exp_f32_e32 v200, v200
	s_waitcnt lgkmcnt(12)
	v_mfma_f32_32x32x16_bf16 v[52:67], v[88:91], v[232:235], v[52:67]
	ds_read_b64_tr_b16 v[232:233], v229 offset:12288
	ds_read_b64_tr_b16 v[234:235], v229 offset:14336
	v_exp_f32_e32 v201, v201
	v_cvt_pk_bf16_f32 v192, v196, v197
	v_cvt_pk_bf16_f32 v193, v198, v199
	v_exp_f32_e32 v202, v202
	s_waitcnt lgkmcnt(12)
	v_mfma_f32_32x32x16_bf16 v[68:83], v[88:91], v[132:135], v[68:83]
	ds_read_b64_tr_b16 v[132:133], v230 offset:12288
	ds_read_b64_tr_b16 v[134:135], v230 offset:14336
	v_exp_f32_e32 v203, v203
	v_pk_add_f32 v[150:151], v[150:151], v[200:201]
	v_pk_add_f32 v[150:151], v[150:151], v[202:203]
	v_cvt_pk_bf16_f32 v194, v200, v201
	v_cvt_pk_bf16_f32 v195, v202, v203
	s_waitcnt lgkmcnt(12)
	v_mfma_f32_32x32x16_bf16 v[20:35], v[100:103], v[136:139], v[20:35]
	ds_read_b64_tr_b16 v[136:137], v231 offset:12288
	ds_read_b64_tr_b16 v[138:139], v231 offset:14336
	v_exp_f32_e32 v204, v204
	v_exp_f32_e32 v205, v205
	v_exp_f32_e32 v206, v206
	s_waitcnt lgkmcnt(12)
	v_mfma_f32_32x32x16_bf16 v[36:51], v[100:103], v[140:143], v[36:51]
	v_exp_f32_e32 v207, v207
	v_pk_add_f32 v[150:151], v[150:151], v[204:205]
	v_pk_add_f32 v[150:151], v[150:151], v[206:207]
	v_exp_f32_e32 v208, v208
	s_waitcnt lgkmcnt(10)
	v_mfma_f32_32x32x16_bf16 v[52:67], v[100:103], v[144:147], v[52:67]
	v_exp_f32_e32 v209, v209
	v_cvt_pk_bf16_f32 v204, v204, v205
	v_cvt_pk_bf16_f32 v205, v206, v207
	v_exp_f32_e32 v210, v210
	s_waitcnt lgkmcnt(8)
	v_mfma_f32_32x32x16_bf16 v[68:83], v[100:103], v[220:223], v[68:83]
	v_exp_f32_e32 v211, v211
	v_pk_add_f32 v[150:151], v[150:151], v[208:209]
	v_pk_add_f32 v[150:151], v[150:151], v[210:211]
	v_cvt_pk_bf16_f32 v206, v208, v209
	v_cvt_pk_bf16_f32 v207, v210, v211
	s_waitcnt lgkmcnt(6)
	v_mfma_f32_32x32x16_bf16 v[20:35], v[104:107], v[224:227], v[20:35]
	v_exp_f32_e32 v212, v212
	v_exp_f32_e32 v213, v213
	v_exp_f32_e32 v214, v214
	s_waitcnt lgkmcnt(4)
	v_mfma_f32_32x32x16_bf16 v[36:51], v[104:107], v[232:235], v[36:51]
	v_exp_f32_e32 v215, v215
	v_pk_add_f32 v[150:151], v[150:151], v[212:213]
	v_pk_add_f32 v[150:151], v[150:151], v[214:215]
	v_exp_f32_e32 v216, v216
	s_waitcnt lgkmcnt(2)
	v_mfma_f32_32x32x16_bf16 v[52:67], v[104:107], v[132:135], v[52:67]
	v_exp_f32_e32 v217, v217
	v_cvt_pk_bf16_f32 v208, v212, v213
	v_cvt_pk_bf16_f32 v209, v214, v215
	v_exp_f32_e32 v218, v218
	s_waitcnt lgkmcnt(0)
	v_mfma_f32_32x32x16_bf16 v[68:83], v[104:107], v[136:139], v[68:83]
	v_exp_f32_e32 v219, v219
	v_pk_add_f32 v[150:151], v[150:151], v[216:217]
	v_pk_add_f32 v[150:151], v[150:151], v[218:219]
	v_cvt_pk_bf16_f32 v210, v216, v217
	v_cvt_pk_bf16_f32 v211, v218, v219
	s_add_u32 s8, s8, 0x40000
	s_addc_u32 s9, s9, 0
	s_waitcnt vmcnt(0) lgkmcnt(0)
	s_barrier
; #define VREADS1(arr, d_) do { const unsigned ad_ = vbase ^ (unsigned)((d_) << 6); __builtin_amdgcn_sched_barrier(0); \
;         _Pragma("unroll") for (int ks_ = 0; ks_ < 4; ++ks_) { VTR(arr[ks_ * 2], ad_, ks_ * 4096); VTR(arr[ks_ * 2 + 1], ad_, ks_ * 4096 + 2048); } __builtin_amdgcn_sched_barrier(0); } while (0)
; #define PV1(arr, d_) do { _Pragma("unroll") for (int ks_ = 0; ks_ < 4; ++ks_) { const s16x4 lo_ = arr[ks_ * 2], hh_ = arr[ks_ * 2 + 1]; \
;         const bf16x8 bv_ = (bf16x8){lo_[0], lo_[1], lo_[2], lo_[3], hh_[0], hh_[1], hh_[2], hh_[3]}; \
;         O[d_] = __builtin_amdgcn_mfma_f32_32x32x16_bf16(pa[ks_], bv_, O[d_], 0, 0, 0); } __builtin_amdgcn_sched_barrier(0); } while (0)
; #define LGKM0() do { __builtin_amdgcn_sched_barrier(0); asm volatile("s_waitcnt lgkmcnt(0)" ::: "memory"); __builtin_amdgcn_sched_barrier(0); } while (0)
; __device__ __forceinline__ void attn_unit(LAS unsigned char* lds, const bf16_t* Z, bf16_t* A2, const float* tabg, int seq_base, int S, int h, int qb, float lam) {
;     ...
;         LGKM0(); VREADS1(vb, 1); PV1(va, 0); LGKM0(); VREADS1(va, 2); PV1(vb, 1); LGKM0(); VREADS1(vb, 3); PV1(va, 2); LGKM0(); PV1(vb, 3);
;     ...
;         if (t + 2 < NT) asm volatile("s_waitcnt vmcnt(4) lgkmcnt(0)" ::: "memory"); else asm volatile("s_waitcnt vmcnt(0) lgkmcnt(0)" ::: "memory");
;         __builtin_amdgcn_s_barrier(); asm volatile("" ::: "memory");
	ds_read_b64_tr_b16 v[132:133], v228 offset:16384
	ds_read_b64_tr_b16 v[134:135], v228 offset:18432
	ds_read_b64_tr_b16 v[136:137], v229 offset:16384
	ds_read_b64_tr_b16 v[138:139], v229 offset:18432
	ds_read_b64_tr_b16 v[140:141], v230 offset:16384
	ds_read_b64_tr_b16 v[142:143], v230 offset:18432
	ds_read_b64_tr_b16 v[144:145], v231 offset:16384
	ds_read_b64_tr_b16 v[146:147], v231 offset:18432
	ds_read_b64_tr_b16 v[220:221], v228 offset:20480
	ds_read_b64_tr_b16 v[222:223], v228 offset:22528
	ds_read_b64_tr_b16 v[224:225], v229 offset:20480
	ds_read_b64_tr_b16 v[226:227], v229 offset:22528
	ds_read_b64_tr_b16 v[232:233], v230 offset:20480
	ds_read_b64_tr_b16 v[234:235], v230 offset:22528
	s_waitcnt lgkmcnt(10)
	v_mfma_f32_32x32x16_bf16 v[20:35], v[188:191], v[132:135], v[20:35]
	ds_read_b64_tr_b16 v[132:133], v231 offset:20480
	ds_read_b64_tr_b16 v[134:135], v231 offset:22528
	v_mfma_f32_32x32x16_bf16 v[36:51], v[188:191], v[136:139], v[36:51]
	ds_read_b64_tr_b16 v[136:137], v228 offset:24576
	ds_read_b64_tr_b16 v[138:139], v228 offset:26624
	s_waitcnt lgkmcnt(10)
	v_mfma_f32_32x32x16_bf16 v[52:67], v[188:191], v[140:143], v[52:67]
	ds_read_b64_tr_b16 v[140:141], v229 offset:24576
	ds_read_b64_tr_b16 v[142:143], v229 offset:26624
	v_mfma_f32_32x32x16_bf16 v[68:83], v[188:191], v[144:147], v[68:83]
	ds_read_b64_tr_b16 v[144:145], v230 offset:24576
	ds_read_b64_tr_b16 v[146:147], v230 offset:26624
	s_waitcnt lgkmcnt(10)
	v_mfma_f32_32x32x16_bf16 v[20:35], v[192:195], v[220:223], v[20:35]
	ds_read_b64_tr_b16 v[220:221], v231 offset:24576
	ds_read_b64_tr_b16 v[222:223], v231 offset:26624
	v_mfma_f32_32x32x16_bf16 v[36:51], v[192:195], v[224:227], v[36:51]
	ds_read_b64_tr_b16 v[224:225], v228 offset:28672
	ds_read_b64_tr_b16 v[226:227], v228 offset:30720
	s_waitcnt lgkmcnt(10)
	v_mfma_f32_32x32x16_bf16 v[52:67], v[192:195], v[232:235], v[52:67]
	ds_read_b64_tr_b16 v[232:233], v229 offset:28672
	ds_read_b64_tr_b16 v[234:235], v229 offset:30720
	v_mfma_f32_32x32x16_bf16 v[68:83], v[192:195], v[132:135], v[68:83]
	ds_read_b64_tr_b16 v[132:133], v230 offset:28672
	ds_read_b64_tr_b16 v[134:135], v230 offset:30720
	s_waitcnt lgkmcnt(10)
	v_mfma_f32_32x32x16_bf16 v[20:35], v[204:207], v[136:139], v[20:35]
	ds_read_b64_tr_b16 v[136:137], v231 offset:28672
	ds_read_b64_tr_b16 v[138:139], v231 offset:30720
	v_mfma_f32_32x32x16_bf16 v[36:51], v[204:207], v[140:143], v[36:51]
	s_waitcnt lgkmcnt(8)
	v_mfma_f32_32x32x16_bf16 v[52:67], v[204:207], v[144:147], v[52:67]
	v_mfma_f32_32x32x16_bf16 v[68:83], v[204:207], v[220:223], v[68:83]
	s_waitcnt lgkmcnt(4)
	v_mfma_f32_32x32x16_bf16 v[20:35], v[208:211], v[224:227], v[20:35]
	v_mfma_f32_32x32x16_bf16 v[36:51], v[208:211], v[232:235], v[36:51]
	s_waitcnt lgkmcnt(0)
	v_mfma_f32_32x32x16_bf16 v[52:67], v[208:211], v[132:135], v[52:67]
	v_mfma_f32_32x32x16_bf16 v[68:83], v[208:211], v[136:139], v[68:83]
	s_waitcnt lgkmcnt(0)
	s_barrier
	s_mov_b32 m0, s32
	s_nop 15
	s_branch .LatA_done

; #define LAS __attribute__((address_space(3)))
; #define VREADS1(arr, d_) do { const unsigned ad_ = vbase ^ (unsigned)((d_) << 6); __builtin_amdgcn_sched_barrier(0); \
;         _Pragma("unroll") for (int ks_ = 0; ks_ < 4; ++ks_) { VTR(arr[ks_ * 2], ad_, ks_ * 4096); VTR(arr[ks_ * 2 + 1], ad_, ks_ * 4096 + 2048); } __builtin_amdgcn_sched_barrier(0); } while (0)
; #define PV1(arr, d_) do { _Pragma("unroll") for (int ks_ = 0; ks_ < 4; ++ks_) { const s16x4 lo_ = arr[ks_ * 2], hh_ = arr[ks_ * 2 + 1]; \
;         const bf16x8 bv_ = (bf16x8){lo_[0], lo_[1], lo_[2], lo_[3], hh_[0], hh_[1], hh_[2], hh_[3]}; \
;         O[d_] = __builtin_amdgcn_mfma_f32_32x32x16_bf16(pa[ks_], bv_, O[d_], 0, 0, 0); } __builtin_amdgcn_sched_barrier(0); } while (0)
; __device__ __forceinline__ void attn_unit(LAS unsigned char* lds, const bf16_t* Z, bf16_t* A2, const float* tabg, int seq_base, int S, int h, int qb, float lam) {
;     ...
;             for (int ds = 0; ds < 4; ++ds) { kf[2 * ds] = *(const LAS bf16x8*)(Kt + (kfo ^ (unsigned)(ds << 5))); kf[2 * ds + 1] = *(const LAS bf16x8*)(Kt + 32 * 256 + (kfo ^ (unsigned)(ds << 5))); }
;             __builtin_amdgcn_sched_barrier(0);
;             p0 = __builtin_amdgcn_mfma_f32_32x32x16_bf16(kf[0], qf[0], cblk, 0, 0, 0);
;             p1 = __builtin_amdgcn_mfma_f32_32x32x16_bf16(kf[1], qf[0], cblk, 0, 0, 0);
; #pragma unroll
;             for (int ds = 1; ds < 4; ++ds) {
;                 p0 = __builtin_amdgcn_mfma_f32_32x32x16_bf16(kf[2 * ds], qf[ds], p0, 0, 0, 0);
;                 p1 = __builtin_amdgcn_mfma_f32_32x32x16_bf16(kf[2 * ds + 1], qf[ds], p1, 0, 0, 0);
;             }
;     ...
; #pragma unroll
;         for (int r = 0; r < 16; ++r) { p0[r] = __builtin_amdgcn_exp2f(p0[r]); p1[r] = __builtin_amdgcn_exp2f(p1[r]); }
; #pragma unroll
;         for (int r = 0; r < 16; r += 2) { ls2 += (f32x2){p0[r], p0[r + 1]}; ls2 += (f32x2){p1[r], p1[r + 1]}; }
;         bf16x8 pa[4]; pa[0] = pack8(p0, 0); pa[1] = pack8(p0, 8); pa[2] = pack8(p1, 0); pa[3] = pack8(p1, 8);
;         LGKM0(); VREADS1(vb, 1); PV1(va, 0); LGKM0(); VREADS1(va, 2); PV1(vb, 1); LGKM0(); VREADS1(vb, 3); PV1(va, 2); LGKM0(); PV1(vb, 3);
;     ...
;         if (t + 2 < NT) asm volatile("s_waitcnt vmcnt(4) lgkmcnt(0)" ::: "memory"); else asm volatile("s_waitcnt vmcnt(0) lgkmcnt(0)" ::: "memory");
;         __builtin_amdgcn_s_barrier(); asm volatile("" ::: "memory");
.LatB_rareret_h0:
	s_waitcnt lgkmcnt(6)
	v_mfma_f32_32x32x16_bf16 v[188:203], v[132:135], v[116:119], v[2:17]
	ds_read_b128 v[132:135], v182 offset:24576
	v_exp_f32_e32 v84, v84
	v_exp_f32_e32 v85, v85
	v_exp_f32_e32 v86, v86
	v_exp_f32_e32 v87, v87
	v_pk_add_f32 v[150:151], v[150:151], v[84:85]
	v_pk_add_f32 v[150:151], v[150:151], v[86:87]
	v_exp_f32_e32 v88, v88
	s_waitcnt lgkmcnt(6)
	s_mov_b32 m0, s25
	v_mfma_f32_32x32x16_bf16 v[204:219], v[136:139], v[116:119], v[2:17]
	global_load_lds_dwordx4 v236, s[8:9]
	v_exp_f32_e32 v89, v89
	v_cvt_pk_bf16_f32 v84, v84, v85
	v_cvt_pk_bf16_f32 v85, v86, v87
	v_exp_f32_e32 v90, v90
	v_exp_f32_e32 v91, v91
	v_pk_add_f32 v[150:151], v[150:151], v[88:89]
	v_pk_add_f32 v[150:151], v[150:151], v[90:91]
	v_cvt_pk_bf16_f32 v86, v88, v89
	v_cvt_pk_bf16_f32 v87, v90, v91
	s_waitcnt lgkmcnt(5)
	v_mfma_f32_32x32x16_bf16 v[188:203], v[140:143], v[120:123], v[188:203]
	v_exp_f32_e32 v92, v92
	v_exp_f32_e32 v93, v93
	v_exp_f32_e32 v94, v94
	v_exp_f32_e32 v95, v95
	v_pk_add_f32 v[150:151], v[150:151], v[92:93]
	v_pk_add_f32 v[150:151], v[150:151], v[94:95]
	v_exp_f32_e32 v96, v96
	s_waitcnt lgkmcnt(4)
	s_add_u32 m0, s25, 0x2000
	v_mfma_f32_32x32x16_bf16 v[204:219], v[144:147], v[120:123], v[204:219]
	global_load_lds_dwordx4 v237, s[8:9]
	v_exp_f32_e32 v97, v97
	v_cvt_pk_bf16_f32 v88, v92, v93
	v_cvt_pk_bf16_f32 v89, v94, v95
	v_exp_f32_e32 v98, v98
	v_exp_f32_e32 v99, v99
	v_pk_add_f32 v[150:151], v[150:151], v[96:97]
	v_pk_add_f32 v[150:151], v[150:151], v[98:99]
	v_cvt_pk_bf16_f32 v90, v96, v97
	v_cvt_pk_bf16_f32 v91, v98, v99
	s_waitcnt lgkmcnt(3)
	v_mfma_f32_32x32x16_bf16 v[188:203], v[220:223], v[124:127], v[188:203]
	v_exp_f32_e32 v100, v100
	v_exp_f32_e32 v101, v101
	v_exp_f32_e32 v102, v102
	v_exp_f32_e32 v103, v103
	v_pk_add_f32 v[150:151], v[150:151], v[100:101]
	v_pk_add_f32 v[150:151], v[150:151], v[102:103]
	v_exp_f32_e32 v104, v104
	s_waitcnt lgkmcnt(2)
	v_mfma_f32_32x32x16_bf16 v[204:219], v[224:227], v[124:127], v[204:219]
	v_exp_f32_e32 v105, v105
	v_cvt_pk_bf16_f32 v100, v100, v101
	v_cvt_pk_bf16_f32 v101, v102, v103
	v_exp_f32_e32 v106, v106
	v_exp_f32_e32 v107, v107
	v_pk_add_f32 v[150:151], v[150:151], v[104:105]
	v_pk_add_f32 v[150:151], v[150:151], v[106:107]
	v_cvt_pk_bf16_f32 v102, v104, v105
	v_cvt_pk_bf16_f32 v103, v106, v107
	s_waitcnt lgkmcnt(1)
	v_mfma_f32_32x32x16_bf16 v[188:203], v[232:235], v[128:131], v[188:203]
	v_exp_f32_e32 v108, v108
	v_exp_f32_e32 v109, v109
	v_exp_f32_e32 v110, v110
	v_exp_f32_e32 v111, v111
	v_pk_add_f32 v[150:151], v[150:151], v[108:109]
	v_pk_add_f32 v[150:151], v[150:151], v[110:111]
	v_exp_f32_e32 v112, v112
	s_waitcnt lgkmcnt(0)
	v_mfma_f32_32x32x16_bf16 v[204:219], v[132:135], v[128:131], v[204:219]
	v_exp_f32_e32 v113, v113
	v_cvt_pk_bf16_f32 v104, v108, v109
	v_cvt_pk_bf16_f32 v105, v110, v111
	v_exp_f32_e32 v114, v114
	v_exp_f32_e32 v115, v115
	v_pk_add_f32 v[150:151], v[150:151], v[112:113]
	v_pk_add_f32 v[150:151], v[150:151], v[114:115]
	v_cvt_pk_bf16_f32 v106, v112, v113
	v_cvt_pk_bf16_f32 v107, v114, v115
	s_add_u32 s8, s8, 0x40000
	s_addc_u32 s9, s9, 0
	s_waitcnt vmcnt(2) lgkmcnt(0)
	s_barrier
	s_sub_u32 s10, s10, 1
	s_cbranch_scc1 .LatB_evs_h1

; #define LAS __attribute__((address_space(3)))
; #define VREADS1(arr, d_) do { const unsigned ad_ = vbase ^ (unsigned)((d_) << 6); __builtin_amdgcn_sched_barrier(0); \
;         _Pragma("unroll") for (int ks_ = 0; ks_ < 4; ++ks_) { VTR(arr[ks_ * 2], ad_, ks_ * 4096); VTR(arr[ks_ * 2 + 1], ad_, ks_ * 4096 + 2048); } __builtin_amdgcn_sched_barrier(0); } while (0)
; #define PV1(arr, d_) do { _Pragma("unroll") for (int ks_ = 0; ks_ < 4; ++ks_) { const s16x4 lo_ = arr[ks_ * 2], hh_ = arr[ks_ * 2 + 1]; \
;         const bf16x8 bv_ = (bf16x8){lo_[0], lo_[1], lo_[2], lo_[3], hh_[0], hh_[1], hh_[2], hh_[3]}; \
;         O[d_] = __builtin_amdgcn_mfma_f32_32x32x16_bf16(pa[ks_], bv_, O[d_], 0, 0, 0); } __builtin_amdgcn_sched_barrier(0); } while (0)
; __device__ __forceinline__ void attn_unit(LAS unsigned char* lds, const bf16_t* Z, bf16_t* A2, const float* tabg, int seq_base, int S, int h, int qb, float lam) {
;     ...
;             for (int ds = 0; ds < 4; ++ds) { kf[2 * ds] = *(const LAS bf16x8*)(Kt + (kfo ^ (unsigned)(ds << 5))); kf[2 * ds + 1] = *(const LAS bf16x8*)(Kt + 32 * 256 + (kfo ^ (unsigned)(ds << 5))); }
;             __builtin_amdgcn_sched_barrier(0);
;             p0 = __builtin_amdgcn_mfma_f32_32x32x16_bf16(kf[0], qf[0], cblk, 0, 0, 0);
;             p1 = __builtin_amdgcn_mfma_f32_32x32x16_bf16(kf[1], qf[0], cblk, 0, 0, 0);
; #pragma unroll
;             for (int ds = 1; ds < 4; ++ds) {
;                 p0 = __builtin_amdgcn_mfma_f32_32x32x16_bf16(kf[2 * ds], qf[ds], p0, 0, 0, 0);
;                 p1 = __builtin_amdgcn_mfma_f32_32x32x16_bf16(kf[2 * ds + 1], qf[ds], p1, 0, 0, 0);
;             }
;     ...
; #pragma unroll
;         for (int r = 0; r < 16; ++r) { p0[r] = __builtin_amdgcn_exp2f(p0[r]); p1[r] = __builtin_amdgcn_exp2f(p1[r]); }
; #pragma unroll
;         for (int r = 0; r < 16; r += 2) { ls2 += (f32x2){p0[r], p0[r + 1]}; ls2 += (f32x2){p1[r], p1[r + 1]}; }
;         bf16x8 pa[4]; pa[0] = pack8(p0, 0); pa[1] = pack8(p0, 8); pa[2] = pack8(p1, 0); pa[3] = pack8(p1, 8);
;         LGKM0(); VREADS1(vb, 1); PV1(va, 0); LGKM0(); VREADS1(va, 2); PV1(vb, 1); LGKM0(); VREADS1(vb, 3); PV1(va, 2); LGKM0(); PV1(vb, 3);
;     ...
;         if (t + 2 < NT) asm volatile("s_waitcnt vmcnt(4) lgkmcnt(0)" ::: "memory"); else asm volatile("s_waitcnt vmcnt(0) lgkmcnt(0)" ::: "memory");
;         __builtin_amdgcn_s_barrier(); asm volatile("" ::: "memory");
.LatB_rareret_h1:
	s_waitcnt lgkmcnt(12)
	v_mfma_f32_32x32x16_bf16 v[20:35], v[84:87], v[132:135], v[20:35]
	ds_read_b64_tr_b16 v[132:133], v231 offset:4096
	ds_read_b64_tr_b16 v[134:135], v231 offset:6144
	v_exp_f32_e32 v188, v188
	v_exp_f32_e32 v189, v189
	s_waitcnt lgkmcnt(12)
	v_mfma_f32_32x32x16_bf16 v[36:51], v[84:87], v[136:139], v[36:51]
	ds_read_b64_tr_b16 v[136:137], v228 offset:8192
	ds_read_b64_tr_b16 v[138:139], v228 offset:10240
	v_exp_f32_e32 v190, v190
	v_exp_f32_e32 v191, v191
	s_waitcnt lgkmcnt(12)
	v_mfma_f32_32x32x16_bf16 v[52:67], v[84:87], v[140:143], v[52:67]
	ds_read_b64_tr_b16 v[140:141], v229 offset:8192
	ds_read_b64_tr_b16 v[142:143], v229 offset:10240
	v_pk_add_f32 v[150:151], v[150:151], v[188:189]
	v_pk_add_f32 v[150:151], v[150:151], v[190:191]
	v_exp_f32_e32 v192, v192
	s_waitcnt lgkmcnt(12)
	s_add_u32 m0, s25, 0x4000
	v_mfma_f32_32x32x16_bf16 v[68:83], v[84:87], v[144:147], v[68:83]
	global_load_lds_dwordx4 v236, s[8:9]
	ds_read_b64_tr_b16 v[144:145], v230 offset:8192
	ds_read_b64_tr_b16 v[146:147], v230 offset:10240
	v_exp_f32_e32 v193, v193
	v_cvt_pk_bf16_f32 v188, v188, v189
	v_cvt_pk_bf16_f32 v189, v190, v191
	s_waitcnt lgkmcnt(12)
	v_mfma_f32_32x32x16_bf16 v[20:35], v[88:91], v[220:223], v[20:35]
	ds_read_b64_tr_b16 v[220:221], v231 offset:8192
	ds_read_b64_tr_b16 v[222:223], v231 offset:10240
	v_exp_f32_e32 v194, v194
	v_exp_f32_e32 v195, v195
	s_waitcnt lgkmcnt(12)
	v_mfma_f32_32x32x16_bf16 v[36:51], v[88:91], v[224:227], v[36:51]
	ds_read_b64_tr_b16 v[224:225], v228 offset:12288
	ds_read_b64_tr_b16 v[226:227], v228 offset:14336
	v_pk_add_f32 v[150:151], v[150:151], v[192:193]
	v_pk_add_f32 v[150:151], v[150:151], v[194:195]
	v_cvt_pk_bf16_f32 v190, v192, v193
	v_cvt_pk_bf16_f32 v191, v194, v195
	s_waitcnt lgkmcnt(12)
	v_mfma_f32_32x32x16_bf16 v[52:67], v[88:91], v[232:235], v[52:67]
	ds_read_b64_tr_b16 v[232:233], v229 offset:12288
	ds_read_b64_tr_b16 v[234:235], v229 offset:14336
	v_exp_f32_e32 v196, v196
	v_exp_f32_e32 v197, v197
	s_waitcnt lgkmcnt(12)
	s_add_u32 m0, s27, 0x8000
	v_mfma_f32_32x32x16_bf16 v[68:83], v[88:91], v[132:135], v[68:83]
	global_load_lds_dwordx4 v149, s[8:9]
	ds_read_b64_tr_b16 v[132:133], v230 offset:12288
	ds_read_b64_tr_b16 v[134:135], v230 offset:14336
	v_exp_f32_e32 v198, v198
	v_exp_f32_e32 v199, v199
	s_waitcnt lgkmcnt(12)
	v_mfma_f32_32x32x16_bf16 v[20:35], v[100:103], v[136:139], v[20:35]
	ds_read_b64_tr_b16 v[136:137], v231 offset:12288
	ds_read_b64_tr_b16 v[138:139], v231 offset:14336
	v_pk_add_f32 v[150:151], v[150:151], v[196:197]
	v_pk_add_f32 v[150:151], v[150:151], v[198:199]
	v_exp_f32_e32 v200, v200
	s_waitcnt lgkmcnt(12)
	v_mfma_f32_32x32x16_bf16 v[36:51], v[100:103], v[140:143], v[36:51]
	ds_read_b128 v[140:143], v19 offset:32768
	v_exp_f32_e32 v201, v201
	v_cvt_pk_bf16_f32 v192, v196, v197
	v_cvt_pk_bf16_f32 v193, v198, v199
	s_waitcnt lgkmcnt(11)
	v_mfma_f32_32x32x16_bf16 v[52:67], v[100:103], v[144:147], v[52:67]
	ds_read_b128 v[144:147], v19 offset:40960
	v_exp_f32_e32 v202, v202
	v_exp_f32_e32 v203, v203
	s_waitcnt lgkmcnt(10)
	s_add_u32 m0, s25, 0x6000
	v_mfma_f32_32x32x16_bf16 v[68:83], v[100:103], v[220:223], v[68:83]
	global_load_lds_dwordx4 v237, s[8:9]
	ds_read_b128 v[220:223], v180 offset:32768
	v_pk_add_f32 v[150:151], v[150:151], v[200:201]
	v_pk_add_f32 v[150:151], v[150:151], v[202:203]
	v_cvt_pk_bf16_f32 v194, v200, v201
	v_cvt_pk_bf16_f32 v195, v202, v203
	s_waitcnt lgkmcnt(9)
	v_mfma_f32_32x32x16_bf16 v[20:35], v[104:107], v[224:227], v[20:35]
	ds_read_b128 v[224:227], v180 offset:40960
	v_exp_f32_e32 v204, v204
	v_exp_f32_e32 v205, v205
	s_waitcnt lgkmcnt(8)
	v_mfma_f32_32x32x16_bf16 v[36:51], v[104:107], v[232:235], v[36:51]
	ds_read_b128 v[232:235], v181 offset:32768
	v_exp_f32_e32 v206, v206
	v_exp_f32_e32 v207, v207
	s_waitcnt lgkmcnt(7)
	v_mfma_f32_32x32x16_bf16 v[52:67], v[104:107], v[132:135], v[52:67]
	ds_read_b128 v[132:135], v181 offset:40960
	v_pk_add_f32 v[150:151], v[150:151], v[204:205]
	v_pk_add_f32 v[150:151], v[150:151], v[206:207]
	v_exp_f32_e32 v208, v208
	s_waitcnt lgkmcnt(6)
	s_add_u32 m0, s27, 0xa000
	v_mfma_f32_32x32x16_bf16 v[68:83], v[104:107], v[136:139], v[68:83]
	global_load_lds_dwordx4 v176, s[8:9]
	ds_read_b128 v[136:139], v182 offset:32768
	v_exp_f32_e32 v209, v209
	v_cvt_pk_bf16_f32 v204, v204, v205
	v_cvt_pk_bf16_f32 v205, v206, v207
	s_waitcnt lgkmcnt(6)
	v_mfma_f32_32x32x16_bf16 v[84:99], v[140:143], v[116:119], v[2:17]
	ds_read_b128 v[140:143], v182 offset:40960
	v_exp_f32_e32 v210, v210
	v_exp_f32_e32 v211, v211
	s_waitcnt lgkmcnt(6)
	v_mfma_f32_32x32x16_bf16 v[100:115], v[144:147], v[116:119], v[2:17]
	v_pk_add_f32 v[150:151], v[150:151], v[208:209]
	v_pk_add_f32 v[150:151], v[150:151], v[210:211]
	v_cvt_pk_bf16_f32 v206, v208, v209
	v_cvt_pk_bf16_f32 v207, v210, v211
	s_waitcnt lgkmcnt(5)
	v_mfma_f32_32x32x16_bf16 v[84:99], v[220:223], v[120:123], v[84:99]
	v_exp_f32_e32 v212, v212
	v_exp_f32_e32 v213, v213
	s_waitcnt lgkmcnt(4)
	v_mfma_f32_32x32x16_bf16 v[100:115], v[224:227], v[120:123], v[100:115]
	v_exp_f32_e32 v214, v214
	v_exp_f32_e32 v215, v215
	s_waitcnt lgkmcnt(3)
	v_mfma_f32_32x32x16_bf16 v[84:99], v[232:235], v[124:127], v[84:99]
	v_pk_add_f32 v[150:151], v[150:151], v[212:213]
	v_pk_add_f32 v[150:151], v[150:151], v[214:215]
	v_exp_f32_e32 v216, v216
	s_waitcnt lgkmcnt(2)
	v_mfma_f32_32x32x16_bf16 v[100:115], v[132:135], v[124:127], v[100:115]
	v_exp_f32_e32 v217, v217
	v_cvt_pk_bf16_f32 v208, v212, v213
	v_cvt_pk_bf16_f32 v209, v214, v215
	s_waitcnt lgkmcnt(1)
	v_mfma_f32_32x32x16_bf16 v[84:99], v[136:139], v[128:131], v[84:99]
	v_exp_f32_e32 v218, v218
	v_exp_f32_e32 v219, v219
	s_waitcnt lgkmcnt(0)
	v_mfma_f32_32x32x16_bf16 v[100:115], v[140:143], v[128:131], v[100:115]
	v_pk_add_f32 v[150:151], v[150:151], v[216:217]
	v_pk_add_f32 v[150:151], v[150:151], v[218:219]
	v_cvt_pk_bf16_f32 v210, v216, v217
	v_cvt_pk_bf16_f32 v211, v218, v219
	s_add_u32 s8, s8, 0x40000
	s_addc_u32 s9, s9, 0
	s_waitcnt vmcnt(4) lgkmcnt(0)
	s_barrier
	s_sub_u32 s10, s10, 1
	s_cbranch_scc1 .LatB_evs_h2

; #define LAS __attribute__((address_space(3)))
; #define VREADS1(arr, d_) do { const unsigned ad_ = vbase ^ (unsigned)((d_) << 6); __builtin_amdgcn_sched_barrier(0); \
;         _Pragma("unroll") for (int ks_ = 0; ks_ < 4; ++ks_) { VTR(arr[ks_ * 2], ad_, ks_ * 4096); VTR(arr[ks_ * 2 + 1], ad_, ks_ * 4096 + 2048); } __builtin_amdgcn_sched_barrier(0); } while (0)
; #define PV1(arr, d_) do { _Pragma("unroll") for (int ks_ = 0; ks_ < 4; ++ks_) { const s16x4 lo_ = arr[ks_ * 2], hh_ = arr[ks_ * 2 + 1]; \
;         const bf16x8 bv_ = (bf16x8){lo_[0], lo_[1], lo_[2], lo_[3], hh_[0], hh_[1], hh_[2], hh_[3]}; \
;         O[d_] = __builtin_amdgcn_mfma_f32_32x32x16_bf16(pa[ks_], bv_, O[d_], 0, 0, 0); } __builtin_amdgcn_sched_barrier(0); } while (0)
; __device__ __forceinline__ void attn_unit(LAS unsigned char* lds, const bf16_t* Z, bf16_t* A2, const float* tabg, int seq_base, int S, int h, int qb, float lam) {
;     ...
;             for (int ds = 0; ds < 4; ++ds) { kf[2 * ds] = *(const LAS bf16x8*)(Kt + (kfo ^ (unsigned)(ds << 5))); kf[2 * ds + 1] = *(const LAS bf16x8*)(Kt + 32 * 256 + (kfo ^ (unsigned)(ds << 5))); }
;             __builtin_amdgcn_sched_barrier(0);
;             p0 = __builtin_amdgcn_mfma_f32_32x32x16_bf16(kf[0], qf[0], cblk, 0, 0, 0);
;             p1 = __builtin_amdgcn_mfma_f32_32x32x16_bf16(kf[1], qf[0], cblk, 0, 0, 0);
; #pragma unroll
;             for (int ds = 1; ds < 4; ++ds) {
;                 p0 = __builtin_amdgcn_mfma_f32_32x32x16_bf16(kf[2 * ds], qf[ds], p0, 0, 0, 0);
;                 p1 = __builtin_amdgcn_mfma_f32_32x32x16_bf16(kf[2 * ds + 1], qf[ds], p1, 0, 0, 0);
;             }
;     ...
; #pragma unroll
;         for (int r = 0; r < 16; ++r) { p0[r] = __builtin_amdgcn_exp2f(p0[r]); p1[r] = __builtin_amdgcn_exp2f(p1[r]); }
; #pragma unroll
;         for (int r = 0; r < 16; r += 2) { ls2 += (f32x2){p0[r], p0[r + 1]}; ls2 += (f32x2){p1[r], p1[r + 1]}; }
;         bf16x8 pa[4]; pa[0] = pack8(p0, 0); pa[1] = pack8(p0, 8); pa[2] = pack8(p1, 0); pa[3] = pack8(p1, 8);
;         LGKM0(); VREADS1(vb, 1); PV1(va, 0); LGKM0(); VREADS1(va, 2); PV1(vb, 1); LGKM0(); VREADS1(vb, 3); PV1(va, 2); LGKM0(); PV1(vb, 3);
;     ...
;         if (t + 2 < NT) asm volatile("s_waitcnt vmcnt(4) lgkmcnt(0)" ::: "memory"); else asm volatile("s_waitcnt vmcnt(0) lgkmcnt(0)" ::: "memory");
;         __builtin_amdgcn_s_barrier(); asm volatile("" ::: "memory");
.LatB_rareret_h2:
	s_waitcnt lgkmcnt(12)
	v_mfma_f32_32x32x16_bf16 v[20:35], v[188:191], v[132:135], v[20:35]
	ds_read_b64_tr_b16 v[132:133], v231 offset:20480
	ds_read_b64_tr_b16 v[134:135], v231 offset:22528
	v_exp_f32_e32 v84, v84
	v_exp_f32_e32 v85, v85
	s_waitcnt lgkmcnt(12)
	v_mfma_f32_32x32x16_bf16 v[36:51], v[188:191], v[136:139], v[36:51]
	ds_read_b64_tr_b16 v[136:137], v228 offset:24576
	ds_read_b64_tr_b16 v[138:139], v228 offset:26624
	v_exp_f32_e32 v86, v86
	v_exp_f32_e32 v87, v87
	s_waitcnt lgkmcnt(12)
	v_mfma_f32_32x32x16_bf16 v[52:67], v[188:191], v[140:143], v[52:67]
	ds_read_b64_tr_b16 v[140:141], v229 offset:24576
	ds_read_b64_tr_b16 v[142:143], v229 offset:26624
	v_pk_add_f32 v[150:151], v[150:151], v[84:85]
	v_pk_add_f32 v[150:151], v[150:151], v[86:87]
	v_exp_f32_e32 v88, v88
	s_waitcnt lgkmcnt(12)
	s_add_u32 m0, s25, 0x8000
	v_mfma_f32_32x32x16_bf16 v[68:83], v[188:191], v[144:147], v[68:83]
	global_load_lds_dwordx4 v236, s[8:9]
	ds_read_b64_tr_b16 v[144:145], v230 offset:24576
	ds_read_b64_tr_b16 v[146:147], v230 offset:26624
	v_exp_f32_e32 v89, v89
	v_cvt_pk_bf16_f32 v84, v84, v85
	v_cvt_pk_bf16_f32 v85, v86, v87
	s_waitcnt lgkmcnt(12)
	v_mfma_f32_32x32x16_bf16 v[20:35], v[192:195], v[220:223], v[20:35]
	ds_read_b64_tr_b16 v[220:221], v231 offset:24576
	ds_read_b64_tr_b16 v[222:223], v231 offset:26624
	v_exp_f32_e32 v90, v90
	v_exp_f32_e32 v91, v91
	s_waitcnt lgkmcnt(12)
	v_mfma_f32_32x32x16_bf16 v[36:51], v[192:195], v[224:227], v[36:51]
	ds_read_b64_tr_b16 v[224:225], v228 offset:28672
	ds_read_b64_tr_b16 v[226:227], v228 offset:30720
	v_pk_add_f32 v[150:151], v[150:151], v[88:89]
	v_pk_add_f32 v[150:151], v[150:151], v[90:91]
	v_cvt_pk_bf16_f32 v86, v88, v89
	v_cvt_pk_bf16_f32 v87, v90, v91
	s_waitcnt lgkmcnt(12)
	v_mfma_f32_32x32x16_bf16 v[52:67], v[192:195], v[232:235], v[52:67]
	ds_read_b64_tr_b16 v[232:233], v229 offset:28672
	ds_read_b64_tr_b16 v[234:235], v229 offset:30720
	v_exp_f32_e32 v92, v92
	v_exp_f32_e32 v93, v93
	s_waitcnt lgkmcnt(12)
	s_mov_b32 m0, s27
	v_mfma_f32_32x32x16_bf16 v[68:83], v[192:195], v[132:135], v[68:83]
	global_load_lds_dwordx4 v149, s[8:9]
	ds_read_b64_tr_b16 v[132:133], v230 offset:28672
	ds_read_b64_tr_b16 v[134:135], v230 offset:30720
	v_exp_f32_e32 v94, v94
	v_exp_f32_e32 v95, v95
	s_waitcnt lgkmcnt(12)
	v_mfma_f32_32x32x16_bf16 v[20:35], v[204:207], v[136:139], v[20:35]
	ds_read_b64_tr_b16 v[136:137], v231 offset:28672
	ds_read_b64_tr_b16 v[138:139], v231 offset:30720
	v_pk_add_f32 v[150:151], v[150:151], v[92:93]
	v_pk_add_f32 v[150:151], v[150:151], v[94:95]
	v_exp_f32_e32 v96, v96
	s_waitcnt lgkmcnt(12)
	v_mfma_f32_32x32x16_bf16 v[36:51], v[204:207], v[140:143], v[36:51]
	ds_read_b128 v[140:143], v19
	v_exp_f32_e32 v97, v97
	v_cvt_pk_bf16_f32 v88, v92, v93
	v_cvt_pk_bf16_f32 v89, v94, v95
	s_waitcnt lgkmcnt(11)
	v_mfma_f32_32x32x16_bf16 v[52:67], v[204:207], v[144:147], v[52:67]
	ds_read_b128 v[144:147], v19 offset:8192
	v_exp_f32_e32 v98, v98
	v_exp_f32_e32 v99, v99
	s_waitcnt lgkmcnt(10)
	s_add_u32 m0, s25, 0xa000
	v_mfma_f32_32x32x16_bf16 v[68:83], v[204:207], v[220:223], v[68:83]
	global_load_lds_dwordx4 v237, s[8:9]
	ds_read_b128 v[220:223], v180
	v_pk_add_f32 v[150:151], v[150:151], v[96:97]
	v_pk_add_f32 v[150:151], v[150:151], v[98:99]
	v_cvt_pk_bf16_f32 v90, v96, v97
	v_cvt_pk_bf16_f32 v91, v98, v99
	s_waitcnt lgkmcnt(9)
	v_mfma_f32_32x32x16_bf16 v[20:35], v[208:211], v[224:227], v[20:35]
	ds_read_b128 v[224:227], v180 offset:8192
	v_exp_f32_e32 v100, v100
	v_exp_f32_e32 v101, v101
	s_waitcnt lgkmcnt(8)
	v_mfma_f32_32x32x16_bf16 v[36:51], v[208:211], v[232:235], v[36:51]
	ds_read_b128 v[232:235], v181
	v_exp_f32_e32 v102, v102
	v_exp_f32_e32 v103, v103
	s_waitcnt lgkmcnt(7)
	v_mfma_f32_32x32x16_bf16 v[52:67], v[208:211], v[132:135], v[52:67]
	ds_read_b128 v[132:135], v181 offset:8192
	v_pk_add_f32 v[150:151], v[150:151], v[100:101]
	v_pk_add_f32 v[150:151], v[150:151], v[102:103]
	v_exp_f32_e32 v104, v104
	s_waitcnt lgkmcnt(6)
	s_add_u32 m0, s27, 0x2000
	v_mfma_f32_32x32x16_bf16 v[68:83], v[208:211], v[136:139], v[68:83]
	global_load_lds_dwordx4 v176, s[8:9]
	ds_read_b128 v[136:139], v182
	v_exp_f32_e32 v105, v105
	v_cvt_pk_bf16_f32 v100, v100, v101
	v_cvt_pk_bf16_f32 v101, v102, v103
	s_waitcnt lgkmcnt(6)
	v_mfma_f32_32x32x16_bf16 v[188:203], v[140:143], v[116:119], v[2:17]
	ds_read_b128 v[140:143], v182 offset:8192
	v_exp_f32_e32 v106, v106
	v_exp_f32_e32 v107, v107
	s_waitcnt lgkmcnt(6)
	v_mfma_f32_32x32x16_bf16 v[204:219], v[144:147], v[116:119], v[2:17]
	v_pk_add_f32 v[150:151], v[150:151], v[104:105]
	v_pk_add_f32 v[150:151], v[150:151], v[106:107]
	v_cvt_pk_bf16_f32 v102, v104, v105
	v_cvt_pk_bf16_f32 v103, v106, v107
	s_waitcnt lgkmcnt(5)
	v_mfma_f32_32x32x16_bf16 v[188:203], v[220:223], v[120:123], v[188:203]
	v_exp_f32_e32 v108, v108
	v_exp_f32_e32 v109, v109
	s_waitcnt lgkmcnt(4)
	v_mfma_f32_32x32x16_bf16 v[204:219], v[224:227], v[120:123], v[204:219]
	v_exp_f32_e32 v110, v110
	v_exp_f32_e32 v111, v111
	s_waitcnt lgkmcnt(3)
	v_mfma_f32_32x32x16_bf16 v[188:203], v[232:235], v[124:127], v[188:203]
	v_pk_add_f32 v[150:151], v[150:151], v[108:109]
	v_pk_add_f32 v[150:151], v[150:151], v[110:111]
	v_exp_f32_e32 v112, v112
	s_waitcnt lgkmcnt(2)
	v_mfma_f32_32x32x16_bf16 v[204:219], v[132:135], v[124:127], v[204:219]
	v_exp_f32_e32 v113, v113
	v_cvt_pk_bf16_f32 v104, v108, v109
	v_cvt_pk_bf16_f32 v105, v110, v111
	s_waitcnt lgkmcnt(1)
	v_mfma_f32_32x32x16_bf16 v[188:203], v[136:139], v[128:131], v[188:203]
	v_exp_f32_e32 v114, v114
	v_exp_f32_e32 v115, v115
	s_waitcnt lgkmcnt(0)
	v_mfma_f32_32x32x16_bf16 v[204:219], v[140:143], v[128:131], v[204:219]
	v_pk_add_f32 v[150:151], v[150:151], v[112:113]
	v_pk_add_f32 v[150:151], v[150:151], v[114:115]
	v_cvt_pk_bf16_f32 v106, v112, v113
	v_cvt_pk_bf16_f32 v107, v114, v115
	s_add_u32 s8, s8, 0x40000
	s_addc_u32 s9, s9, 0
	s_waitcnt vmcnt(4) lgkmcnt(0)
	s_barrier
	s_sub_u32 s10, s10, 1
	s_cbranch_scc1 .LatB_evs_h3

; #define LAS __attribute__((address_space(3)))
; #define VREADS1(arr, d_) do { const unsigned ad_ = vbase ^ (unsigned)((d_) << 6); __builtin_amdgcn_sched_barrier(0); \
;         _Pragma("unroll") for (int ks_ = 0; ks_ < 4; ++ks_) { VTR(arr[ks_ * 2], ad_, ks_ * 4096); VTR(arr[ks_ * 2 + 1], ad_, ks_ * 4096 + 2048); } __builtin_amdgcn_sched_barrier(0); } while (0)
; #define PV1(arr, d_) do { _Pragma("unroll") for (int ks_ = 0; ks_ < 4; ++ks_) { const s16x4 lo_ = arr[ks_ * 2], hh_ = arr[ks_ * 2 + 1]; \
;         const bf16x8 bv_ = (bf16x8){lo_[0], lo_[1], lo_[2], lo_[3], hh_[0], hh_[1], hh_[2], hh_[3]}; \
;         O[d_] = __builtin_amdgcn_mfma_f32_32x32x16_bf16(pa[ks_], bv_, O[d_], 0, 0, 0); } __builtin_amdgcn_sched_barrier(0); } while (0)
; __device__ __forceinline__ void attn_unit(LAS unsigned char* lds, const bf16_t* Z, bf16_t* A2, const float* tabg, int seq_base, int S, int h, int qb, float lam) {
;     ...
;             for (int ds = 0; ds < 4; ++ds) { kf[2 * ds] = *(const LAS bf16x8*)(Kt + (kfo ^ (unsigned)(ds << 5))); kf[2 * ds + 1] = *(const LAS bf16x8*)(Kt + 32 * 256 + (kfo ^ (unsigned)(ds << 5))); }
;             __builtin_amdgcn_sched_barrier(0);
;             p0 = __builtin_amdgcn_mfma_f32_32x32x16_bf16(kf[0], qf[0], cblk, 0, 0, 0);
;             p1 = __builtin_amdgcn_mfma_f32_32x32x16_bf16(kf[1], qf[0], cblk, 0, 0, 0);
; #pragma unroll
;             for (int ds = 1; ds < 4; ++ds) {
;                 p0 = __builtin_amdgcn_mfma_f32_32x32x16_bf16(kf[2 * ds], qf[ds], p0, 0, 0, 0);
;                 p1 = __builtin_amdgcn_mfma_f32_32x32x16_bf16(kf[2 * ds + 1], qf[ds], p1, 0, 0, 0);
;             }
;     ...
; #pragma unroll
;         for (int r = 0; r < 16; ++r) { p0[r] = __builtin_amdgcn_exp2f(p0[r]); p1[r] = __builtin_amdgcn_exp2f(p1[r]); }
; #pragma unroll
;         for (int r = 0; r < 16; r += 2) { ls2 += (f32x2){p0[r], p0[r + 1]}; ls2 += (f32x2){p1[r], p1[r + 1]}; }
;         bf16x8 pa[4]; pa[0] = pack8(p0, 0); pa[1] = pack8(p0, 8); pa[2] = pack8(p1, 0); pa[3] = pack8(p1, 8);
;         LGKM0(); VREADS1(vb, 1); PV1(va, 0); LGKM0(); VREADS1(va, 2); PV1(vb, 1); LGKM0(); VREADS1(vb, 3); PV1(va, 2); LGKM0(); PV1(vb, 3);
;     ...
;         if (t + 2 < NT) asm volatile("s_waitcnt vmcnt(4) lgkmcnt(0)" ::: "memory"); else asm volatile("s_waitcnt vmcnt(0) lgkmcnt(0)" ::: "memory");
;         __builtin_amdgcn_s_barrier(); asm volatile("" ::: "memory");
.LatB_rareret_h3:
	s_waitcnt lgkmcnt(12)
	v_mfma_f32_32x32x16_bf16 v[20:35], v[84:87], v[132:135], v[20:35]
	ds_read_b64_tr_b16 v[132:133], v231 offset:36864
	ds_read_b64_tr_b16 v[134:135], v231 offset:38912
	v_exp_f32_e32 v188, v188
	v_exp_f32_e32 v189, v189
	s_waitcnt lgkmcnt(12)
	v_mfma_f32_32x32x16_bf16 v[36:51], v[84:87], v[136:139], v[36:51]
	ds_read_b64_tr_b16 v[136:137], v228 offset:40960
	ds_read_b64_tr_b16 v[138:139], v228 offset:43008
	v_exp_f32_e32 v190, v190
	v_exp_f32_e32 v191, v191
	s_waitcnt lgkmcnt(12)
	v_mfma_f32_32x32x16_bf16 v[52:67], v[84:87], v[140:143], v[52:67]
	ds_read_b64_tr_b16 v[140:141], v229 offset:40960
	ds_read_b64_tr_b16 v[142:143], v229 offset:43008
	v_pk_add_f32 v[150:151], v[150:151], v[188:189]
	v_pk_add_f32 v[150:151], v[150:151], v[190:191]
	v_exp_f32_e32 v192, v192
	s_waitcnt lgkmcnt(12)
	s_mov_b32 m0, s25
	v_mfma_f32_32x32x16_bf16 v[68:83], v[84:87], v[144:147], v[68:83]
	global_load_lds_dwordx4 v236, s[8:9]
	ds_read_b64_tr_b16 v[144:145], v230 offset:40960
	ds_read_b64_tr_b16 v[146:147], v230 offset:43008
	v_exp_f32_e32 v193, v193
	v_cvt_pk_bf16_f32 v188, v188, v189
	v_cvt_pk_bf16_f32 v189, v190, v191
	s_waitcnt lgkmcnt(12)
	v_mfma_f32_32x32x16_bf16 v[20:35], v[88:91], v[220:223], v[20:35]
	ds_read_b64_tr_b16 v[220:221], v231 offset:40960
	ds_read_b64_tr_b16 v[222:223], v231 offset:43008
	v_exp_f32_e32 v194, v194
	v_exp_f32_e32 v195, v195
	s_waitcnt lgkmcnt(12)
	v_mfma_f32_32x32x16_bf16 v[36:51], v[88:91], v[224:227], v[36:51]
	ds_read_b64_tr_b16 v[224:225], v228 offset:45056
	ds_read_b64_tr_b16 v[226:227], v228 offset:47104
	v_pk_add_f32 v[150:151], v[150:151], v[192:193]
	v_pk_add_f32 v[150:151], v[150:151], v[194:195]
	v_cvt_pk_bf16_f32 v190, v192, v193
	v_cvt_pk_bf16_f32 v191, v194, v195
	s_waitcnt lgkmcnt(12)
	v_mfma_f32_32x32x16_bf16 v[52:67], v[88:91], v[232:235], v[52:67]
	ds_read_b64_tr_b16 v[232:233], v229 offset:45056
	ds_read_b64_tr_b16 v[234:235], v229 offset:47104
	v_exp_f32_e32 v196, v196
	v_exp_f32_e32 v197, v197
	s_waitcnt lgkmcnt(12)
	s_add_u32 m0, s27, 0x4000
	v_mfma_f32_32x32x16_bf16 v[68:83], v[88:91], v[132:135], v[68:83]
	global_load_lds_dwordx4 v149, s[8:9]
	ds_read_b64_tr_b16 v[132:133], v230 offset:45056
	ds_read_b64_tr_b16 v[134:135], v230 offset:47104
	v_exp_f32_e32 v198, v198
	v_exp_f32_e32 v199, v199
	s_waitcnt lgkmcnt(12)
	v_mfma_f32_32x32x16_bf16 v[20:35], v[100:103], v[136:139], v[20:35]
	ds_read_b64_tr_b16 v[136:137], v231 offset:45056
	ds_read_b64_tr_b16 v[138:139], v231 offset:47104
	v_pk_add_f32 v[150:151], v[150:151], v[196:197]
	v_pk_add_f32 v[150:151], v[150:151], v[198:199]
	v_exp_f32_e32 v200, v200
	s_waitcnt lgkmcnt(12)
	v_mfma_f32_32x32x16_bf16 v[36:51], v[100:103], v[140:143], v[36:51]
	ds_read_b128 v[140:143], v19 offset:16384
	v_exp_f32_e32 v201, v201
	v_cvt_pk_bf16_f32 v192, v196, v197
	v_cvt_pk_bf16_f32 v193, v198, v199
	s_waitcnt lgkmcnt(11)
	v_mfma_f32_32x32x16_bf16 v[52:67], v[100:103], v[144:147], v[52:67]
	ds_read_b128 v[144:147], v19 offset:24576
	v_exp_f32_e32 v202, v202
	v_exp_f32_e32 v203, v203
	s_waitcnt lgkmcnt(10)
	s_add_u32 m0, s25, 0x2000
	v_mfma_f32_32x32x16_bf16 v[68:83], v[100:103], v[220:223], v[68:83]
	global_load_lds_dwordx4 v237, s[8:9]
	ds_read_b128 v[220:223], v180 offset:16384
	v_pk_add_f32 v[150:151], v[150:151], v[200:201]
	v_pk_add_f32 v[150:151], v[150:151], v[202:203]
	v_cvt_pk_bf16_f32 v194, v200, v201
	v_cvt_pk_bf16_f32 v195, v202, v203
	s_waitcnt lgkmcnt(9)
	v_mfma_f32_32x32x16_bf16 v[20:35], v[104:107], v[224:227], v[20:35]
	ds_read_b128 v[224:227], v180 offset:24576
	v_exp_f32_e32 v204, v204
	v_exp_f32_e32 v205, v205
	s_waitcnt lgkmcnt(8)
	v_mfma_f32_32x32x16_bf16 v[36:51], v[104:107], v[232:235], v[36:51]
	ds_read_b128 v[232:235], v181 offset:16384
	v_exp_f32_e32 v206, v206
	v_exp_f32_e32 v207, v207
	s_waitcnt lgkmcnt(7)
	v_mfma_f32_32x32x16_bf16 v[52:67], v[104:107], v[132:135], v[52:67]
	ds_read_b128 v[132:135], v181 offset:24576
	v_pk_add_f32 v[150:151], v[150:151], v[204:205]
	v_pk_add_f32 v[150:151], v[150:151], v[206:207]
	v_exp_f32_e32 v208, v208
	s_waitcnt lgkmcnt(6)
	s_add_u32 m0, s27, 0x6000
	v_mfma_f32_32x32x16_bf16 v[68:83], v[104:107], v[136:139], v[68:83]
	global_load_lds_dwordx4 v176, s[8:9]
	ds_read_b128 v[136:139], v182 offset:16384
	v_exp_f32_e32 v209, v209
	v_cvt_pk_bf16_f32 v204, v204, v205
	v_cvt_pk_bf16_f32 v205, v206, v207
	s_waitcnt lgkmcnt(6)
	v_mfma_f32_32x32x16_bf16 v[84:99], v[140:143], v[116:119], v[2:17]
	ds_read_b128 v[140:143], v182 offset:24576
	v_exp_f32_e32 v210, v210
	v_exp_f32_e32 v211, v211
	s_waitcnt lgkmcnt(6)
	v_mfma_f32_32x32x16_bf16 v[100:115], v[144:147], v[116:119], v[2:17]
	v_pk_add_f32 v[150:151], v[150:151], v[208:209]
	v_pk_add_f32 v[150:151], v[150:151], v[210:211]
	v_cvt_pk_bf16_f32 v206, v208, v209
	v_cvt_pk_bf16_f32 v207, v210, v211
	s_waitcnt lgkmcnt(5)
	v_mfma_f32_32x32x16_bf16 v[84:99], v[220:223], v[120:123], v[84:99]
	v_exp_f32_e32 v212, v212
	v_exp_f32_e32 v213, v213
	s_waitcnt lgkmcnt(4)
	v_mfma_f32_32x32x16_bf16 v[100:115], v[224:227], v[120:123], v[100:115]
	v_exp_f32_e32 v214, v214
	v_exp_f32_e32 v215, v215
	s_waitcnt lgkmcnt(3)
	v_mfma_f32_32x32x16_bf16 v[84:99], v[232:235], v[124:127], v[84:99]
	v_pk_add_f32 v[150:151], v[150:151], v[212:213]
	v_pk_add_f32 v[150:151], v[150:151], v[214:215]
	v_exp_f32_e32 v216, v216
	s_waitcnt lgkmcnt(2)
	v_mfma_f32_32x32x16_bf16 v[100:115], v[132:135], v[124:127], v[100:115]
	v_exp_f32_e32 v217, v217
	v_cvt_pk_bf16_f32 v208, v212, v213
	v_cvt_pk_bf16_f32 v209, v214, v215
	s_waitcnt lgkmcnt(1)
	v_mfma_f32_32x32x16_bf16 v[84:99], v[136:139], v[128:131], v[84:99]
	v_exp_f32_e32 v218, v218
	v_exp_f32_e32 v219, v219
	s_waitcnt lgkmcnt(0)
	v_mfma_f32_32x32x16_bf16 v[100:115], v[140:143], v[128:131], v[100:115]
	v_pk_add_f32 v[150:151], v[150:151], v[216:217]
	v_pk_add_f32 v[150:151], v[150:151], v[218:219]
	v_cvt_pk_bf16_f32 v210, v216, v217
	v_cvt_pk_bf16_f32 v211, v218, v219
	s_add_u32 s8, s8, 0x40000
	s_addc_u32 s9, s9, 0
	s_waitcnt vmcnt(4) lgkmcnt(0)
	s_barrier
	s_sub_u32 s10, s10, 1
	s_cbranch_scc1 .LatB_evs_h4

; #define LAS __attribute__((address_space(3)))
; #define VREADS1(arr, d_) do { const unsigned ad_ = vbase ^ (unsigned)((d_) << 6); __builtin_amdgcn_sched_barrier(0); \
;         _Pragma("unroll") for (int ks_ = 0; ks_ < 4; ++ks_) { VTR(arr[ks_ * 2], ad_, ks_ * 4096); VTR(arr[ks_ * 2 + 1], ad_, ks_ * 4096 + 2048); } __builtin_amdgcn_sched_barrier(0); } while (0)
; #define PV1(arr, d_) do { _Pragma("unroll") for (int ks_ = 0; ks_ < 4; ++ks_) { const s16x4 lo_ = arr[ks_ * 2], hh_ = arr[ks_ * 2 + 1]; \
;         const bf16x8 bv_ = (bf16x8){lo_[0], lo_[1], lo_[2], lo_[3], hh_[0], hh_[1], hh_[2], hh_[3]}; \
;         O[d_] = __builtin_amdgcn_mfma_f32_32x32x16_bf16(pa[ks_], bv_, O[d_], 0, 0, 0); } __builtin_amdgcn_sched_barrier(0); } while (0)
; __device__ __forceinline__ void attn_unit(LAS unsigned char* lds, const bf16_t* Z, bf16_t* A2, const float* tabg, int seq_base, int S, int h, int qb, float lam) {
;     ...
;             for (int ds = 0; ds < 4; ++ds) { kf[2 * ds] = *(const LAS bf16x8*)(Kt + (kfo ^ (unsigned)(ds << 5))); kf[2 * ds + 1] = *(const LAS bf16x8*)(Kt + 32 * 256 + (kfo ^ (unsigned)(ds << 5))); }
;             __builtin_amdgcn_sched_barrier(0);
;             p0 = __builtin_amdgcn_mfma_f32_32x32x16_bf16(kf[0], qf[0], cblk, 0, 0, 0);
;             p1 = __builtin_amdgcn_mfma_f32_32x32x16_bf16(kf[1], qf[0], cblk, 0, 0, 0);
; #pragma unroll
;             for (int ds = 1; ds < 4; ++ds) {
;                 p0 = __builtin_amdgcn_mfma_f32_32x32x16_bf16(kf[2 * ds], qf[ds], p0, 0, 0, 0);
;                 p1 = __builtin_amdgcn_mfma_f32_32x32x16_bf16(kf[2 * ds + 1], qf[ds], p1, 0, 0, 0);
;             }
;     ...
; #pragma unroll
;         for (int r = 0; r < 16; ++r) { p0[r] = __builtin_amdgcn_exp2f(p0[r]); p1[r] = __builtin_amdgcn_exp2f(p1[r]); }
; #pragma unroll
;         for (int r = 0; r < 16; r += 2) { ls2 += (f32x2){p0[r], p0[r + 1]}; ls2 += (f32x2){p1[r], p1[r + 1]}; }
;         bf16x8 pa[4]; pa[0] = pack8(p0, 0); pa[1] = pack8(p0, 8); pa[2] = pack8(p1, 0); pa[3] = pack8(p1, 8);
;         LGKM0(); VREADS1(vb, 1); PV1(va, 0); LGKM0(); VREADS1(va, 2); PV1(vb, 1); LGKM0(); VREADS1(vb, 3); PV1(va, 2); LGKM0(); PV1(vb, 3);
;     ...
;         if (t + 2 < NT) asm volatile("s_waitcnt vmcnt(4) lgkmcnt(0)" ::: "memory"); else asm volatile("s_waitcnt vmcnt(0) lgkmcnt(0)" ::: "memory");
;         __builtin_amdgcn_s_barrier(); asm volatile("" ::: "memory");
.LatB_rareret_h4:
	s_waitcnt lgkmcnt(12)
	v_mfma_f32_32x32x16_bf16 v[20:35], v[188:191], v[132:135], v[20:35]
	ds_read_b64_tr_b16 v[132:133], v231 offset:4096
	ds_read_b64_tr_b16 v[134:135], v231 offset:6144
	v_exp_f32_e32 v84, v84
	v_exp_f32_e32 v85, v85
	s_waitcnt lgkmcnt(12)
	v_mfma_f32_32x32x16_bf16 v[36:51], v[188:191], v[136:139], v[36:51]
	ds_read_b64_tr_b16 v[136:137], v228 offset:8192
	ds_read_b64_tr_b16 v[138:139], v228 offset:10240
	v_exp_f32_e32 v86, v86
	v_exp_f32_e32 v87, v87
	s_waitcnt lgkmcnt(12)
	v_mfma_f32_32x32x16_bf16 v[52:67], v[188:191], v[140:143], v[52:67]
	ds_read_b64_tr_b16 v[140:141], v229 offset:8192
	ds_read_b64_tr_b16 v[142:143], v229 offset:10240
	v_pk_add_f32 v[150:151], v[150:151], v[84:85]
	v_pk_add_f32 v[150:151], v[150:151], v[86:87]
	v_exp_f32_e32 v88, v88
	s_waitcnt lgkmcnt(12)
	s_add_u32 m0, s25, 0x4000
	v_mfma_f32_32x32x16_bf16 v[68:83], v[188:191], v[144:147], v[68:83]
	global_load_lds_dwordx4 v236, s[8:9]
	ds_read_b64_tr_b16 v[144:145], v230 offset:8192
	ds_read_b64_tr_b16 v[146:147], v230 offset:10240
	v_exp_f32_e32 v89, v89
	v_cvt_pk_bf16_f32 v84, v84, v85
	v_cvt_pk_bf16_f32 v85, v86, v87
	s_waitcnt lgkmcnt(12)
	v_mfma_f32_32x32x16_bf16 v[20:35], v[192:195], v[220:223], v[20:35]
	ds_read_b64_tr_b16 v[220:221], v231 offset:8192
	ds_read_b64_tr_b16 v[222:223], v231 offset:10240
	v_exp_f32_e32 v90, v90
	v_exp_f32_e32 v91, v91
	s_waitcnt lgkmcnt(12)
	v_mfma_f32_32x32x16_bf16 v[36:51], v[192:195], v[224:227], v[36:51]
	ds_read_b64_tr_b16 v[224:225], v228 offset:12288
	ds_read_b64_tr_b16 v[226:227], v228 offset:14336
	v_pk_add_f32 v[150:151], v[150:151], v[88:89]
	v_pk_add_f32 v[150:151], v[150:151], v[90:91]
	v_cvt_pk_bf16_f32 v86, v88, v89
	v_cvt_pk_bf16_f32 v87, v90, v91
	s_waitcnt lgkmcnt(12)
	v_mfma_f32_32x32x16_bf16 v[52:67], v[192:195], v[232:235], v[52:67]
	ds_read_b64_tr_b16 v[232:233], v229 offset:12288
	ds_read_b64_tr_b16 v[234:235], v229 offset:14336
	v_exp_f32_e32 v92, v92
	v_exp_f32_e32 v93, v93
	s_waitcnt lgkmcnt(12)
	s_add_u32 m0, s27, 0x8000
	v_mfma_f32_32x32x16_bf16 v[68:83], v[192:195], v[132:135], v[68:83]
	global_load_lds_dwordx4 v149, s[8:9]
	ds_read_b64_tr_b16 v[132:133], v230 offset:12288
	ds_read_b64_tr_b16 v[134:135], v230 offset:14336
	v_exp_f32_e32 v94, v94
	v_exp_f32_e32 v95, v95
	s_waitcnt lgkmcnt(12)
	v_mfma_f32_32x32x16_bf16 v[20:35], v[204:207], v[136:139], v[20:35]
	ds_read_b64_tr_b16 v[136:137], v231 offset:12288
	ds_read_b64_tr_b16 v[138:139], v231 offset:14336
	v_pk_add_f32 v[150:151], v[150:151], v[92:93]
	v_pk_add_f32 v[150:151], v[150:151], v[94:95]
	v_exp_f32_e32 v96, v96
	s_waitcnt lgkmcnt(12)
	v_mfma_f32_32x32x16_bf16 v[36:51], v[204:207], v[140:143], v[36:51]
	ds_read_b128 v[140:143], v19 offset:32768
	v_exp_f32_e32 v97, v97
	v_cvt_pk_bf16_f32 v88, v92, v93
	v_cvt_pk_bf16_f32 v89, v94, v95
	s_waitcnt lgkmcnt(11)
	v_mfma_f32_32x32x16_bf16 v[52:67], v[204:207], v[144:147], v[52:67]
	ds_read_b128 v[144:147], v19 offset:40960
	v_exp_f32_e32 v98, v98
	v_exp_f32_e32 v99, v99
	s_waitcnt lgkmcnt(10)
	s_add_u32 m0, s25, 0x6000
	v_mfma_f32_32x32x16_bf16 v[68:83], v[204:207], v[220:223], v[68:83]
	global_load_lds_dwordx4 v237, s[8:9]
	ds_read_b128 v[220:223], v180 offset:32768
	v_pk_add_f32 v[150:151], v[150:151], v[96:97]
	v_pk_add_f32 v[150:151], v[150:151], v[98:99]
	v_cvt_pk_bf16_f32 v90, v96, v97
	v_cvt_pk_bf16_f32 v91, v98, v99
	s_waitcnt lgkmcnt(9)
	v_mfma_f32_32x32x16_bf16 v[20:35], v[208:211], v[224:227], v[20:35]
	ds_read_b128 v[224:227], v180 offset:40960
	v_exp_f32_e32 v100, v100
	v_exp_f32_e32 v101, v101
	s_waitcnt lgkmcnt(8)
	v_mfma_f32_32x32x16_bf16 v[36:51], v[208:211], v[232:235], v[36:51]
	ds_read_b128 v[232:235], v181 offset:32768
	v_exp_f32_e32 v102, v102
	v_exp_f32_e32 v103, v103
	s_waitcnt lgkmcnt(7)
	v_mfma_f32_32x32x16_bf16 v[52:67], v[208:211], v[132:135], v[52:67]
	ds_read_b128 v[132:135], v181 offset:40960
	v_pk_add_f32 v[150:151], v[150:151], v[100:101]
	v_pk_add_f32 v[150:151], v[150:151], v[102:103]
	v_exp_f32_e32 v104, v104
	s_waitcnt lgkmcnt(6)
	s_add_u32 m0, s27, 0xa000
	v_mfma_f32_32x32x16_bf16 v[68:83], v[208:211], v[136:139], v[68:83]
	global_load_lds_dwordx4 v176, s[8:9]
	ds_read_b128 v[136:139], v182 offset:32768
	v_exp_f32_e32 v105, v105
	v_cvt_pk_bf16_f32 v100, v100, v101
	v_cvt_pk_bf16_f32 v101, v102, v103
	s_waitcnt lgkmcnt(6)
	v_mfma_f32_32x32x16_bf16 v[188:203], v[140:143], v[116:119], v[2:17]
	ds_read_b128 v[140:143], v182 offset:40960
	v_exp_f32_e32 v106, v106
	v_exp_f32_e32 v107, v107
	s_waitcnt lgkmcnt(6)
	v_mfma_f32_32x32x16_bf16 v[204:219], v[144:147], v[116:119], v[2:17]
	v_pk_add_f32 v[150:151], v[150:151], v[104:105]
	v_pk_add_f32 v[150:151], v[150:151], v[106:107]
	v_cvt_pk_bf16_f32 v102, v104, v105
	v_cvt_pk_bf16_f32 v103, v106, v107
	s_waitcnt lgkmcnt(5)
	v_mfma_f32_32x32x16_bf16 v[188:203], v[220:223], v[120:123], v[188:203]
	v_exp_f32_e32 v108, v108
	v_exp_f32_e32 v109, v109
	s_waitcnt lgkmcnt(4)
	v_mfma_f32_32x32x16_bf16 v[204:219], v[224:227], v[120:123], v[204:219]
	v_exp_f32_e32 v110, v110
	v_exp_f32_e32 v111, v111
	s_waitcnt lgkmcnt(3)
	v_mfma_f32_32x32x16_bf16 v[188:203], v[232:235], v[124:127], v[188:203]
	v_pk_add_f32 v[150:151], v[150:151], v[108:109]
	v_pk_add_f32 v[150:151], v[150:151], v[110:111]
	v_exp_f32_e32 v112, v112
	s_waitcnt lgkmcnt(2)
	v_mfma_f32_32x32x16_bf16 v[204:219], v[132:135], v[124:127], v[204:219]
	v_exp_f32_e32 v113, v113
	v_cvt_pk_bf16_f32 v104, v108, v109
	v_cvt_pk_bf16_f32 v105, v110, v111
	s_waitcnt lgkmcnt(1)
	v_mfma_f32_32x32x16_bf16 v[188:203], v[136:139], v[128:131], v[188:203]
	v_exp_f32_e32 v114, v114
	v_exp_f32_e32 v115, v115
	s_waitcnt lgkmcnt(0)
	v_mfma_f32_32x32x16_bf16 v[204:219], v[140:143], v[128:131], v[204:219]
	v_pk_add_f32 v[150:151], v[150:151], v[112:113]
	v_pk_add_f32 v[150:151], v[150:151], v[114:115]
	v_cvt_pk_bf16_f32 v106, v112, v113
	v_cvt_pk_bf16_f32 v107, v114, v115
	s_add_u32 s8, s8, 0x40000
	s_addc_u32 s9, s9, 0
	s_waitcnt vmcnt(4) lgkmcnt(0)
	s_barrier
	s_sub_u32 s10, s10, 1
	s_cbranch_scc1 .LatB_evs_h5

; #define LAS __attribute__((address_space(3)))
; #define VREADS1(arr, d_) do { const unsigned ad_ = vbase ^ (unsigned)((d_) << 6); __builtin_amdgcn_sched_barrier(0); \
;         _Pragma("unroll") for (int ks_ = 0; ks_ < 4; ++ks_) { VTR(arr[ks_ * 2], ad_, ks_ * 4096); VTR(arr[ks_ * 2 + 1], ad_, ks_ * 4096 + 2048); } __builtin_amdgcn_sched_barrier(0); } while (0)
; #define PV1(arr, d_) do { _Pragma("unroll") for (int ks_ = 0; ks_ < 4; ++ks_) { const s16x4 lo_ = arr[ks_ * 2], hh_ = arr[ks_ * 2 + 1]; \
;         const bf16x8 bv_ = (bf16x8){lo_[0], lo_[1], lo_[2], lo_[3], hh_[0], hh_[1], hh_[2], hh_[3]}; \
;         O[d_] = __builtin_amdgcn_mfma_f32_32x32x16_bf16(pa[ks_], bv_, O[d_], 0, 0, 0); } __builtin_amdgcn_sched_barrier(0); } while (0)
; __device__ __forceinline__ void attn_unit(LAS unsigned char* lds, const bf16_t* Z, bf16_t* A2, const float* tabg, int seq_base, int S, int h, int qb, float lam) {
;     ...
;             for (int ds = 0; ds < 4; ++ds) { kf[2 * ds] = *(const LAS bf16x8*)(Kt + (kfo ^ (unsigned)(ds << 5))); kf[2 * ds + 1] = *(const LAS bf16x8*)(Kt + 32 * 256 + (kfo ^ (unsigned)(ds << 5))); }
;             __builtin_amdgcn_sched_barrier(0);
;             p0 = __builtin_amdgcn_mfma_f32_32x32x16_bf16(kf[0], qf[0], cblk, 0, 0, 0);
;             p1 = __builtin_amdgcn_mfma_f32_32x32x16_bf16(kf[1], qf[0], cblk, 0, 0, 0);
; #pragma unroll
;             for (int ds = 1; ds < 4; ++ds) {
;                 p0 = __builtin_amdgcn_mfma_f32_32x32x16_bf16(kf[2 * ds], qf[ds], p0, 0, 0, 0);
;                 p1 = __builtin_amdgcn_mfma_f32_32x32x16_bf16(kf[2 * ds + 1], qf[ds], p1, 0, 0, 0);
;             }
;     ...
; #pragma unroll
;         for (int r = 0; r < 16; ++r) { p0[r] = __builtin_amdgcn_exp2f(p0[r]); p1[r] = __builtin_amdgcn_exp2f(p1[r]); }
; #pragma unroll
;         for (int r = 0; r < 16; r += 2) { ls2 += (f32x2){p0[r], p0[r + 1]}; ls2 += (f32x2){p1[r], p1[r + 1]}; }
;         bf16x8 pa[4]; pa[0] = pack8(p0, 0); pa[1] = pack8(p0, 8); pa[2] = pack8(p1, 0); pa[3] = pack8(p1, 8);
;         LGKM0(); VREADS1(vb, 1); PV1(va, 0); LGKM0(); VREADS1(va, 2); PV1(vb, 1); LGKM0(); VREADS1(vb, 3); PV1(va, 2); LGKM0(); PV1(vb, 3);
;     ...
;         if (t + 2 < NT) asm volatile("s_waitcnt vmcnt(4) lgkmcnt(0)" ::: "memory"); else asm volatile("s_waitcnt vmcnt(0) lgkmcnt(0)" ::: "memory");
;         __builtin_amdgcn_s_barrier(); asm volatile("" ::: "memory");
.LatB_rareret_h5:
	s_waitcnt lgkmcnt(12)
	v_mfma_f32_32x32x16_bf16 v[20:35], v[84:87], v[132:135], v[20:35]
	ds_read_b64_tr_b16 v[132:133], v231 offset:20480
	ds_read_b64_tr_b16 v[134:135], v231 offset:22528
	v_exp_f32_e32 v188, v188
	v_exp_f32_e32 v189, v189
	s_waitcnt lgkmcnt(12)
	v_mfma_f32_32x32x16_bf16 v[36:51], v[84:87], v[136:139], v[36:51]
	ds_read_b64_tr_b16 v[136:137], v228 offset:24576
	ds_read_b64_tr_b16 v[138:139], v228 offset:26624
	v_exp_f32_e32 v190, v190
	v_exp_f32_e32 v191, v191
	s_waitcnt lgkmcnt(12)
	v_mfma_f32_32x32x16_bf16 v[52:67], v[84:87], v[140:143], v[52:67]
	ds_read_b64_tr_b16 v[140:141], v229 offset:24576
	ds_read_b64_tr_b16 v[142:143], v229 offset:26624
	v_pk_add_f32 v[150:151], v[150:151], v[188:189]
	v_pk_add_f32 v[150:151], v[150:151], v[190:191]
	v_exp_f32_e32 v192, v192
	s_waitcnt lgkmcnt(12)
	s_add_u32 m0, s25, 0x8000
	v_mfma_f32_32x32x16_bf16 v[68:83], v[84:87], v[144:147], v[68:83]
	global_load_lds_dwordx4 v236, s[8:9]
	ds_read_b64_tr_b16 v[144:145], v230 offset:24576
	ds_read_b64_tr_b16 v[146:147], v230 offset:26624
	v_exp_f32_e32 v193, v193
	v_cvt_pk_bf16_f32 v188, v188, v189
	v_cvt_pk_bf16_f32 v189, v190, v191
	s_waitcnt lgkmcnt(12)
	v_mfma_f32_32x32x16_bf16 v[20:35], v[88:91], v[220:223], v[20:35]
	ds_read_b64_tr_b16 v[220:221], v231 offset:24576
	ds_read_b64_tr_b16 v[222:223], v231 offset:26624
	v_exp_f32_e32 v194, v194
	v_exp_f32_e32 v195, v195
	s_waitcnt lgkmcnt(12)
	v_mfma_f32_32x32x16_bf16 v[36:51], v[88:91], v[224:227], v[36:51]
	ds_read_b64_tr_b16 v[224:225], v228 offset:28672
	ds_read_b64_tr_b16 v[226:227], v228 offset:30720
	v_pk_add_f32 v[150:151], v[150:151], v[192:193]
	v_pk_add_f32 v[150:151], v[150:151], v[194:195]
	v_cvt_pk_bf16_f32 v190, v192, v193
	v_cvt_pk_bf16_f32 v191, v194, v195
	s_waitcnt lgkmcnt(12)
	v_mfma_f32_32x32x16_bf16 v[52:67], v[88:91], v[232:235], v[52:67]
	ds_read_b64_tr_b16 v[232:233], v229 offset:28672
	ds_read_b64_tr_b16 v[234:235], v229 offset:30720
	v_exp_f32_e32 v196, v196
	v_exp_f32_e32 v197, v197
	s_waitcnt lgkmcnt(12)
	s_mov_b32 m0, s27
	v_mfma_f32_32x32x16_bf16 v[68:83], v[88:91], v[132:135], v[68:83]
	global_load_lds_dwordx4 v149, s[8:9]
	ds_read_b64_tr_b16 v[132:133], v230 offset:28672
	ds_read_b64_tr_b16 v[134:135], v230 offset:30720
	v_exp_f32_e32 v198, v198
	v_exp_f32_e32 v199, v199
	s_waitcnt lgkmcnt(12)
	v_mfma_f32_32x32x16_bf16 v[20:35], v[100:103], v[136:139], v[20:35]
	ds_read_b64_tr_b16 v[136:137], v231 offset:28672
	ds_read_b64_tr_b16 v[138:139], v231 offset:30720
	v_pk_add_f32 v[150:151], v[150:151], v[196:197]
	v_pk_add_f32 v[150:151], v[150:151], v[198:199]
	v_exp_f32_e32 v200, v200
	s_waitcnt lgkmcnt(12)
	v_mfma_f32_32x32x16_bf16 v[36:51], v[100:103], v[140:143], v[36:51]
	ds_read_b128 v[140:143], v19
	v_exp_f32_e32 v201, v201
	v_cvt_pk_bf16_f32 v192, v196, v197
	v_cvt_pk_bf16_f32 v193, v198, v199
	s_waitcnt lgkmcnt(11)
	v_mfma_f32_32x32x16_bf16 v[52:67], v[100:103], v[144:147], v[52:67]
	ds_read_b128 v[144:147], v19 offset:8192
	v_exp_f32_e32 v202, v202
	v_exp_f32_e32 v203, v203
	s_waitcnt lgkmcnt(10)
	s_add_u32 m0, s25, 0xa000
	v_mfma_f32_32x32x16_bf16 v[68:83], v[100:103], v[220:223], v[68:83]
	global_load_lds_dwordx4 v237, s[8:9]
	ds_read_b128 v[220:223], v180
	v_pk_add_f32 v[150:151], v[150:151], v[200:201]
	v_pk_add_f32 v[150:151], v[150:151], v[202:203]
	v_cvt_pk_bf16_f32 v194, v200, v201
	v_cvt_pk_bf16_f32 v195, v202, v203
	s_waitcnt lgkmcnt(9)
	v_mfma_f32_32x32x16_bf16 v[20:35], v[104:107], v[224:227], v[20:35]
	ds_read_b128 v[224:227], v180 offset:8192
	v_exp_f32_e32 v204, v204
	v_exp_f32_e32 v205, v205
	s_waitcnt lgkmcnt(8)
	v_mfma_f32_32x32x16_bf16 v[36:51], v[104:107], v[232:235], v[36:51]
	ds_read_b128 v[232:235], v181
	v_exp_f32_e32 v206, v206
	v_exp_f32_e32 v207, v207
	s_waitcnt lgkmcnt(7)
	v_mfma_f32_32x32x16_bf16 v[52:67], v[104:107], v[132:135], v[52:67]
	ds_read_b128 v[132:135], v181 offset:8192
	v_pk_add_f32 v[150:151], v[150:151], v[204:205]
	v_pk_add_f32 v[150:151], v[150:151], v[206:207]
	v_exp_f32_e32 v208, v208
	s_waitcnt lgkmcnt(6)
	s_add_u32 m0, s27, 0x2000
	v_mfma_f32_32x32x16_bf16 v[68:83], v[104:107], v[136:139], v[68:83]
	global_load_lds_dwordx4 v176, s[8:9]
	ds_read_b128 v[136:139], v182
	v_exp_f32_e32 v209, v209
	v_cvt_pk_bf16_f32 v204, v204, v205
	v_cvt_pk_bf16_f32 v205, v206, v207
	s_waitcnt lgkmcnt(6)
	v_mfma_f32_32x32x16_bf16 v[84:99], v[140:143], v[116:119], v[2:17]
	ds_read_b128 v[140:143], v182 offset:8192
	v_exp_f32_e32 v210, v210
	v_exp_f32_e32 v211, v211
	s_waitcnt lgkmcnt(6)
	v_mfma_f32_32x32x16_bf16 v[100:115], v[144:147], v[116:119], v[2:17]
	v_pk_add_f32 v[150:151], v[150:151], v[208:209]
	v_pk_add_f32 v[150:151], v[150:151], v[210:211]
	v_cvt_pk_bf16_f32 v206, v208, v209
	v_cvt_pk_bf16_f32 v207, v210, v211
	s_waitcnt lgkmcnt(5)
	v_mfma_f32_32x32x16_bf16 v[84:99], v[220:223], v[120:123], v[84:99]
	v_exp_f32_e32 v212, v212
	v_exp_f32_e32 v213, v213
	s_waitcnt lgkmcnt(4)
	v_mfma_f32_32x32x16_bf16 v[100:115], v[224:227], v[120:123], v[100:115]
	v_exp_f32_e32 v214, v214
	v_exp_f32_e32 v215, v215
	s_waitcnt lgkmcnt(3)
	v_mfma_f32_32x32x16_bf16 v[84:99], v[232:235], v[124:127], v[84:99]
	v_pk_add_f32 v[150:151], v[150:151], v[212:213]
	v_pk_add_f32 v[150:151], v[150:151], v[214:215]
	v_exp_f32_e32 v216, v216
	s_waitcnt lgkmcnt(2)
	v_mfma_f32_32x32x16_bf16 v[100:115], v[132:135], v[124:127], v[100:115]
	v_exp_f32_e32 v217, v217
	v_cvt_pk_bf16_f32 v208, v212, v213
	v_cvt_pk_bf16_f32 v209, v214, v215
	s_waitcnt lgkmcnt(1)
	v_mfma_f32_32x32x16_bf16 v[84:99], v[136:139], v[128:131], v[84:99]
	v_exp_f32_e32 v218, v218
	v_exp_f32_e32 v219, v219
	s_waitcnt lgkmcnt(0)
	v_mfma_f32_32x32x16_bf16 v[100:115], v[140:143], v[128:131], v[100:115]
	v_pk_add_f32 v[150:151], v[150:151], v[216:217]
	v_pk_add_f32 v[150:151], v[150:151], v[218:219]
	v_cvt_pk_bf16_f32 v210, v216, v217
	v_cvt_pk_bf16_f32 v211, v218, v219
	s_add_u32 s8, s8, 0x40000
	s_addc_u32 s9, s9, 0
	s_waitcnt vmcnt(4) lgkmcnt(0)
	s_barrier
	s_movk_i32 s36, 41

; #define LAS __attribute__((address_space(3)))
; #define VREADS1(arr, d_) do { const unsigned ad_ = vbase ^ (unsigned)((d_) << 6); __builtin_amdgcn_sched_barrier(0); \
;         _Pragma("unroll") for (int ks_ = 0; ks_ < 4; ++ks_) { VTR(arr[ks_ * 2], ad_, ks_ * 4096); VTR(arr[ks_ * 2 + 1], ad_, ks_ * 4096 + 2048); } __builtin_amdgcn_sched_barrier(0); } while (0)
; #define PV1(arr, d_) do { _Pragma("unroll") for (int ks_ = 0; ks_ < 4; ++ks_) { const s16x4 lo_ = arr[ks_ * 2], hh_ = arr[ks_ * 2 + 1]; \
;         const bf16x8 bv_ = (bf16x8){lo_[0], lo_[1], lo_[2], lo_[3], hh_[0], hh_[1], hh_[2], hh_[3]}; \
;         O[d_] = __builtin_amdgcn_mfma_f32_32x32x16_bf16(pa[ks_], bv_, O[d_], 0, 0, 0); } __builtin_amdgcn_sched_barrier(0); } while (0)
; __device__ __forceinline__ void attn_unit(LAS unsigned char* lds, const bf16_t* Z, bf16_t* A2, const float* tabg, int seq_base, int S, int h, int qb, float lam) {
;     ...
;             for (int ds = 0; ds < 4; ++ds) { kf[2 * ds] = *(const LAS bf16x8*)(Kt + (kfo ^ (unsigned)(ds << 5))); kf[2 * ds + 1] = *(const LAS bf16x8*)(Kt + 32 * 256 + (kfo ^ (unsigned)(ds << 5))); }
;             __builtin_amdgcn_sched_barrier(0);
;             p0 = __builtin_amdgcn_mfma_f32_32x32x16_bf16(kf[0], qf[0], cblk, 0, 0, 0);
;             p1 = __builtin_amdgcn_mfma_f32_32x32x16_bf16(kf[1], qf[0], cblk, 0, 0, 0);
; #pragma unroll
;             for (int ds = 1; ds < 4; ++ds) {
;                 p0 = __builtin_amdgcn_mfma_f32_32x32x16_bf16(kf[2 * ds], qf[ds], p0, 0, 0, 0);
;                 p1 = __builtin_amdgcn_mfma_f32_32x32x16_bf16(kf[2 * ds + 1], qf[ds], p1, 0, 0, 0);
;             }
;     ...
; #pragma unroll
;         for (int r = 0; r < 16; ++r) { p0[r] = __builtin_amdgcn_exp2f(p0[r]); p1[r] = __builtin_amdgcn_exp2f(p1[r]); }
; #pragma unroll
;         for (int r = 0; r < 16; r += 2) { ls2 += (f32x2){p0[r], p0[r + 1]}; ls2 += (f32x2){p1[r], p1[r + 1]}; }
;         bf16x8 pa[4]; pa[0] = pack8(p0, 0); pa[1] = pack8(p0, 8); pa[2] = pack8(p1, 0); pa[3] = pack8(p1, 8);
;         LGKM0(); VREADS1(vb, 1); PV1(va, 0); LGKM0(); VREADS1(va, 2); PV1(vb, 1); LGKM0(); VREADS1(vb, 3); PV1(va, 2); LGKM0(); PV1(vb, 3);
;     ...
;         if (t + 2 < NT) asm volatile("s_waitcnt vmcnt(4) lgkmcnt(0)" ::: "memory"); else asm volatile("s_waitcnt vmcnt(0) lgkmcnt(0)" ::: "memory");
;         __builtin_amdgcn_s_barrier(); asm volatile("" ::: "memory");
.LatB_rareret_m0:
	s_waitcnt lgkmcnt(12)
	v_mfma_f32_32x32x16_bf16 v[20:35], v[188:191], v[132:135], v[20:35]
	ds_read_b64_tr_b16 v[132:133], v231 offset:36864
	ds_read_b64_tr_b16 v[134:135], v231 offset:38912
	v_exp_f32_e32 v84, v84
	v_exp_f32_e32 v85, v85
	s_waitcnt lgkmcnt(12)
	v_mfma_f32_32x32x16_bf16 v[36:51], v[188:191], v[136:139], v[36:51]
	ds_read_b64_tr_b16 v[136:137], v228 offset:40960
	ds_read_b64_tr_b16 v[138:139], v228 offset:43008
	v_exp_f32_e32 v86, v86
	v_exp_f32_e32 v87, v87
	s_waitcnt lgkmcnt(12)
	v_mfma_f32_32x32x16_bf16 v[52:67], v[188:191], v[140:143], v[52:67]
	ds_read_b64_tr_b16 v[140:141], v229 offset:40960
	ds_read_b64_tr_b16 v[142:143], v229 offset:43008
	v_pk_add_f32 v[150:151], v[150:151], v[84:85]
	v_pk_add_f32 v[150:151], v[150:151], v[86:87]
	v_exp_f32_e32 v88, v88
	s_waitcnt lgkmcnt(12)
	s_mov_b32 m0, s25
	v_mfma_f32_32x32x16_bf16 v[68:83], v[188:191], v[144:147], v[68:83]
	global_load_lds_dwordx4 v236, s[8:9]
	ds_read_b64_tr_b16 v[144:145], v230 offset:40960
	ds_read_b64_tr_b16 v[146:147], v230 offset:43008
	v_exp_f32_e32 v89, v89
	v_cvt_pk_bf16_f32 v84, v84, v85
	v_cvt_pk_bf16_f32 v85, v86, v87
	s_waitcnt lgkmcnt(12)
	v_mfma_f32_32x32x16_bf16 v[20:35], v[192:195], v[220:223], v[20:35]
	ds_read_b64_tr_b16 v[220:221], v231 offset:40960
	ds_read_b64_tr_b16 v[222:223], v231 offset:43008
	v_exp_f32_e32 v90, v90
	v_exp_f32_e32 v91, v91
	s_waitcnt lgkmcnt(12)
	v_mfma_f32_32x32x16_bf16 v[36:51], v[192:195], v[224:227], v[36:51]
	ds_read_b64_tr_b16 v[224:225], v228 offset:45056
	ds_read_b64_tr_b16 v[226:227], v228 offset:47104
	v_pk_add_f32 v[150:151], v[150:151], v[88:89]
	v_pk_add_f32 v[150:151], v[150:151], v[90:91]
	v_cvt_pk_bf16_f32 v86, v88, v89
	v_cvt_pk_bf16_f32 v87, v90, v91
	s_waitcnt lgkmcnt(12)
	v_mfma_f32_32x32x16_bf16 v[52:67], v[192:195], v[232:235], v[52:67]
	ds_read_b64_tr_b16 v[232:233], v229 offset:45056
	ds_read_b64_tr_b16 v[234:235], v229 offset:47104
	v_exp_f32_e32 v92, v92
	v_exp_f32_e32 v93, v93
	s_waitcnt lgkmcnt(12)
	s_add_u32 m0, s27, 0x4000
	v_mfma_f32_32x32x16_bf16 v[68:83], v[192:195], v[132:135], v[68:83]
	global_load_lds_dwordx4 v149, s[8:9]
	ds_read_b64_tr_b16 v[132:133], v230 offset:45056
	ds_read_b64_tr_b16 v[134:135], v230 offset:47104
	v_exp_f32_e32 v94, v94
	v_exp_f32_e32 v95, v95
	s_waitcnt lgkmcnt(12)
	v_mfma_f32_32x32x16_bf16 v[20:35], v[204:207], v[136:139], v[20:35]
	ds_read_b64_tr_b16 v[136:137], v231 offset:45056
	ds_read_b64_tr_b16 v[138:139], v231 offset:47104
	v_pk_add_f32 v[150:151], v[150:151], v[92:93]
	v_pk_add_f32 v[150:151], v[150:151], v[94:95]
	v_exp_f32_e32 v96, v96
	s_waitcnt lgkmcnt(12)
	v_mfma_f32_32x32x16_bf16 v[36:51], v[204:207], v[140:143], v[36:51]
	ds_read_b128 v[140:143], v19 offset:16384
	v_exp_f32_e32 v97, v97
	v_cvt_pk_bf16_f32 v88, v92, v93
	v_cvt_pk_bf16_f32 v89, v94, v95
	s_waitcnt lgkmcnt(11)
	v_mfma_f32_32x32x16_bf16 v[52:67], v[204:207], v[144:147], v[52:67]
	ds_read_b128 v[144:147], v19 offset:24576
	v_exp_f32_e32 v98, v98
	v_exp_f32_e32 v99, v99
	s_waitcnt lgkmcnt(10)
	s_add_u32 m0, s25, 0x2000
	v_mfma_f32_32x32x16_bf16 v[68:83], v[204:207], v[220:223], v[68:83]
	global_load_lds_dwordx4 v237, s[8:9]
	ds_read_b128 v[220:223], v180 offset:16384
	v_pk_add_f32 v[150:151], v[150:151], v[96:97]
	v_pk_add_f32 v[150:151], v[150:151], v[98:99]
	v_cvt_pk_bf16_f32 v90, v96, v97
	v_cvt_pk_bf16_f32 v91, v98, v99
	s_waitcnt lgkmcnt(9)
	v_mfma_f32_32x32x16_bf16 v[20:35], v[208:211], v[224:227], v[20:35]
	ds_read_b128 v[224:227], v180 offset:24576
	v_exp_f32_e32 v100, v100
	v_exp_f32_e32 v101, v101
	s_waitcnt lgkmcnt(8)
	v_mfma_f32_32x32x16_bf16 v[36:51], v[208:211], v[232:235], v[36:51]
	ds_read_b128 v[232:235], v181 offset:16384
	v_exp_f32_e32 v102, v102
	v_exp_f32_e32 v103, v103
	s_waitcnt lgkmcnt(7)
	v_mfma_f32_32x32x16_bf16 v[52:67], v[208:211], v[132:135], v[52:67]
	ds_read_b128 v[132:135], v181 offset:24576
	v_pk_add_f32 v[150:151], v[150:151], v[100:101]
	v_pk_add_f32 v[150:151], v[150:151], v[102:103]
	v_exp_f32_e32 v104, v104
	s_waitcnt lgkmcnt(6)
	s_add_u32 m0, s27, 0x6000
	v_mfma_f32_32x32x16_bf16 v[68:83], v[208:211], v[136:139], v[68:83]
	global_load_lds_dwordx4 v176, s[8:9]
	ds_read_b128 v[136:139], v182 offset:16384
	v_exp_f32_e32 v105, v105
	v_cvt_pk_bf16_f32 v100, v100, v101
	v_cvt_pk_bf16_f32 v101, v102, v103
	s_waitcnt lgkmcnt(6)
	v_mfma_f32_32x32x16_bf16 v[188:203], v[140:143], v[116:119], v[2:17]
	ds_read_b128 v[140:143], v182 offset:24576
	v_exp_f32_e32 v106, v106
	v_exp_f32_e32 v107, v107
	s_waitcnt lgkmcnt(6)
	v_mfma_f32_32x32x16_bf16 v[204:219], v[144:147], v[116:119], v[2:17]
	v_pk_add_f32 v[150:151], v[150:151], v[104:105]
	v_pk_add_f32 v[150:151], v[150:151], v[106:107]
	v_cvt_pk_bf16_f32 v102, v104, v105
	v_cvt_pk_bf16_f32 v103, v106, v107
	s_waitcnt lgkmcnt(5)
	v_mfma_f32_32x32x16_bf16 v[188:203], v[220:223], v[120:123], v[188:203]
	v_exp_f32_e32 v108, v108
	v_exp_f32_e32 v109, v109
	s_waitcnt lgkmcnt(4)
	v_mfma_f32_32x32x16_bf16 v[204:219], v[224:227], v[120:123], v[204:219]
	v_exp_f32_e32 v110, v110
	v_exp_f32_e32 v111, v111
	s_waitcnt lgkmcnt(3)
	v_mfma_f32_32x32x16_bf16 v[188:203], v[232:235], v[124:127], v[188:203]
	v_pk_add_f32 v[150:151], v[150:151], v[108:109]
	v_pk_add_f32 v[150:151], v[150:151], v[110:111]
	v_exp_f32_e32 v112, v112
	s_waitcnt lgkmcnt(2)
	v_mfma_f32_32x32x16_bf16 v[204:219], v[132:135], v[124:127], v[204:219]
	v_exp_f32_e32 v113, v113
	v_cvt_pk_bf16_f32 v104, v108, v109
	v_cvt_pk_bf16_f32 v105, v110, v111
	s_waitcnt lgkmcnt(1)
	v_mfma_f32_32x32x16_bf16 v[188:203], v[136:139], v[128:131], v[188:203]
	v_exp_f32_e32 v114, v114
	v_exp_f32_e32 v115, v115
	s_waitcnt lgkmcnt(0)
	v_mfma_f32_32x32x16_bf16 v[204:219], v[140:143], v[128:131], v[204:219]
	v_pk_add_f32 v[150:151], v[150:151], v[112:113]
	v_pk_add_f32 v[150:151], v[150:151], v[114:115]
	v_cvt_pk_bf16_f32 v106, v112, v113
	v_cvt_pk_bf16_f32 v107, v114, v115
	s_add_u32 s8, s8, 0x40000
	s_addc_u32 s9, s9, 0
	s_waitcnt vmcnt(4) lgkmcnt(0)
	s_barrier
	s_sub_u32 s10, s10, 1
	s_cbranch_scc1 .LatB_evs_m1

; #define LAS __attribute__((address_space(3)))
; #define VREADS1(arr, d_) do { const unsigned ad_ = vbase ^ (unsigned)((d_) << 6); __builtin_amdgcn_sched_barrier(0); \
;         _Pragma("unroll") for (int ks_ = 0; ks_ < 4; ++ks_) { VTR(arr[ks_ * 2], ad_, ks_ * 4096); VTR(arr[ks_ * 2 + 1], ad_, ks_ * 4096 + 2048); } __builtin_amdgcn_sched_barrier(0); } while (0)
; #define PV1(arr, d_) do { _Pragma("unroll") for (int ks_ = 0; ks_ < 4; ++ks_) { const s16x4 lo_ = arr[ks_ * 2], hh_ = arr[ks_ * 2 + 1]; \
;         const bf16x8 bv_ = (bf16x8){lo_[0], lo_[1], lo_[2], lo_[3], hh_[0], hh_[1], hh_[2], hh_[3]}; \
;         O[d_] = __builtin_amdgcn_mfma_f32_32x32x16_bf16(pa[ks_], bv_, O[d_], 0, 0, 0); } __builtin_amdgcn_sched_barrier(0); } while (0)
; __device__ __forceinline__ void attn_unit(LAS unsigned char* lds, const bf16_t* Z, bf16_t* A2, const float* tabg, int seq_base, int S, int h, int qb, float lam) {
;     ...
;             for (int ds = 0; ds < 4; ++ds) { kf[2 * ds] = *(const LAS bf16x8*)(Kt + (kfo ^ (unsigned)(ds << 5))); kf[2 * ds + 1] = *(const LAS bf16x8*)(Kt + 32 * 256 + (kfo ^ (unsigned)(ds << 5))); }
;             __builtin_amdgcn_sched_barrier(0);
;             p0 = __builtin_amdgcn_mfma_f32_32x32x16_bf16(kf[0], qf[0], cblk, 0, 0, 0);
;             p1 = __builtin_amdgcn_mfma_f32_32x32x16_bf16(kf[1], qf[0], cblk, 0, 0, 0);
; #pragma unroll
;             for (int ds = 1; ds < 4; ++ds) {
;                 p0 = __builtin_amdgcn_mfma_f32_32x32x16_bf16(kf[2 * ds], qf[ds], p0, 0, 0, 0);
;                 p1 = __builtin_amdgcn_mfma_f32_32x32x16_bf16(kf[2 * ds + 1], qf[ds], p1, 0, 0, 0);
;             }
;     ...
; #pragma unroll
;         for (int r = 0; r < 16; ++r) { p0[r] = __builtin_amdgcn_exp2f(p0[r]); p1[r] = __builtin_amdgcn_exp2f(p1[r]); }
; #pragma unroll
;         for (int r = 0; r < 16; r += 2) { ls2 += (f32x2){p0[r], p0[r + 1]}; ls2 += (f32x2){p1[r], p1[r + 1]}; }
;         bf16x8 pa[4]; pa[0] = pack8(p0, 0); pa[1] = pack8(p0, 8); pa[2] = pack8(p1, 0); pa[3] = pack8(p1, 8);
;         LGKM0(); VREADS1(vb, 1); PV1(va, 0); LGKM0(); VREADS1(va, 2); PV1(vb, 1); LGKM0(); VREADS1(vb, 3); PV1(va, 2); LGKM0(); PV1(vb, 3);
;     ...
;         if (t + 2 < NT) asm volatile("s_waitcnt vmcnt(4) lgkmcnt(0)" ::: "memory"); else asm volatile("s_waitcnt vmcnt(0) lgkmcnt(0)" ::: "memory");
;         __builtin_amdgcn_s_barrier(); asm volatile("" ::: "memory");
.LatB_rareret_m5:
	s_waitcnt lgkmcnt(12)
	v_mfma_f32_32x32x16_bf16 v[20:35], v[84:87], v[132:135], v[20:35]
	ds_read_b64_tr_b16 v[132:133], v231 offset:20480
	ds_read_b64_tr_b16 v[134:135], v231 offset:22528
	v_exp_f32_e32 v188, v188
	v_exp_f32_e32 v189, v189
	s_waitcnt lgkmcnt(12)
	v_mfma_f32_32x32x16_bf16 v[36:51], v[84:87], v[136:139], v[36:51]
	ds_read_b64_tr_b16 v[136:137], v228 offset:24576
	ds_read_b64_tr_b16 v[138:139], v228 offset:26624
	v_exp_f32_e32 v190, v190
	v_exp_f32_e32 v191, v191
	s_waitcnt lgkmcnt(12)
	v_mfma_f32_32x32x16_bf16 v[52:67], v[84:87], v[140:143], v[52:67]
	ds_read_b64_tr_b16 v[140:141], v229 offset:24576
	ds_read_b64_tr_b16 v[142:143], v229 offset:26624
	v_pk_add_f32 v[150:151], v[150:151], v[188:189]
	v_pk_add_f32 v[150:151], v[150:151], v[190:191]
	v_exp_f32_e32 v192, v192
	s_waitcnt lgkmcnt(12)
	s_add_u32 m0, s25, 0x8000
	v_mfma_f32_32x32x16_bf16 v[68:83], v[84:87], v[144:147], v[68:83]
	global_load_lds_dwordx4 v236, s[8:9]
	ds_read_b64_tr_b16 v[144:145], v230 offset:24576
	ds_read_b64_tr_b16 v[146:147], v230 offset:26624
	v_exp_f32_e32 v193, v193
	v_cvt_pk_bf16_f32 v188, v188, v189
	v_cvt_pk_bf16_f32 v189, v190, v191
	s_waitcnt lgkmcnt(12)
	v_mfma_f32_32x32x16_bf16 v[20:35], v[88:91], v[220:223], v[20:35]
	ds_read_b64_tr_b16 v[220:221], v231 offset:24576
	ds_read_b64_tr_b16 v[222:223], v231 offset:26624
	v_exp_f32_e32 v194, v194
	v_exp_f32_e32 v195, v195
	s_waitcnt lgkmcnt(12)
	v_mfma_f32_32x32x16_bf16 v[36:51], v[88:91], v[224:227], v[36:51]
	ds_read_b64_tr_b16 v[224:225], v228 offset:28672
	ds_read_b64_tr_b16 v[226:227], v228 offset:30720
	v_pk_add_f32 v[150:151], v[150:151], v[192:193]
	v_pk_add_f32 v[150:151], v[150:151], v[194:195]
	v_cvt_pk_bf16_f32 v190, v192, v193
	v_cvt_pk_bf16_f32 v191, v194, v195
	s_waitcnt lgkmcnt(12)
	v_mfma_f32_32x32x16_bf16 v[52:67], v[88:91], v[232:235], v[52:67]
	ds_read_b64_tr_b16 v[232:233], v229 offset:28672
	ds_read_b64_tr_b16 v[234:235], v229 offset:30720
	v_exp_f32_e32 v196, v196
	v_exp_f32_e32 v197, v197
	s_waitcnt lgkmcnt(12)
	s_mov_b32 m0, s27
	v_mfma_f32_32x32x16_bf16 v[68:83], v[88:91], v[132:135], v[68:83]
	global_load_lds_dwordx4 v149, s[8:9]
	ds_read_b64_tr_b16 v[132:133], v230 offset:28672
	ds_read_b64_tr_b16 v[134:135], v230 offset:30720
	v_exp_f32_e32 v198, v198
	v_exp_f32_e32 v199, v199
	s_waitcnt lgkmcnt(12)
	v_mfma_f32_32x32x16_bf16 v[20:35], v[100:103], v[136:139], v[20:35]
	ds_read_b64_tr_b16 v[136:137], v231 offset:28672
	ds_read_b64_tr_b16 v[138:139], v231 offset:30720
	v_pk_add_f32 v[150:151], v[150:151], v[196:197]
	v_pk_add_f32 v[150:151], v[150:151], v[198:199]
	v_exp_f32_e32 v200, v200
	s_waitcnt lgkmcnt(12)
	v_mfma_f32_32x32x16_bf16 v[36:51], v[100:103], v[140:143], v[36:51]
	ds_read_b128 v[140:143], v19
	v_exp_f32_e32 v201, v201
	v_cvt_pk_bf16_f32 v192, v196, v197
	v_cvt_pk_bf16_f32 v193, v198, v199
	s_waitcnt lgkmcnt(11)
	v_mfma_f32_32x32x16_bf16 v[52:67], v[100:103], v[144:147], v[52:67]
	ds_read_b128 v[144:147], v19 offset:8192
	v_exp_f32_e32 v202, v202
	v_exp_f32_e32 v203, v203
	s_waitcnt lgkmcnt(10)
	s_add_u32 m0, s25, 0xa000
	v_mfma_f32_32x32x16_bf16 v[68:83], v[100:103], v[220:223], v[68:83]
	global_load_lds_dwordx4 v237, s[8:9]
	ds_read_b128 v[220:223], v180
	v_pk_add_f32 v[150:151], v[150:151], v[200:201]
	v_pk_add_f32 v[150:151], v[150:151], v[202:203]
	v_cvt_pk_bf16_f32 v194, v200, v201
	v_cvt_pk_bf16_f32 v195, v202, v203
	s_waitcnt lgkmcnt(9)
	v_mfma_f32_32x32x16_bf16 v[20:35], v[104:107], v[224:227], v[20:35]
	ds_read_b128 v[224:227], v180 offset:8192
	v_exp_f32_e32 v204, v204
	v_exp_f32_e32 v205, v205
	s_waitcnt lgkmcnt(8)
	v_mfma_f32_32x32x16_bf16 v[36:51], v[104:107], v[232:235], v[36:51]
	ds_read_b128 v[232:235], v181
	v_exp_f32_e32 v206, v206
	v_exp_f32_e32 v207, v207
	s_waitcnt lgkmcnt(7)
	v_mfma_f32_32x32x16_bf16 v[52:67], v[104:107], v[132:135], v[52:67]
	ds_read_b128 v[132:135], v181 offset:8192
	v_pk_add_f32 v[150:151], v[150:151], v[204:205]
	v_pk_add_f32 v[150:151], v[150:151], v[206:207]
	v_exp_f32_e32 v208, v208
	s_waitcnt lgkmcnt(6)
	s_add_u32 m0, s27, 0x2000
	v_mfma_f32_32x32x16_bf16 v[68:83], v[104:107], v[136:139], v[68:83]
	global_load_lds_dwordx4 v176, s[8:9]
	ds_read_b128 v[136:139], v182
	v_exp_f32_e32 v209, v209
	v_cvt_pk_bf16_f32 v204, v204, v205
	v_cvt_pk_bf16_f32 v205, v206, v207
	s_waitcnt lgkmcnt(6)
	v_mfma_f32_32x32x16_bf16 v[84:99], v[140:143], v[116:119], v[2:17]
	ds_read_b128 v[140:143], v182 offset:8192
	v_exp_f32_e32 v210, v210
	v_exp_f32_e32 v211, v211
	s_waitcnt lgkmcnt(6)
	v_mfma_f32_32x32x16_bf16 v[100:115], v[144:147], v[116:119], v[2:17]
	v_pk_add_f32 v[150:151], v[150:151], v[208:209]
	v_pk_add_f32 v[150:151], v[150:151], v[210:211]
	v_cvt_pk_bf16_f32 v206, v208, v209
	v_cvt_pk_bf16_f32 v207, v210, v211
	s_waitcnt lgkmcnt(5)
	v_mfma_f32_32x32x16_bf16 v[84:99], v[220:223], v[120:123], v[84:99]
	v_exp_f32_e32 v212, v212
	v_exp_f32_e32 v213, v213
	s_waitcnt lgkmcnt(4)
	v_mfma_f32_32x32x16_bf16 v[100:115], v[224:227], v[120:123], v[100:115]
	v_exp_f32_e32 v214, v214
	v_exp_f32_e32 v215, v215
	s_waitcnt lgkmcnt(3)
	v_mfma_f32_32x32x16_bf16 v[84:99], v[232:235], v[124:127], v[84:99]
	v_pk_add_f32 v[150:151], v[150:151], v[212:213]
	v_pk_add_f32 v[150:151], v[150:151], v[214:215]
	v_exp_f32_e32 v216, v216
	s_waitcnt lgkmcnt(2)
	v_mfma_f32_32x32x16_bf16 v[100:115], v[132:135], v[124:127], v[100:115]
	v_exp_f32_e32 v217, v217
	v_cvt_pk_bf16_f32 v208, v212, v213
	v_cvt_pk_bf16_f32 v209, v214, v215
	s_waitcnt lgkmcnt(1)
	v_mfma_f32_32x32x16_bf16 v[84:99], v[136:139], v[128:131], v[84:99]
	v_exp_f32_e32 v218, v218
	v_exp_f32_e32 v219, v219
	s_waitcnt lgkmcnt(0)
	v_mfma_f32_32x32x16_bf16 v[100:115], v[140:143], v[128:131], v[100:115]
	v_pk_add_f32 v[150:151], v[150:151], v[216:217]
	v_pk_add_f32 v[150:151], v[150:151], v[218:219]
	v_cvt_pk_bf16_f32 v210, v216, v217
	v_cvt_pk_bf16_f32 v211, v218, v219
	s_add_u32 s8, s8, 0x40000
	s_addc_u32 s9, s9, 0
	s_waitcnt vmcnt(4) lgkmcnt(0)
	s_barrier
	s_sub_u32 s36, s36, 1
	s_cmp_lg_u32 s36, 0
	s_cbranch_scc1 .LatB_loop
	s_sub_u32 s10, s10, 1
	s_cbranch_scc1 .LatB_evs_x4

; #define LAS __attribute__((address_space(3)))
; #define VREADS1(arr, d_) do { const unsigned ad_ = vbase ^ (unsigned)((d_) << 6); __builtin_amdgcn_sched_barrier(0); \
;         _Pragma("unroll") for (int ks_ = 0; ks_ < 4; ++ks_) { VTR(arr[ks_ * 2], ad_, ks_ * 4096); VTR(arr[ks_ * 2 + 1], ad_, ks_ * 4096 + 2048); } __builtin_amdgcn_sched_barrier(0); } while (0)
; #define PV1(arr, d_) do { _Pragma("unroll") for (int ks_ = 0; ks_ < 4; ++ks_) { const s16x4 lo_ = arr[ks_ * 2], hh_ = arr[ks_ * 2 + 1]; \
;         const bf16x8 bv_ = (bf16x8){lo_[0], lo_[1], lo_[2], lo_[3], hh_[0], hh_[1], hh_[2], hh_[3]}; \
;         O[d_] = __builtin_amdgcn_mfma_f32_32x32x16_bf16(pa[ks_], bv_, O[d_], 0, 0, 0); } __builtin_amdgcn_sched_barrier(0); } while (0)
; __device__ __forceinline__ void attn_unit(LAS unsigned char* lds, const bf16_t* Z, bf16_t* A2, const float* tabg, int seq_base, int S, int h, int qb, float lam) {
;     ...
;             for (int ds = 0; ds < 4; ++ds) { kf[2 * ds] = *(const LAS bf16x8*)(Kt + (kfo ^ (unsigned)(ds << 5))); kf[2 * ds + 1] = *(const LAS bf16x8*)(Kt + 32 * 256 + (kfo ^ (unsigned)(ds << 5))); }
;             __builtin_amdgcn_sched_barrier(0);
;             p0 = __builtin_amdgcn_mfma_f32_32x32x16_bf16(kf[0], qf[0], cblk, 0, 0, 0);
;             p1 = __builtin_amdgcn_mfma_f32_32x32x16_bf16(kf[1], qf[0], cblk, 0, 0, 0);
; #pragma unroll
;             for (int ds = 1; ds < 4; ++ds) {
;                 p0 = __builtin_amdgcn_mfma_f32_32x32x16_bf16(kf[2 * ds], qf[ds], p0, 0, 0, 0);
;                 p1 = __builtin_amdgcn_mfma_f32_32x32x16_bf16(kf[2 * ds + 1], qf[ds], p1, 0, 0, 0);
;             }
;     ...
; #pragma unroll
;         for (int r = 0; r < 16; ++r) { p0[r] = __builtin_amdgcn_exp2f(p0[r]); p1[r] = __builtin_amdgcn_exp2f(p1[r]); }
; #pragma unroll
;         for (int r = 0; r < 16; r += 2) { ls2 += (f32x2){p0[r], p0[r + 1]}; ls2 += (f32x2){p1[r], p1[r + 1]}; }
;         bf16x8 pa[4]; pa[0] = pack8(p0, 0); pa[1] = pack8(p0, 8); pa[2] = pack8(p1, 0); pa[3] = pack8(p1, 8);
;         LGKM0(); VREADS1(vb, 1); PV1(va, 0); LGKM0(); VREADS1(va, 2); PV1(vb, 1); LGKM0(); VREADS1(vb, 3); PV1(va, 2); LGKM0(); PV1(vb, 3);
;     ...
;         if (t + 2 < NT) asm volatile("s_waitcnt vmcnt(4) lgkmcnt(0)" ::: "memory"); else asm volatile("s_waitcnt vmcnt(0) lgkmcnt(0)" ::: "memory");
;         __builtin_amdgcn_s_barrier(); asm volatile("" ::: "memory");
.LatB_rareret_x3:
	s_waitcnt lgkmcnt(12)
	v_mfma_f32_32x32x16_bf16 v[20:35], v[84:87], v[132:135], v[20:35]
	ds_read_b64_tr_b16 v[132:133], v231 offset:4096
	ds_read_b64_tr_b16 v[134:135], v231 offset:6144
	v_exp_f32_e32 v188, v188
	v_exp_f32_e32 v189, v189
	s_waitcnt lgkmcnt(12)
	v_mfma_f32_32x32x16_bf16 v[36:51], v[84:87], v[136:139], v[36:51]
	ds_read_b64_tr_b16 v[136:137], v228 offset:8192
	ds_read_b64_tr_b16 v[138:139], v228 offset:10240
	v_exp_f32_e32 v190, v190
	v_exp_f32_e32 v191, v191
	s_waitcnt lgkmcnt(12)
	v_mfma_f32_32x32x16_bf16 v[52:67], v[84:87], v[140:143], v[52:67]
	ds_read_b64_tr_b16 v[140:141], v229 offset:8192
	ds_read_b64_tr_b16 v[142:143], v229 offset:10240
	v_pk_add_f32 v[150:151], v[150:151], v[188:189]
	v_pk_add_f32 v[150:151], v[150:151], v[190:191]
	v_exp_f32_e32 v192, v192
	s_waitcnt lgkmcnt(12)
	v_mfma_f32_32x32x16_bf16 v[68:83], v[84:87], v[144:147], v[68:83]
	ds_read_b64_tr_b16 v[144:145], v230 offset:8192
	ds_read_b64_tr_b16 v[146:147], v230 offset:10240
	v_exp_f32_e32 v193, v193
	v_cvt_pk_bf16_f32 v188, v188, v189
	v_cvt_pk_bf16_f32 v189, v190, v191
	s_waitcnt lgkmcnt(12)
	v_mfma_f32_32x32x16_bf16 v[20:35], v[88:91], v[220:223], v[20:35]
	ds_read_b64_tr_b16 v[220:221], v231 offset:8192
	ds_read_b64_tr_b16 v[222:223], v231 offset:10240
	v_exp_f32_e32 v194, v194
	v_exp_f32_e32 v195, v195
	s_waitcnt lgkmcnt(12)
	v_mfma_f32_32x32x16_bf16 v[36:51], v[88:91], v[224:227], v[36:51]
	ds_read_b64_tr_b16 v[224:225], v228 offset:12288
	ds_read_b64_tr_b16 v[226:227], v228 offset:14336
	v_pk_add_f32 v[150:151], v[150:151], v[192:193]
	v_pk_add_f32 v[150:151], v[150:151], v[194:195]
	v_cvt_pk_bf16_f32 v190, v192, v193
	v_cvt_pk_bf16_f32 v191, v194, v195
	s_waitcnt lgkmcnt(12)
	v_mfma_f32_32x32x16_bf16 v[52:67], v[88:91], v[232:235], v[52:67]
	ds_read_b64_tr_b16 v[232:233], v229 offset:12288
	ds_read_b64_tr_b16 v[234:235], v229 offset:14336
	v_exp_f32_e32 v196, v196
	v_exp_f32_e32 v197, v197
	s_waitcnt lgkmcnt(12)
	s_add_u32 m0, s27, 0x8000
	v_mfma_f32_32x32x16_bf16 v[68:83], v[88:91], v[132:135], v[68:83]
	global_load_lds_dwordx4 v149, s[8:9]
	ds_read_b64_tr_b16 v[132:133], v230 offset:12288
	ds_read_b64_tr_b16 v[134:135], v230 offset:14336
	v_exp_f32_e32 v198, v198
	v_exp_f32_e32 v199, v199
	s_waitcnt lgkmcnt(12)
	v_mfma_f32_32x32x16_bf16 v[20:35], v[100:103], v[136:139], v[20:35]
	ds_read_b64_tr_b16 v[136:137], v231 offset:12288
	ds_read_b64_tr_b16 v[138:139], v231 offset:14336
	v_pk_add_f32 v[150:151], v[150:151], v[196:197]
	v_pk_add_f32 v[150:151], v[150:151], v[198:199]
	v_exp_f32_e32 v200, v200
	s_waitcnt lgkmcnt(12)
	v_mfma_f32_32x32x16_bf16 v[36:51], v[100:103], v[140:143], v[36:51]
	ds_read_b128 v[140:143], v19 offset:32768
	v_exp_f32_e32 v201, v201
	v_cvt_pk_bf16_f32 v192, v196, v197
	v_cvt_pk_bf16_f32 v193, v198, v199
	s_waitcnt lgkmcnt(11)
	v_mfma_f32_32x32x16_bf16 v[52:67], v[100:103], v[144:147], v[52:67]
	ds_read_b128 v[144:147], v19 offset:40960
	v_exp_f32_e32 v202, v202
	v_exp_f32_e32 v203, v203
	s_waitcnt lgkmcnt(10)
	v_mfma_f32_32x32x16_bf16 v[68:83], v[100:103], v[220:223], v[68:83]
	ds_read_b128 v[220:223], v180 offset:32768
	v_pk_add_f32 v[150:151], v[150:151], v[200:201]
	v_pk_add_f32 v[150:151], v[150:151], v[202:203]
	v_cvt_pk_bf16_f32 v194, v200, v201
	v_cvt_pk_bf16_f32 v195, v202, v203
	s_waitcnt lgkmcnt(9)
	v_mfma_f32_32x32x16_bf16 v[20:35], v[104:107], v[224:227], v[20:35]
	ds_read_b128 v[224:227], v180 offset:40960
	v_exp_f32_e32 v204, v204
	v_exp_f32_e32 v205, v205
	s_waitcnt lgkmcnt(8)
	v_mfma_f32_32x32x16_bf16 v[36:51], v[104:107], v[232:235], v[36:51]
	ds_read_b128 v[232:235], v181 offset:32768
	v_exp_f32_e32 v206, v206
	v_exp_f32_e32 v207, v207
	s_waitcnt lgkmcnt(7)
	v_mfma_f32_32x32x16_bf16 v[52:67], v[104:107], v[132:135], v[52:67]
	ds_read_b128 v[132:135], v181 offset:40960
	v_pk_add_f32 v[150:151], v[150:151], v[204:205]
	v_pk_add_f32 v[150:151], v[150:151], v[206:207]
	v_exp_f32_e32 v208, v208
	s_waitcnt lgkmcnt(6)
	s_add_u32 m0, s27, 0xa000
	v_mfma_f32_32x32x16_bf16 v[68:83], v[104:107], v[136:139], v[68:83]
	global_load_lds_dwordx4 v176, s[8:9]
	ds_read_b128 v[136:139], v182 offset:32768
	v_exp_f32_e32 v209, v209
	v_cvt_pk_bf16_f32 v204, v204, v205
	v_cvt_pk_bf16_f32 v205, v206, v207
	s_waitcnt lgkmcnt(6)
	v_mfma_f32_32x32x16_bf16 v[84:99], v[140:143], v[116:119], v[2:17]
	ds_read_b128 v[140:143], v182 offset:40960
	v_exp_f32_e32 v210, v210
	v_exp_f32_e32 v211, v211
	s_waitcnt lgkmcnt(6)
	v_mfma_f32_32x32x16_bf16 v[100:115], v[144:147], v[116:119], v[2:17]
	v_pk_add_f32 v[150:151], v[150:151], v[208:209]
	v_pk_add_f32 v[150:151], v[150:151], v[210:211]
	v_cvt_pk_bf16_f32 v206, v208, v209
	v_cvt_pk_bf16_f32 v207, v210, v211
	s_waitcnt lgkmcnt(5)
	v_mfma_f32_32x32x16_bf16 v[84:99], v[220:223], v[120:123], v[84:99]
	v_exp_f32_e32 v212, v212
	v_exp_f32_e32 v213, v213
	s_waitcnt lgkmcnt(4)
	v_mfma_f32_32x32x16_bf16 v[100:115], v[224:227], v[120:123], v[100:115]
	v_exp_f32_e32 v214, v214
	v_exp_f32_e32 v215, v215
	s_waitcnt lgkmcnt(3)
	v_mfma_f32_32x32x16_bf16 v[84:99], v[232:235], v[124:127], v[84:99]
	v_pk_add_f32 v[150:151], v[150:151], v[212:213]
	v_pk_add_f32 v[150:151], v[150:151], v[214:215]
	v_exp_f32_e32 v216, v216
	s_waitcnt lgkmcnt(2)
	v_mfma_f32_32x32x16_bf16 v[100:115], v[132:135], v[124:127], v[100:115]
	v_exp_f32_e32 v217, v217
	v_cvt_pk_bf16_f32 v208, v212, v213
	v_cvt_pk_bf16_f32 v209, v214, v215
	s_waitcnt lgkmcnt(1)
	v_mfma_f32_32x32x16_bf16 v[84:99], v[136:139], v[128:131], v[84:99]
	v_exp_f32_e32 v218, v218
	v_exp_f32_e32 v219, v219
	s_waitcnt lgkmcnt(0)
	v_mfma_f32_32x32x16_bf16 v[100:115], v[140:143], v[128:131], v[100:115]
	v_pk_add_f32 v[150:151], v[150:151], v[216:217]
	v_pk_add_f32 v[150:151], v[150:151], v[218:219]
	v_cvt_pk_bf16_f32 v210, v216, v217
	v_cvt_pk_bf16_f32 v211, v218, v219
	s_add_u32 s8, s8, 0x40000
	s_addc_u32 s9, s9, 0
	s_waitcnt vmcnt(2) lgkmcnt(0)
	s_barrier
	s_sub_u32 s10, s10, 1
	s_cbranch_scc1 .LatB_evs_x2

; #define LAS __attribute__((address_space(3)))
; #define VREADS1(arr, d_) do { const unsigned ad_ = vbase ^ (unsigned)((d_) << 6); __builtin_amdgcn_sched_barrier(0); \
;         _Pragma("unroll") for (int ks_ = 0; ks_ < 4; ++ks_) { VTR(arr[ks_ * 2], ad_, ks_ * 4096); VTR(arr[ks_ * 2 + 1], ad_, ks_ * 4096 + 2048); } __builtin_amdgcn_sched_barrier(0); } while (0)
; #define PV1(arr, d_) do { _Pragma("unroll") for (int ks_ = 0; ks_ < 4; ++ks_) { const s16x4 lo_ = arr[ks_ * 2], hh_ = arr[ks_ * 2 + 1]; \
;         const bf16x8 bv_ = (bf16x8){lo_[0], lo_[1], lo_[2], lo_[3], hh_[0], hh_[1], hh_[2], hh_[3]}; \
;         O[d_] = __builtin_amdgcn_mfma_f32_32x32x16_bf16(pa[ks_], bv_, O[d_], 0, 0, 0); } __builtin_amdgcn_sched_barrier(0); } while (0)
; __device__ __forceinline__ void attn_unit(LAS unsigned char* lds, const bf16_t* Z, bf16_t* A2, const float* tabg, int seq_base, int S, int h, int qb, float lam) {
;     ...
;             for (int ds = 0; ds < 4; ++ds) { kf[2 * ds] = *(const LAS bf16x8*)(Kt + (kfo ^ (unsigned)(ds << 5))); kf[2 * ds + 1] = *(const LAS bf16x8*)(Kt + 32 * 256 + (kfo ^ (unsigned)(ds << 5))); }
;             __builtin_amdgcn_sched_barrier(0);
;             p0 = __builtin_amdgcn_mfma_f32_32x32x16_bf16(kf[0], qf[0], cblk, 0, 0, 0);
;             p1 = __builtin_amdgcn_mfma_f32_32x32x16_bf16(kf[1], qf[0], cblk, 0, 0, 0);
; #pragma unroll
;             for (int ds = 1; ds < 4; ++ds) {
;                 p0 = __builtin_amdgcn_mfma_f32_32x32x16_bf16(kf[2 * ds], qf[ds], p0, 0, 0, 0);
;                 p1 = __builtin_amdgcn_mfma_f32_32x32x16_bf16(kf[2 * ds + 1], qf[ds], p1, 0, 0, 0);
;             }
;     ...
; #pragma unroll
;         for (int r = 0; r < 16; ++r) { p0[r] = __builtin_amdgcn_exp2f(p0[r]); p1[r] = __builtin_amdgcn_exp2f(p1[r]); }
; #pragma unroll
;         for (int r = 0; r < 16; r += 2) { ls2 += (f32x2){p0[r], p0[r + 1]}; ls2 += (f32x2){p1[r], p1[r + 1]}; }
;         bf16x8 pa[4]; pa[0] = pack8(p0, 0); pa[1] = pack8(p0, 8); pa[2] = pack8(p1, 0); pa[3] = pack8(p1, 8);
;         LGKM0(); VREADS1(vb, 1); PV1(va, 0); LGKM0(); VREADS1(va, 2); PV1(vb, 1); LGKM0(); VREADS1(vb, 3); PV1(va, 2); LGKM0(); PV1(vb, 3);
;     ...
;         if (t + 2 < NT) asm volatile("s_waitcnt vmcnt(4) lgkmcnt(0)" ::: "memory"); else asm volatile("s_waitcnt vmcnt(0) lgkmcnt(0)" ::: "memory");
;         __builtin_amdgcn_s_barrier(); asm volatile("" ::: "memory");
.LatB_rareret_x2:
	s_waitcnt lgkmcnt(12)
	v_mfma_f32_32x32x16_bf16 v[20:35], v[188:191], v[132:135], v[20:35]
	ds_read_b64_tr_b16 v[132:133], v231 offset:20480
	ds_read_b64_tr_b16 v[134:135], v231 offset:22528
	v_exp_f32_e32 v84, v84
	v_exp_f32_e32 v85, v85
	s_waitcnt lgkmcnt(12)
	v_mfma_f32_32x32x16_bf16 v[36:51], v[188:191], v[136:139], v[36:51]
	ds_read_b64_tr_b16 v[136:137], v228 offset:24576
	ds_read_b64_tr_b16 v[138:139], v228 offset:26624
	v_exp_f32_e32 v86, v86
	v_exp_f32_e32 v87, v87
	s_waitcnt lgkmcnt(12)
	v_mfma_f32_32x32x16_bf16 v[52:67], v[188:191], v[140:143], v[52:67]
	ds_read_b64_tr_b16 v[140:141], v229 offset:24576
	ds_read_b64_tr_b16 v[142:143], v229 offset:26624
	v_pk_add_f32 v[150:151], v[150:151], v[84:85]
	v_pk_add_f32 v[150:151], v[150:151], v[86:87]
	v_exp_f32_e32 v88, v88
	s_waitcnt lgkmcnt(12)
	v_mfma_f32_32x32x16_bf16 v[68:83], v[188:191], v[144:147], v[68:83]
	ds_read_b64_tr_b16 v[144:145], v230 offset:24576
	ds_read_b64_tr_b16 v[146:147], v230 offset:26624
	v_exp_f32_e32 v89, v89
	v_cvt_pk_bf16_f32 v84, v84, v85
	v_cvt_pk_bf16_f32 v85, v86, v87
	s_waitcnt lgkmcnt(12)
	v_mfma_f32_32x32x16_bf16 v[20:35], v[192:195], v[220:223], v[20:35]
	ds_read_b64_tr_b16 v[220:221], v231 offset:24576
	ds_read_b64_tr_b16 v[222:223], v231 offset:26624
	v_exp_f32_e32 v90, v90
	v_exp_f32_e32 v91, v91
	s_waitcnt lgkmcnt(12)
	v_mfma_f32_32x32x16_bf16 v[36:51], v[192:195], v[224:227], v[36:51]
	ds_read_b64_tr_b16 v[224:225], v228 offset:28672
	ds_read_b64_tr_b16 v[226:227], v228 offset:30720
	v_pk_add_f32 v[150:151], v[150:151], v[88:89]
	v_pk_add_f32 v[150:151], v[150:151], v[90:91]
	v_cvt_pk_bf16_f32 v86, v88, v89
	v_cvt_pk_bf16_f32 v87, v90, v91
	s_waitcnt lgkmcnt(12)
	v_mfma_f32_32x32x16_bf16 v[52:67], v[192:195], v[232:235], v[52:67]
	ds_read_b64_tr_b16 v[232:233], v229 offset:28672
	ds_read_b64_tr_b16 v[234:235], v229 offset:30720
	v_exp_f32_e32 v92, v92
	v_exp_f32_e32 v93, v93
	s_waitcnt lgkmcnt(12)
	s_mov_b32 m0, s27
	v_mfma_f32_32x32x16_bf16 v[68:83], v[192:195], v[132:135], v[68:83]
	global_load_lds_dwordx4 v149, s[8:9]
	ds_read_b64_tr_b16 v[132:133], v230 offset:28672
	ds_read_b64_tr_b16 v[134:135], v230 offset:30720
	v_exp_f32_e32 v94, v94
	v_exp_f32_e32 v95, v95
	s_waitcnt lgkmcnt(12)
	v_mfma_f32_32x32x16_bf16 v[20:35], v[204:207], v[136:139], v[20:35]
	ds_read_b64_tr_b16 v[136:137], v231 offset:28672
	ds_read_b64_tr_b16 v[138:139], v231 offset:30720
	v_pk_add_f32 v[150:151], v[150:151], v[92:93]
	v_pk_add_f32 v[150:151], v[150:151], v[94:95]
	v_exp_f32_e32 v96, v96
	s_waitcnt lgkmcnt(12)
	v_mfma_f32_32x32x16_bf16 v[36:51], v[204:207], v[140:143], v[36:51]
	ds_read_b128 v[140:143], v19
	v_exp_f32_e32 v97, v97
	v_cvt_pk_bf16_f32 v88, v92, v93
	v_cvt_pk_bf16_f32 v89, v94, v95
	s_waitcnt lgkmcnt(11)
	v_mfma_f32_32x32x16_bf16 v[52:67], v[204:207], v[144:147], v[52:67]
	ds_read_b128 v[144:147], v19 offset:8192
	v_exp_f32_e32 v98, v98
	v_exp_f32_e32 v99, v99
	s_waitcnt lgkmcnt(10)
	v_mfma_f32_32x32x16_bf16 v[68:83], v[204:207], v[220:223], v[68:83]
	ds_read_b128 v[220:223], v180
	v_pk_add_f32 v[150:151], v[150:151], v[96:97]
	v_pk_add_f32 v[150:151], v[150:151], v[98:99]
	v_cvt_pk_bf16_f32 v90, v96, v97
	v_cvt_pk_bf16_f32 v91, v98, v99
	s_waitcnt lgkmcnt(9)
	v_mfma_f32_32x32x16_bf16 v[20:35], v[208:211], v[224:227], v[20:35]
	ds_read_b128 v[224:227], v180 offset:8192
	v_exp_f32_e32 v100, v100
	v_exp_f32_e32 v101, v101
	s_waitcnt lgkmcnt(8)
	v_mfma_f32_32x32x16_bf16 v[36:51], v[208:211], v[232:235], v[36:51]
	ds_read_b128 v[232:235], v181
	v_exp_f32_e32 v102, v102
	v_exp_f32_e32 v103, v103
	s_waitcnt lgkmcnt(7)
	v_mfma_f32_32x32x16_bf16 v[52:67], v[208:211], v[132:135], v[52:67]
	ds_read_b128 v[132:135], v181 offset:8192
	v_pk_add_f32 v[150:151], v[150:151], v[100:101]
	v_pk_add_f32 v[150:151], v[150:151], v[102:103]
	v_exp_f32_e32 v104, v104
	s_waitcnt lgkmcnt(6)
	s_add_u32 m0, s27, 0x2000
	v_mfma_f32_32x32x16_bf16 v[68:83], v[208:211], v[136:139], v[68:83]
	global_load_lds_dwordx4 v176, s[8:9]
	ds_read_b128 v[136:139], v182
	v_exp_f32_e32 v105, v105
	v_cvt_pk_bf16_f32 v100, v100, v101
	v_cvt_pk_bf16_f32 v101, v102, v103
	s_waitcnt lgkmcnt(6)
	v_mfma_f32_32x32x16_bf16 v[188:203], v[140:143], v[116:119], v[2:17]
	ds_read_b128 v[140:143], v182 offset:8192
	v_exp_f32_e32 v106, v106
	v_exp_f32_e32 v107, v107
	s_waitcnt lgkmcnt(6)
	v_mfma_f32_32x32x16_bf16 v[204:219], v[144:147], v[116:119], v[2:17]
	v_pk_add_f32 v[150:151], v[150:151], v[104:105]
	v_pk_add_f32 v[150:151], v[150:151], v[106:107]
	v_cvt_pk_bf16_f32 v102, v104, v105
	v_cvt_pk_bf16_f32 v103, v106, v107
	s_waitcnt lgkmcnt(5)
	v_mfma_f32_32x32x16_bf16 v[188:203], v[220:223], v[120:123], v[188:203]
	v_exp_f32_e32 v108, v108
	v_exp_f32_e32 v109, v109
	s_waitcnt lgkmcnt(4)
	v_mfma_f32_32x32x16_bf16 v[204:219], v[224:227], v[120:123], v[204:219]
	v_exp_f32_e32 v110, v110
	v_exp_f32_e32 v111, v111
	s_waitcnt lgkmcnt(3)
	v_mfma_f32_32x32x16_bf16 v[188:203], v[232:235], v[124:127], v[188:203]
	v_pk_add_f32 v[150:151], v[150:151], v[108:109]
	v_pk_add_f32 v[150:151], v[150:151], v[110:111]
	v_exp_f32_e32 v112, v112
	s_waitcnt lgkmcnt(2)
	v_mfma_f32_32x32x16_bf16 v[204:219], v[132:135], v[124:127], v[204:219]
	v_exp_f32_e32 v113, v113
	v_cvt_pk_bf16_f32 v104, v108, v109
	v_cvt_pk_bf16_f32 v105, v110, v111
	s_waitcnt lgkmcnt(1)
	v_mfma_f32_32x32x16_bf16 v[188:203], v[136:139], v[128:131], v[188:203]
	v_exp_f32_e32 v114, v114
	v_exp_f32_e32 v115, v115
	s_waitcnt lgkmcnt(0)
	v_mfma_f32_32x32x16_bf16 v[204:219], v[140:143], v[128:131], v[204:219]
	v_pk_add_f32 v[150:151], v[150:151], v[112:113]
	v_pk_add_f32 v[150:151], v[150:151], v[114:115]
	v_cvt_pk_bf16_f32 v106, v112, v113
	v_cvt_pk_bf16_f32 v107, v114, v115
	s_add_u32 s8, s8, 0x40000
	s_addc_u32 s9, s9, 0
	s_waitcnt vmcnt(2) lgkmcnt(0)
	s_barrier
	s_sub_u32 s10, s10, 1
	s_cbranch_scc1 .LatB_evs_x1

; #define VREADS1(arr, d_) do { const unsigned ad_ = vbase ^ (unsigned)((d_) << 6); __builtin_amdgcn_sched_barrier(0); \
;         _Pragma("unroll") for (int ks_ = 0; ks_ < 4; ++ks_) { VTR(arr[ks_ * 2], ad_, ks_ * 4096); VTR(arr[ks_ * 2 + 1], ad_, ks_ * 4096 + 2048); } __builtin_amdgcn_sched_barrier(0); } while (0)
; #define PV1(arr, d_) do { _Pragma("unroll") for (int ks_ = 0; ks_ < 4; ++ks_) { const s16x4 lo_ = arr[ks_ * 2], hh_ = arr[ks_ * 2 + 1]; \
;         const bf16x8 bv_ = (bf16x8){lo_[0], lo_[1], lo_[2], lo_[3], hh_[0], hh_[1], hh_[2], hh_[3]}; \
;         O[d_] = __builtin_amdgcn_mfma_f32_32x32x16_bf16(pa[ks_], bv_, O[d_], 0, 0, 0); } __builtin_amdgcn_sched_barrier(0); } while (0)
; #define LGKM0() do { __builtin_amdgcn_sched_barrier(0); asm volatile("s_waitcnt lgkmcnt(0)" ::: "memory"); __builtin_amdgcn_sched_barrier(0); } while (0)
; __device__ __forceinline__ void attn_unit(LAS unsigned char* lds, const bf16_t* Z, bf16_t* A2, const float* tabg, int seq_base, int S, int h, int qb, float lam) {
;     ...
; #pragma unroll
;         for (int r = 0; r < 16; ++r) { p0[r] = __builtin_amdgcn_exp2f(p0[r]); p1[r] = __builtin_amdgcn_exp2f(p1[r]); }
; #pragma unroll
;         for (int r = 0; r < 16; r += 2) { ls2 += (f32x2){p0[r], p0[r + 1]}; ls2 += (f32x2){p1[r], p1[r + 1]}; }
;         bf16x8 pa[4]; pa[0] = pack8(p0, 0); pa[1] = pack8(p0, 8); pa[2] = pack8(p1, 0); pa[3] = pack8(p1, 8);
;         LGKM0(); VREADS1(vb, 1); PV1(va, 0); LGKM0(); VREADS1(va, 2); PV1(vb, 1); LGKM0(); VREADS1(vb, 3); PV1(va, 2); LGKM0(); PV1(vb, 3);
;     ...
;         if (t + 2 < NT) asm volatile("s_waitcnt vmcnt(4) lgkmcnt(0)" ::: "memory"); else asm volatile("s_waitcnt vmcnt(0) lgkmcnt(0)" ::: "memory");
;         __builtin_amdgcn_s_barrier(); asm volatile("" ::: "memory");
.LatB_rareret_x1:
	s_waitcnt lgkmcnt(12)
	v_mfma_f32_32x32x16_bf16 v[20:35], v[84:87], v[132:135], v[20:35]
	ds_read_b64_tr_b16 v[132:133], v231 offset:36864
	ds_read_b64_tr_b16 v[134:135], v231 offset:38912
	v_exp_f32_e32 v188, v188
	v_exp_f32_e32 v189, v189
	v_exp_f32_e32 v190, v190
	s_waitcnt lgkmcnt(12)
	v_mfma_f32_32x32x16_bf16 v[36:51], v[84:87], v[136:139], v[36:51]
	ds_read_b64_tr_b16 v[136:137], v228 offset:40960
	ds_read_b64_tr_b16 v[138:139], v228 offset:43008
	v_exp_f32_e32 v191, v191
	v_pk_add_f32 v[150:151], v[150:151], v[188:189]
	v_pk_add_f32 v[150:151], v[150:151], v[190:191]
	v_exp_f32_e32 v192, v192
	s_waitcnt lgkmcnt(12)
	v_mfma_f32_32x32x16_bf16 v[52:67], v[84:87], v[140:143], v[52:67]
	ds_read_b64_tr_b16 v[140:141], v229 offset:40960
	ds_read_b64_tr_b16 v[142:143], v229 offset:43008
	v_exp_f32_e32 v193, v193
	v_cvt_pk_bf16_f32 v188, v188, v189
	v_cvt_pk_bf16_f32 v189, v190, v191
	v_exp_f32_e32 v194, v194
	s_waitcnt lgkmcnt(12)
	v_mfma_f32_32x32x16_bf16 v[68:83], v[84:87], v[144:147], v[68:83]
	ds_read_b64_tr_b16 v[144:145], v230 offset:40960
	ds_read_b64_tr_b16 v[146:147], v230 offset:43008
	v_exp_f32_e32 v195, v195
	v_pk_add_f32 v[150:151], v[150:151], v[192:193]
	v_pk_add_f32 v[150:151], v[150:151], v[194:195]
	v_cvt_pk_bf16_f32 v190, v192, v193
	v_cvt_pk_bf16_f32 v191, v194, v195
	s_waitcnt lgkmcnt(12)
	v_mfma_f32_32x32x16_bf16 v[20:35], v[88:91], v[220:223], v[20:35]
	ds_read_b64_tr_b16 v[220:221], v231 offset:40960
	ds_read_b64_tr_b16 v[222:223], v231 offset:43008
	v_exp_f32_e32 v196, v196
	v_exp_f32_e32 v197, v197
	v_exp_f32_e32 v198, v198
	s_waitcnt lgkmcnt(12)
	v_mfma_f32_32x32x16_bf16 v[36:51], v[88:91], v[224:227], v[36:51]
	ds_read_b64_tr_b16 v[224:225], v228 offset:45056
	ds_read_b64_tr_b16 v[226:227], v228 offset:47104
	v_exp_f32_e32 v199, v199
	v_pk_add_f32 v[150:151], v[150:151], v[196:197]
	v_pk_add_f32 v[150:151], v[150:151], v[198:199]
	v_exp_f32_e32 v200, v200
	s_waitcnt lgkmcnt(12)
	v_mfma_f32_32x32x16_bf16 v[52:67], v[88:91], v[232:235], v[52:67]
	ds_read_b64_tr_b16 v[232:233], v229 offset:45056
	ds_read_b64_tr_b16 v[234:235], v229 offset:47104
	v_exp_f32_e32 v201, v201
	v_cvt_pk_bf16_f32 v192, v196, v197
	v_cvt_pk_bf16_f32 v193, v198, v199
	v_exp_f32_e32 v202, v202
	s_waitcnt lgkmcnt(12)
	v_mfma_f32_32x32x16_bf16 v[68:83], v[88:91], v[132:135], v[68:83]
	ds_read_b64_tr_b16 v[132:133], v230 offset:45056
	ds_read_b64_tr_b16 v[134:135], v230 offset:47104
	v_exp_f32_e32 v203, v203
	v_pk_add_f32 v[150:151], v[150:151], v[200:201]
	v_pk_add_f32 v[150:151], v[150:151], v[202:203]
	v_cvt_pk_bf16_f32 v194, v200, v201
	v_cvt_pk_bf16_f32 v195, v202, v203
	s_waitcnt lgkmcnt(12)
	v_mfma_f32_32x32x16_bf16 v[20:35], v[100:103], v[136:139], v[20:35]
	ds_read_b64_tr_b16 v[136:137], v231 offset:45056
	ds_read_b64_tr_b16 v[138:139], v231 offset:47104
	v_exp_f32_e32 v204, v204
	v_exp_f32_e32 v205, v205
	v_exp_f32_e32 v206, v206
	s_waitcnt lgkmcnt(12)
	v_mfma_f32_32x32x16_bf16 v[36:51], v[100:103], v[140:143], v[36:51]
	v_exp_f32_e32 v207, v207
	v_pk_add_f32 v[150:151], v[150:151], v[204:205]
	v_pk_add_f32 v[150:151], v[150:151], v[206:207]
	v_exp_f32_e32 v208, v208
	s_waitcnt lgkmcnt(10)
	v_mfma_f32_32x32x16_bf16 v[52:67], v[100:103], v[144:147], v[52:67]
	v_exp_f32_e32 v209, v209
	v_cvt_pk_bf16_f32 v204, v204, v205
	v_cvt_pk_bf16_f32 v205, v206, v207
	v_exp_f32_e32 v210, v210
	s_waitcnt lgkmcnt(8)
	v_mfma_f32_32x32x16_bf16 v[68:83], v[100:103], v[220:223], v[68:83]
	v_exp_f32_e32 v211, v211
	v_pk_add_f32 v[150:151], v[150:151], v[208:209]
	v_pk_add_f32 v[150:151], v[150:151], v[210:211]
	v_cvt_pk_bf16_f32 v206, v208, v209
	v_cvt_pk_bf16_f32 v207, v210, v211
	s_waitcnt lgkmcnt(6)
	v_mfma_f32_32x32x16_bf16 v[20:35], v[104:107], v[224:227], v[20:35]
	v_exp_f32_e32 v212, v212
	v_exp_f32_e32 v213, v213
	v_exp_f32_e32 v214, v214
	s_waitcnt lgkmcnt(4)
	v_mfma_f32_32x32x16_bf16 v[36:51], v[104:107], v[232:235], v[36:51]
	v_exp_f32_e32 v215, v215
	v_pk_add_f32 v[150:151], v[150:151], v[212:213]
	v_pk_add_f32 v[150:151], v[150:151], v[214:215]
	v_exp_f32_e32 v216, v216
	s_waitcnt lgkmcnt(2)
	v_mfma_f32_32x32x16_bf16 v[52:67], v[104:107], v[132:135], v[52:67]
	v_exp_f32_e32 v217, v217
	v_cvt_pk_bf16_f32 v208, v212, v213
	v_cvt_pk_bf16_f32 v209, v214, v215
	v_exp_f32_e32 v218, v218
	s_waitcnt lgkmcnt(0)
	v_mfma_f32_32x32x16_bf16 v[68:83], v[104:107], v[136:139], v[68:83]
	v_exp_f32_e32 v219, v219
	v_pk_add_f32 v[150:151], v[150:151], v[216:217]
	v_pk_add_f32 v[150:151], v[150:151], v[218:219]
	v_cvt_pk_bf16_f32 v210, v216, v217
	v_cvt_pk_bf16_f32 v211, v218, v219
	s_add_u32 s8, s8, 0x40000
	s_addc_u32 s9, s9, 0
	s_waitcnt vmcnt(0) lgkmcnt(0)
	s_barrier
; #define VREADS1(arr, d_) do { const unsigned ad_ = vbase ^ (unsigned)((d_) << 6); __builtin_amdgcn_sched_barrier(0); \
;         _Pragma("unroll") for (int ks_ = 0; ks_ < 4; ++ks_) { VTR(arr[ks_ * 2], ad_, ks_ * 4096); VTR(arr[ks_ * 2 + 1], ad_, ks_ * 4096 + 2048); } __builtin_amdgcn_sched_barrier(0); } while (0)
; #define PV1(arr, d_) do { _Pragma("unroll") for (int ks_ = 0; ks_ < 4; ++ks_) { const s16x4 lo_ = arr[ks_ * 2], hh_ = arr[ks_ * 2 + 1]; \
;         const bf16x8 bv_ = (bf16x8){lo_[0], lo_[1], lo_[2], lo_[3], hh_[0], hh_[1], hh_[2], hh_[3]}; \
;         O[d_] = __builtin_amdgcn_mfma_f32_32x32x16_bf16(pa[ks_], bv_, O[d_], 0, 0, 0); } __builtin_amdgcn_sched_barrier(0); } while (0)
; #define LGKM0() do { __builtin_amdgcn_sched_barrier(0); asm volatile("s_waitcnt lgkmcnt(0)" ::: "memory"); __builtin_amdgcn_sched_barrier(0); } while (0)
; __device__ __forceinline__ void attn_unit(LAS unsigned char* lds, const bf16_t* Z, bf16_t* A2, const float* tabg, int seq_base, int S, int h, int qb, float lam) {
;     ...
;         LGKM0(); VREADS1(vb, 1); PV1(va, 0); LGKM0(); VREADS1(va, 2); PV1(vb, 1); LGKM0(); VREADS1(vb, 3); PV1(va, 2); LGKM0(); PV1(vb, 3);
;     ...
;         if (t + 2 < NT) asm volatile("s_waitcnt vmcnt(4) lgkmcnt(0)" ::: "memory"); else asm volatile("s_waitcnt vmcnt(0) lgkmcnt(0)" ::: "memory");
;         __builtin_amdgcn_s_barrier(); asm volatile("" ::: "memory");
	ds_read_b64_tr_b16 v[132:133], v228 offset:0
	ds_read_b64_tr_b16 v[134:135], v228 offset:2048
	ds_read_b64_tr_b16 v[136:137], v229 offset:0
	ds_read_b64_tr_b16 v[138:139], v229 offset:2048
	ds_read_b64_tr_b16 v[140:141], v230 offset:0
	ds_read_b64_tr_b16 v[142:143], v230 offset:2048
	ds_read_b64_tr_b16 v[144:145], v231 offset:0
	ds_read_b64_tr_b16 v[146:147], v231 offset:2048
	ds_read_b64_tr_b16 v[220:221], v228 offset:4096
	ds_read_b64_tr_b16 v[222:223], v228 offset:6144
	ds_read_b64_tr_b16 v[224:225], v229 offset:4096
	ds_read_b64_tr_b16 v[226:227], v229 offset:6144
	ds_read_b64_tr_b16 v[232:233], v230 offset:4096
	ds_read_b64_tr_b16 v[234:235], v230 offset:6144
	s_waitcnt lgkmcnt(10)
	v_mfma_f32_32x32x16_bf16 v[20:35], v[188:191], v[132:135], v[20:35]
	ds_read_b64_tr_b16 v[132:133], v231 offset:4096
	ds_read_b64_tr_b16 v[134:135], v231 offset:6144
	v_mfma_f32_32x32x16_bf16 v[36:51], v[188:191], v[136:139], v[36:51]
	ds_read_b64_tr_b16 v[136:137], v228 offset:8192
	ds_read_b64_tr_b16 v[138:139], v228 offset:10240
	s_waitcnt lgkmcnt(10)
	v_mfma_f32_32x32x16_bf16 v[52:67], v[188:191], v[140:143], v[52:67]
	ds_read_b64_tr_b16 v[140:141], v229 offset:8192
	ds_read_b64_tr_b16 v[142:143], v229 offset:10240
	v_mfma_f32_32x32x16_bf16 v[68:83], v[188:191], v[144:147], v[68:83]
	ds_read_b64_tr_b16 v[144:145], v230 offset:8192
	ds_read_b64_tr_b16 v[146:147], v230 offset:10240
	s_waitcnt lgkmcnt(10)
	v_mfma_f32_32x32x16_bf16 v[20:35], v[192:195], v[220:223], v[20:35]
	ds_read_b64_tr_b16 v[220:221], v231 offset:8192
	ds_read_b64_tr_b16 v[222:223], v231 offset:10240
	v_mfma_f32_32x32x16_bf16 v[36:51], v[192:195], v[224:227], v[36:51]
	ds_read_b64_tr_b16 v[224:225], v228 offset:12288
	ds_read_b64_tr_b16 v[226:227], v228 offset:14336
	s_waitcnt lgkmcnt(10)
	v_mfma_f32_32x32x16_bf16 v[52:67], v[192:195], v[232:235], v[52:67]
	ds_read_b64_tr_b16 v[232:233], v229 offset:12288
	ds_read_b64_tr_b16 v[234:235], v229 offset:14336
	v_mfma_f32_32x32x16_bf16 v[68:83], v[192:195], v[132:135], v[68:83]
	ds_read_b64_tr_b16 v[132:133], v230 offset:12288
	ds_read_b64_tr_b16 v[134:135], v230 offset:14336
	s_waitcnt lgkmcnt(10)
	v_mfma_f32_32x32x16_bf16 v[20:35], v[204:207], v[136:139], v[20:35]
	ds_read_b64_tr_b16 v[136:137], v231 offset:12288
	ds_read_b64_tr_b16 v[138:139], v231 offset:14336
	v_mfma_f32_32x32x16_bf16 v[36:51], v[204:207], v[140:143], v[36:51]
	s_waitcnt lgkmcnt(8)
	v_mfma_f32_32x32x16_bf16 v[52:67], v[204:207], v[144:147], v[52:67]
	v_mfma_f32_32x32x16_bf16 v[68:83], v[204:207], v[220:223], v[68:83]
	s_waitcnt lgkmcnt(4)
	v_mfma_f32_32x32x16_bf16 v[20:35], v[208:211], v[224:227], v[20:35]
	v_mfma_f32_32x32x16_bf16 v[36:51], v[208:211], v[232:235], v[36:51]
	s_waitcnt lgkmcnt(0)
	v_mfma_f32_32x32x16_bf16 v[52:67], v[208:211], v[132:135], v[52:67]
	v_mfma_f32_32x32x16_bf16 v[68:83], v[208:211], v[136:139], v[68:83]
	s_waitcnt lgkmcnt(0)
	s_barrier
	s_mov_b32 m0, s32
	s_nop 15
	s_branch .LatB_done
